# phase_mla_qk: hand-written fast path for gridDim=256 (8 rows per wave, all row loads up front, hardware v_sin/v_cos on the reduced revolution count instead of 16 inlined polynomial sincosf per trip);
# speedup vs baseline: 1.0285x; 1.0093x over previous
; DI int otid() { int t = threadIdx.x; asm volatile("" : "+v"(t)); return t; }
; DI void phase_mla_qk(const Params& p) {
;     bf16_t* qkv = (bf16_t*)(p.ws + ACT); bf16_t* lat = (bf16_t*)(p.ws + LAT); const float* qkg = p.in[27];
;     const int tid = otid(), lane = tid & 63, gw = blockIdx.x * 8 + (tid >> 6), nw = gridDim.x * 8;
;     const int l16 = lane & 15, l8 = lane & 7;
;     float gk[8], gkr[8];
; #pragma unroll
;     for (int e = 0; e < 8; ++e) { gk[e] = qkg[192 + l16 * 8 + e]; gkr[e] = qkg[192 + 128 + l8 * 8 + e]; }
;     float inv[8];
; #pragma unroll
;     for (int e = 0; e < 8; ++e) inv[e] = powf(10000.f, -(float)((l8 & 3) * 8 + e) * (1.f / 32.f));
;     for (int row0 = gw; row0 < MTOK; row0 += 2 * nw) {
;         u32x4 wk[2][4], wp[2]; bool ok[2]; int rw[2];
; #pragma unroll
;         for (int r = 0; r < 2; ++r) { ok[r] = row0 + r * nw < MTOK; rw[r] = ok[r] ? row0 + r * nw : row0;
;             const bf16_t* qr = qkv + (size_t)rw[r] * 7168;
; #pragma unroll
;             for (int i = 0; i < 4; ++i) { const int head = 4 * i + (lane >> 4); wk[r][i] = *(const u32x4*)(qr + 3072 + head * 256 + l16 * 8); }
;             wp[r] = *(const u32x4*)(lat + (size_t)rw[r] * 1088 + 1024 + l8 * 8); }
.LBB0_1425:
	s_or_b64 exec, exec, s[6:7]
	v_mov_b32_e32 v21, v181
	s_waitcnt lgkmcnt(0)
	s_barrier
	s_cmp_eq_u32 s18, 0x100
	s_cbranch_scc0 .Lmq_orig
	s_load_dwordx2 s[6:7], s[0:1], 0xf0
	s_load_dwordx2 s[8:9], s[0:1], 0xd8
	v_and_b32_e32 v197, 63, v181
	v_and_b32_e32 v198, 15, v197
	v_and_b32_e32 v199, 7, v197
	v_lshrrev_b32_e32 v200, 4, v197
	v_lshlrev_b32_e32 v195, 9, v200
	v_lshl_add_u32 v195, v198, 4, v195
	v_lshlrev_b32_e32 v196, 4, v199
	v_lshlrev_b32_e32 v201, 5, v198
	v_lshlrev_b32_e32 v202, 5, v199
	s_waitcnt lgkmcnt(0)
	global_load_dwordx4 v[160:163], v201, s[8:9] offset:768
	global_load_dwordx4 v[164:167], v201, s[8:9] offset:784
	global_load_dwordx4 v[168:171], v202, s[8:9] offset:1280
	global_load_dwordx4 v[172:175], v202, s[8:9] offset:1296
	v_xor_b32_e32 v191, 1, v197
	v_lshlrev_b32_e32 v191, 2, v191
	v_xor_b32_e32 v192, 2, v197
	v_lshlrev_b32_e32 v192, 2, v192
	v_xor_b32_e32 v193, 4, v197
	v_lshlrev_b32_e32 v193, 2, v193
	v_xor_b32_e32 v194, 8, v197
	v_lshlrev_b32_e32 v194, 2, v194
	v_and_b32_e32 v203, 3, v199
	v_lshl_add_u32 v204, v203, 3, 0
	v_cvt_f32_u32_e32 v204, v204
	v_mul_f32_e32 v204, 0xbed49a78, v204
	v_exp_f32_e32 v182, v204
	v_lshl_add_u32 v204, v203, 3, 1
	v_cvt_f32_u32_e32 v204, v204
	v_mul_f32_e32 v204, 0xbed49a78, v204
	v_exp_f32_e32 v183, v204
	v_lshl_add_u32 v204, v203, 3, 2
	v_cvt_f32_u32_e32 v204, v204
	v_mul_f32_e32 v204, 0xbed49a78, v204
	v_exp_f32_e32 v184, v204
	v_lshl_add_u32 v204, v203, 3, 3
	v_cvt_f32_u32_e32 v204, v204
	v_mul_f32_e32 v204, 0xbed49a78, v204
	v_exp_f32_e32 v185, v204
	v_lshl_add_u32 v204, v203, 3, 4
	v_cvt_f32_u32_e32 v204, v204
	v_mul_f32_e32 v204, 0xbed49a78, v204
	v_exp_f32_e32 v186, v204
	v_lshl_add_u32 v204, v203, 3, 5
	v_cvt_f32_u32_e32 v204, v204
	v_mul_f32_e32 v204, 0xbed49a78, v204
	v_exp_f32_e32 v187, v204
	v_lshl_add_u32 v204, v203, 3, 6
	v_cvt_f32_u32_e32 v204, v204
	v_mul_f32_e32 v204, 0xbed49a78, v204
	v_exp_f32_e32 v188, v204
	v_lshl_add_u32 v204, v203, 3, 7
	v_cvt_f32_u32_e32 v204, v204
	v_mul_f32_e32 v204, 0xbed49a78, v204
	v_exp_f32_e32 v189, v204
	v_lshrrev_b32_e32 v206, 6, v181
	s_nop 0
	v_readfirstlane_b32 s10, v206
	s_lshl_b32 s11, s2, 3
	s_add_i32 s10, s10, s11
	s_add_u32 s12, s6, 0xbf00000
	s_addc_u32 s13, s7, 0
	s_mul_i32 s14, s10, 14336
	s_mul_hi_u32 s15, s10, 14336
	s_add_u32 s12, s12, s14
	s_addc_u32 s13, s13, s15
	s_add_u32 s12, s12, 0x1800
	s_addc_u32 s13, s13, 0
	s_mul_i32 s14, s10, 2176
	s_mul_hi_u32 s15, s10, 2176
	s_add_u32 s16, s6, s14
	s_addc_u32 s17, s7, s15
	s_add_u32 s16, s16, 0x800
	s_addc_u32 s17, s17, 0
	s_mov_b64 s[26:27], s[12:13]
	s_mov_b64 s[28:29], s[16:17]
	global_load_dwordx4 v[0:3], v195, s[26:27]
	global_load_dwordx4 v[4:7], v195, s[26:27] offset:2048
	s_add_u32 s30, s26, 0x1000
	s_addc_u32 s31, s27, 0
	global_load_dwordx4 v[8:11], v195, s[30:31]
	global_load_dwordx4 v[12:15], v195, s[30:31] offset:2048
	global_load_dwordx4 v[16:19], v196, s[28:29]
	s_add_u32 s26, s26, 0x1c00000
	s_addc_u32 s27, s27, 0
	s_add_u32 s28, s28, 0x440000
	s_addc_u32 s29, s29, 0
	global_load_dwordx4 v[20:23], v195, s[26:27]
	global_load_dwordx4 v[24:27], v195, s[26:27] offset:2048
	s_add_u32 s30, s26, 0x1000
	s_addc_u32 s31, s27, 0
	global_load_dwordx4 v[28:31], v195, s[30:31]
	global_load_dwordx4 v[32:35], v195, s[30:31] offset:2048
	global_load_dwordx4 v[36:39], v196, s[28:29]
	s_add_u32 s26, s26, 0x1c00000
	s_addc_u32 s27, s27, 0
	s_add_u32 s28, s28, 0x440000
	s_addc_u32 s29, s29, 0
	global_load_dwordx4 v[40:43], v195, s[26:27]
	global_load_dwordx4 v[44:47], v195, s[26:27] offset:2048
	s_add_u32 s30, s26, 0x1000
	s_addc_u32 s31, s27, 0
	global_load_dwordx4 v[48:51], v195, s[30:31]
	global_load_dwordx4 v[52:55], v195, s[30:31] offset:2048
	global_load_dwordx4 v[56:59], v196, s[28:29]
	s_add_u32 s26, s26, 0x1c00000
	s_addc_u32 s27, s27, 0
	s_add_u32 s28, s28, 0x440000
	s_addc_u32 s29, s29, 0
	global_load_dwordx4 v[60:63], v195, s[26:27]
	global_load_dwordx4 v[64:67], v195, s[26:27] offset:2048
	s_add_u32 s30, s26, 0x1000
	s_addc_u32 s31, s27, 0
	global_load_dwordx4 v[68:71], v195, s[30:31]
	global_load_dwordx4 v[72:75], v195, s[30:31] offset:2048
	global_load_dwordx4 v[76:79], v196, s[28:29]
	s_add_u32 s26, s26, 0x1c00000
	s_addc_u32 s27, s27, 0
	s_add_u32 s28, s28, 0x440000
	s_addc_u32 s29, s29, 0
	global_load_dwordx4 v[80:83], v195, s[26:27]
	global_load_dwordx4 v[84:87], v195, s[26:27] offset:2048
	s_add_u32 s30, s26, 0x1000
	s_addc_u32 s31, s27, 0
	global_load_dwordx4 v[88:91], v195, s[30:31]
	global_load_dwordx4 v[92:95], v195, s[30:31] offset:2048
	global_load_dwordx4 v[96:99], v196, s[28:29]
	s_add_u32 s26, s26, 0x1c00000
	s_addc_u32 s27, s27, 0
	s_add_u32 s28, s28, 0x440000
	s_addc_u32 s29, s29, 0
	global_load_dwordx4 v[100:103], v195, s[26:27]
	global_load_dwordx4 v[104:107], v195, s[26:27] offset:2048
	s_add_u32 s30, s26, 0x1000
	s_addc_u32 s31, s27, 0
	global_load_dwordx4 v[108:111], v195, s[30:31]
	global_load_dwordx4 v[112:115], v195, s[30:31] offset:2048
	global_load_dwordx4 v[116:119], v196, s[28:29]
	s_add_u32 s26, s26, 0x1c00000
	s_addc_u32 s27, s27, 0
	s_add_u32 s28, s28, 0x440000
	s_addc_u32 s29, s29, 0
	global_load_dwordx4 v[120:123], v195, s[26:27]
	global_load_dwordx4 v[124:127], v195, s[26:27] offset:2048
	s_add_u32 s30, s26, 0x1000
	s_addc_u32 s31, s27, 0
	global_load_dwordx4 v[128:131], v195, s[30:31]
	global_load_dwordx4 v[132:135], v195, s[30:31] offset:2048
	global_load_dwordx4 v[136:139], v196, s[28:29]
	s_add_u32 s26, s26, 0x1c00000
	s_addc_u32 s27, s27, 0
	s_add_u32 s28, s28, 0x440000
	s_addc_u32 s29, s29, 0
	global_load_dwordx4 v[140:143], v195, s[26:27]
	global_load_dwordx4 v[144:147], v195, s[26:27] offset:2048
	s_add_u32 s30, s26, 0x1000
	s_addc_u32 s31, s27, 0
	global_load_dwordx4 v[148:151], v195, s[30:31]
	global_load_dwordx4 v[152:155], v195, s[30:31] offset:2048
	global_load_dwordx4 v[156:159], v196, s[28:29]
	v_mov_b32_e32 v205, -1.0
	v_cmp_gt_u32_e32 vcc, 4, v199
	v_mov_b32_e32 v204, 1.0
	s_nop 1
	v_cndmask_b32_e32 v190, v204, v205, vcc
	s_mov_b64 s[26:27], s[12:13]
	s_mov_b64 s[28:29], s[16:17]
	s_mov_b32 s34, s10
	s_waitcnt vmcnt(30)
; DI void phase_mla_qk(const Params& p) {
;     ...
;                 float f[8]; unpack8(wk[r][i], f); float ss = 0.f;
; #pragma unroll
;                 for (int e = 0; e < 8; ++e) ss += f[e] * f[e];
;                 ss += __shfl_xor(ss, 1); ss += __shfl_xor(ss, 2); ss += __shfl_xor(ss, 4); ss += __shfl_xor(ss, 8);
;     ...
;             { float f[8], o[8]; unpack8(wp[r], f); float ss = 0.f;
; #pragma unroll
;               for (int e = 0; e < 8; ++e) ss += f[e] * f[e];
;               ss += __shfl_xor(ss, 1); ss += __shfl_xor(ss, 2); ss += __shfl_xor(ss, 4);
	v_lshlrev_b32_e32 v218, 16, v0
	v_and_b32_e32 v219, 0xffff0000, v0
	v_mul_f32_e32 v207, v218, v218
	v_fmac_f32_e32 v207, v219, v219
	v_lshlrev_b32_e32 v218, 16, v1
	v_and_b32_e32 v219, 0xffff0000, v1
	v_fmac_f32_e32 v207, v218, v218
	v_fmac_f32_e32 v207, v219, v219
	v_lshlrev_b32_e32 v218, 16, v2
	v_and_b32_e32 v219, 0xffff0000, v2
	v_fmac_f32_e32 v207, v218, v218
	v_fmac_f32_e32 v207, v219, v219
	v_lshlrev_b32_e32 v218, 16, v3
	v_and_b32_e32 v219, 0xffff0000, v3
	v_fmac_f32_e32 v207, v218, v218
	v_fmac_f32_e32 v207, v219, v219
	v_lshlrev_b32_e32 v218, 16, v4
	v_and_b32_e32 v219, 0xffff0000, v4
	v_mul_f32_e32 v208, v218, v218
	v_fmac_f32_e32 v208, v219, v219
	v_lshlrev_b32_e32 v218, 16, v5
	v_and_b32_e32 v219, 0xffff0000, v5
	v_fmac_f32_e32 v208, v218, v218
	v_fmac_f32_e32 v208, v219, v219
	v_lshlrev_b32_e32 v218, 16, v6
	v_and_b32_e32 v219, 0xffff0000, v6
	v_fmac_f32_e32 v208, v218, v218
	v_fmac_f32_e32 v208, v219, v219
	v_lshlrev_b32_e32 v218, 16, v7
	v_and_b32_e32 v219, 0xffff0000, v7
	v_fmac_f32_e32 v208, v218, v218
	v_fmac_f32_e32 v208, v219, v219
	v_lshlrev_b32_e32 v218, 16, v8
	v_and_b32_e32 v219, 0xffff0000, v8
	v_mul_f32_e32 v209, v218, v218
	v_fmac_f32_e32 v209, v219, v219
	v_lshlrev_b32_e32 v218, 16, v9
	v_and_b32_e32 v219, 0xffff0000, v9
	v_fmac_f32_e32 v209, v218, v218
	v_fmac_f32_e32 v209, v219, v219
	v_lshlrev_b32_e32 v218, 16, v10
	v_and_b32_e32 v219, 0xffff0000, v10
	v_fmac_f32_e32 v209, v218, v218
	v_fmac_f32_e32 v209, v219, v219
	v_lshlrev_b32_e32 v218, 16, v11
	v_and_b32_e32 v219, 0xffff0000, v11
	v_fmac_f32_e32 v209, v218, v218
	v_fmac_f32_e32 v209, v219, v219
	v_lshlrev_b32_e32 v218, 16, v12
	v_and_b32_e32 v219, 0xffff0000, v12
	v_mul_f32_e32 v210, v218, v218
	v_fmac_f32_e32 v210, v219, v219
	v_lshlrev_b32_e32 v218, 16, v13
	v_and_b32_e32 v219, 0xffff0000, v13
	v_fmac_f32_e32 v210, v218, v218
	v_fmac_f32_e32 v210, v219, v219
	v_lshlrev_b32_e32 v218, 16, v14
	v_and_b32_e32 v219, 0xffff0000, v14
	v_fmac_f32_e32 v210, v218, v218
	v_fmac_f32_e32 v210, v219, v219
	v_lshlrev_b32_e32 v218, 16, v15
	v_and_b32_e32 v219, 0xffff0000, v15
	v_fmac_f32_e32 v210, v218, v218
	v_fmac_f32_e32 v210, v219, v219
	v_lshlrev_b32_e32 v218, 16, v16
	v_and_b32_e32 v219, 0xffff0000, v16
	v_mul_f32_e32 v211, v218, v218
	v_fmac_f32_e32 v211, v219, v219
	v_lshlrev_b32_e32 v218, 16, v17
	v_and_b32_e32 v219, 0xffff0000, v17
	v_fmac_f32_e32 v211, v218, v218
	v_fmac_f32_e32 v211, v219, v219
	v_lshlrev_b32_e32 v218, 16, v18
	v_and_b32_e32 v219, 0xffff0000, v18
	v_fmac_f32_e32 v211, v218, v218
	v_fmac_f32_e32 v211, v219, v219
	v_lshlrev_b32_e32 v218, 16, v19
	v_and_b32_e32 v219, 0xffff0000, v19
	v_fmac_f32_e32 v211, v218, v218
	v_fmac_f32_e32 v211, v219, v219
	v_lshlrev_b32_e32 v218, 16, v20
	v_and_b32_e32 v219, 0xffff0000, v20
	v_mul_f32_e32 v212, v218, v218
	v_fmac_f32_e32 v212, v219, v219
	v_lshlrev_b32_e32 v218, 16, v21
	v_and_b32_e32 v219, 0xffff0000, v21
	v_fmac_f32_e32 v212, v218, v218
	v_fmac_f32_e32 v212, v219, v219
	v_lshlrev_b32_e32 v218, 16, v22
	v_and_b32_e32 v219, 0xffff0000, v22
	v_fmac_f32_e32 v212, v218, v218
	v_fmac_f32_e32 v212, v219, v219
	v_lshlrev_b32_e32 v218, 16, v23
	v_and_b32_e32 v219, 0xffff0000, v23
	v_fmac_f32_e32 v212, v218, v218
	v_fmac_f32_e32 v212, v219, v219
	v_lshlrev_b32_e32 v218, 16, v24
	v_and_b32_e32 v219, 0xffff0000, v24
	v_mul_f32_e32 v213, v218, v218
	v_fmac_f32_e32 v213, v219, v219
	v_lshlrev_b32_e32 v218, 16, v25
	v_and_b32_e32 v219, 0xffff0000, v25
	v_fmac_f32_e32 v213, v218, v218
	v_fmac_f32_e32 v213, v219, v219
	v_lshlrev_b32_e32 v218, 16, v26
	v_and_b32_e32 v219, 0xffff0000, v26
	v_fmac_f32_e32 v213, v218, v218
	v_fmac_f32_e32 v213, v219, v219
	v_lshlrev_b32_e32 v218, 16, v27
	v_and_b32_e32 v219, 0xffff0000, v27
	v_fmac_f32_e32 v213, v218, v218
	v_fmac_f32_e32 v213, v219, v219
	v_lshlrev_b32_e32 v218, 16, v28
	v_and_b32_e32 v219, 0xffff0000, v28
	v_mul_f32_e32 v214, v218, v218
	v_fmac_f32_e32 v214, v219, v219
	v_lshlrev_b32_e32 v218, 16, v29
	v_and_b32_e32 v219, 0xffff0000, v29
	v_fmac_f32_e32 v214, v218, v218
	v_fmac_f32_e32 v214, v219, v219
	v_lshlrev_b32_e32 v218, 16, v30
	v_and_b32_e32 v219, 0xffff0000, v30
	v_fmac_f32_e32 v214, v218, v218
	v_fmac_f32_e32 v214, v219, v219
	v_lshlrev_b32_e32 v218, 16, v31
	v_and_b32_e32 v219, 0xffff0000, v31
	v_fmac_f32_e32 v214, v218, v218
	v_fmac_f32_e32 v214, v219, v219
	v_lshlrev_b32_e32 v218, 16, v32
	v_and_b32_e32 v219, 0xffff0000, v32
	v_mul_f32_e32 v215, v218, v218
	v_fmac_f32_e32 v215, v219, v219
	v_lshlrev_b32_e32 v218, 16, v33
	v_and_b32_e32 v219, 0xffff0000, v33
	v_fmac_f32_e32 v215, v218, v218
	v_fmac_f32_e32 v215, v219, v219
	v_lshlrev_b32_e32 v218, 16, v34
	v_and_b32_e32 v219, 0xffff0000, v34
	v_fmac_f32_e32 v215, v218, v218
	v_fmac_f32_e32 v215, v219, v219
	v_lshlrev_b32_e32 v218, 16, v35
	v_and_b32_e32 v219, 0xffff0000, v35
	v_fmac_f32_e32 v215, v218, v218
	v_fmac_f32_e32 v215, v219, v219
	v_lshlrev_b32_e32 v218, 16, v36
	v_and_b32_e32 v219, 0xffff0000, v36
	v_mul_f32_e32 v216, v218, v218
	v_fmac_f32_e32 v216, v219, v219
	v_lshlrev_b32_e32 v218, 16, v37
	v_and_b32_e32 v219, 0xffff0000, v37
	v_fmac_f32_e32 v216, v218, v218
	v_fmac_f32_e32 v216, v219, v219
	v_lshlrev_b32_e32 v218, 16, v38
	v_and_b32_e32 v219, 0xffff0000, v38
	v_fmac_f32_e32 v216, v218, v218
	v_fmac_f32_e32 v216, v219, v219
	v_lshlrev_b32_e32 v218, 16, v39
	v_and_b32_e32 v219, 0xffff0000, v39
	v_fmac_f32_e32 v216, v218, v218
	v_fmac_f32_e32 v216, v219, v219
	ds_bpermute_b32 v220, v191, v207
	ds_bpermute_b32 v221, v191, v208
	ds_bpermute_b32 v222, v191, v209
	ds_bpermute_b32 v223, v191, v210
	ds_bpermute_b32 v224, v191, v211
	ds_bpermute_b32 v225, v191, v212
	ds_bpermute_b32 v226, v191, v213
	ds_bpermute_b32 v227, v191, v214
	ds_bpermute_b32 v228, v191, v215
	ds_bpermute_b32 v229, v191, v216
	s_waitcnt lgkmcnt(0)
; DI u32x4 pack8(const float (&f)[8]) { u32x4 w; w.x = pk2(f[0], f[1]); w.y = pk2(f[2], f[3]); w.z = pk2(f[4], f[5]); w.w = pk2(f[6], f[7]); return w; }
; DI void phase_mla_qk(const Params& p) {
;     ...
;                 ss += __shfl_xor(ss, 1); ss += __shfl_xor(ss, 2); ss += __shfl_xor(ss, 4); ss += __shfl_xor(ss, 8);
;                 const float sc = rsqrtf(ss * (1.f / 128.f) + EPS);
; #pragma unroll
;                 for (int e = 0; e < 8; ++e) f[e] *= sc * gk[e];
;                 if (ok[r]) *(u32x4*)(qr + 3072 + head * 256 + l16 * 8) = pack8(f);
	v_add_f32_e32 v207, v207, v220
	v_add_f32_e32 v208, v208, v221
	v_add_f32_e32 v209, v209, v222
	v_add_f32_e32 v210, v210, v223
	v_add_f32_e32 v211, v211, v224
	v_add_f32_e32 v212, v212, v225
	v_add_f32_e32 v213, v213, v226
	v_add_f32_e32 v214, v214, v227
	v_add_f32_e32 v215, v215, v228
	v_add_f32_e32 v216, v216, v229
	ds_bpermute_b32 v220, v192, v207
	ds_bpermute_b32 v221, v192, v208
	ds_bpermute_b32 v222, v192, v209
	ds_bpermute_b32 v223, v192, v210
	ds_bpermute_b32 v224, v192, v211
	ds_bpermute_b32 v225, v192, v212
	ds_bpermute_b32 v226, v192, v213
	ds_bpermute_b32 v227, v192, v214
	ds_bpermute_b32 v228, v192, v215
	ds_bpermute_b32 v229, v192, v216
	s_waitcnt lgkmcnt(0)
	v_add_f32_e32 v207, v207, v220
	v_add_f32_e32 v208, v208, v221
	v_add_f32_e32 v209, v209, v222
	v_add_f32_e32 v210, v210, v223
	v_add_f32_e32 v211, v211, v224
	v_add_f32_e32 v212, v212, v225
	v_add_f32_e32 v213, v213, v226
	v_add_f32_e32 v214, v214, v227
	v_add_f32_e32 v215, v215, v228
	v_add_f32_e32 v216, v216, v229
	ds_bpermute_b32 v220, v193, v207
	ds_bpermute_b32 v221, v193, v208
	ds_bpermute_b32 v222, v193, v209
	ds_bpermute_b32 v223, v193, v210
	ds_bpermute_b32 v224, v193, v211
	ds_bpermute_b32 v225, v193, v212
	ds_bpermute_b32 v226, v193, v213
	ds_bpermute_b32 v227, v193, v214
	ds_bpermute_b32 v228, v193, v215
	ds_bpermute_b32 v229, v193, v216
	s_waitcnt lgkmcnt(0)
	v_add_f32_e32 v207, v207, v220
	v_add_f32_e32 v208, v208, v221
	v_add_f32_e32 v209, v209, v222
	v_add_f32_e32 v210, v210, v223
	v_add_f32_e32 v211, v211, v224
	v_add_f32_e32 v212, v212, v225
	v_add_f32_e32 v213, v213, v226
	v_add_f32_e32 v214, v214, v227
	v_add_f32_e32 v215, v215, v228
	v_add_f32_e32 v216, v216, v229
	ds_bpermute_b32 v220, v194, v207
	ds_bpermute_b32 v221, v194, v208
	ds_bpermute_b32 v222, v194, v209
	ds_bpermute_b32 v223, v194, v210
	ds_bpermute_b32 v225, v194, v212
	ds_bpermute_b32 v226, v194, v213
	ds_bpermute_b32 v227, v194, v214
	ds_bpermute_b32 v228, v194, v215
	s_waitcnt lgkmcnt(0)
	v_add_f32_e32 v207, v207, v220
	v_add_f32_e32 v208, v208, v221
	v_add_f32_e32 v209, v209, v222
	v_add_f32_e32 v210, v210, v223
	v_add_f32_e32 v212, v212, v225
	v_add_f32_e32 v213, v213, v226
	v_add_f32_e32 v214, v214, v227
	v_add_f32_e32 v215, v215, v228
	v_mul_f32_e32 v207, 0x3c000000, v207
	v_add_f32_e32 v207, 0x358637bd, v207
	v_mul_f32_e32 v208, 0x3c000000, v208
	v_add_f32_e32 v208, 0x358637bd, v208
	v_mul_f32_e32 v209, 0x3c000000, v209
	v_add_f32_e32 v209, 0x358637bd, v209
	v_mul_f32_e32 v210, 0x3c000000, v210
	v_add_f32_e32 v210, 0x358637bd, v210
	v_mul_f32_e32 v211, 0x3c800000, v211
	v_add_f32_e32 v211, 0x358637bd, v211
	v_mul_f32_e32 v212, 0x3c000000, v212
	v_add_f32_e32 v212, 0x358637bd, v212
	v_mul_f32_e32 v213, 0x3c000000, v213
	v_add_f32_e32 v213, 0x358637bd, v213
	v_mul_f32_e32 v214, 0x3c000000, v214
	v_add_f32_e32 v214, 0x358637bd, v214
	v_mul_f32_e32 v215, 0x3c000000, v215
	v_add_f32_e32 v215, 0x358637bd, v215
	v_mul_f32_e32 v216, 0x3c800000, v216
	v_add_f32_e32 v216, 0x358637bd, v216
	v_rsq_f32_e32 v207, v207
	v_rsq_f32_e32 v208, v208
	v_rsq_f32_e32 v209, v209
	v_rsq_f32_e32 v210, v210
	v_rsq_f32_e32 v211, v211
	v_rsq_f32_e32 v212, v212
	v_rsq_f32_e32 v213, v213
	v_rsq_f32_e32 v214, v214
	v_rsq_f32_e32 v215, v215
	v_rsq_f32_e32 v216, v216
	s_nop 1
	s_add_u32 s30, s26, 0x1000
	s_addc_u32 s31, s27, 0
	v_mul_f32_e32 v218, v207, v160
	v_mul_f32_e32 v219, v207, v161
	v_lshlrev_b32_e32 v230, 16, v0
	v_and_b32_e32 v231, 0xffff0000, v0
	v_mul_f32_e32 v230, v230, v218
	v_mul_f32_e32 v231, v231, v219
	v_cvt_pk_bf16_f32 v0, v230, v231
	v_mul_f32_e32 v218, v207, v162
	v_mul_f32_e32 v219, v207, v163
	v_lshlrev_b32_e32 v230, 16, v1
	v_and_b32_e32 v231, 0xffff0000, v1
	v_mul_f32_e32 v230, v230, v218
	v_mul_f32_e32 v231, v231, v219
	v_cvt_pk_bf16_f32 v1, v230, v231
	v_mul_f32_e32 v218, v207, v164
	v_mul_f32_e32 v219, v207, v165
	v_lshlrev_b32_e32 v230, 16, v2
	v_and_b32_e32 v231, 0xffff0000, v2
	v_mul_f32_e32 v230, v230, v218
	v_mul_f32_e32 v231, v231, v219
	v_cvt_pk_bf16_f32 v2, v230, v231
	v_mul_f32_e32 v218, v207, v166
	v_mul_f32_e32 v219, v207, v167
	v_lshlrev_b32_e32 v230, 16, v3
	v_and_b32_e32 v231, 0xffff0000, v3
	v_mul_f32_e32 v230, v230, v218
	v_mul_f32_e32 v231, v231, v219
	v_cvt_pk_bf16_f32 v3, v230, v231
	global_store_dwordx4 v195, v[0:3], s[26:27]
	v_mul_f32_e32 v218, v208, v160
	v_mul_f32_e32 v219, v208, v161
	v_lshlrev_b32_e32 v230, 16, v4
	v_and_b32_e32 v231, 0xffff0000, v4
	v_mul_f32_e32 v230, v230, v218
	v_mul_f32_e32 v231, v231, v219
	v_cvt_pk_bf16_f32 v4, v230, v231
	v_mul_f32_e32 v218, v208, v162
	v_mul_f32_e32 v219, v208, v163
	v_lshlrev_b32_e32 v230, 16, v5
	v_and_b32_e32 v231, 0xffff0000, v5
	v_mul_f32_e32 v230, v230, v218
	v_mul_f32_e32 v231, v231, v219
	v_cvt_pk_bf16_f32 v5, v230, v231
	v_mul_f32_e32 v218, v208, v164
	v_mul_f32_e32 v219, v208, v165
	v_lshlrev_b32_e32 v230, 16, v6
	v_and_b32_e32 v231, 0xffff0000, v6
	v_mul_f32_e32 v230, v230, v218
	v_mul_f32_e32 v231, v231, v219
	v_cvt_pk_bf16_f32 v6, v230, v231
	v_mul_f32_e32 v218, v208, v166
	v_mul_f32_e32 v219, v208, v167
	v_lshlrev_b32_e32 v230, 16, v7
	v_and_b32_e32 v231, 0xffff0000, v7
	v_mul_f32_e32 v230, v230, v218
	v_mul_f32_e32 v231, v231, v219
	v_cvt_pk_bf16_f32 v7, v230, v231
	global_store_dwordx4 v195, v[4:7], s[26:27] offset:2048
	v_mul_f32_e32 v218, v209, v160
	v_mul_f32_e32 v219, v209, v161
	v_lshlrev_b32_e32 v230, 16, v8
	v_and_b32_e32 v231, 0xffff0000, v8
	v_mul_f32_e32 v230, v230, v218
	v_mul_f32_e32 v231, v231, v219
	v_cvt_pk_bf16_f32 v8, v230, v231
	v_mul_f32_e32 v218, v209, v162
	v_mul_f32_e32 v219, v209, v163
	v_lshlrev_b32_e32 v230, 16, v9
	v_and_b32_e32 v231, 0xffff0000, v9
	v_mul_f32_e32 v230, v230, v218
; DI u32x4 pack8(const float (&f)[8]) { u32x4 w; w.x = pk2(f[0], f[1]); w.y = pk2(f[2], f[3]); w.z = pk2(f[4], f[5]); w.w = pk2(f[6], f[7]); return w; }
; DI void phase_mla_qk(const Params& p) {
;     ...
;                 if (ok[r]) *(u32x4*)(qr + 3072 + head * 256 + l16 * 8) = pack8(f);
;     ...
;               for (int e = 0; e < 8; ++e) {
;                   const float a = f[e] * sc * gkr[e], pa = __shfl_xor(a, 4);
;                   float sn, cs; sincosf(pos * inv[e], &sn, &cs);
	v_mul_f32_e32 v231, v231, v219
	v_cvt_pk_bf16_f32 v9, v230, v231
	v_mul_f32_e32 v218, v209, v164
	v_mul_f32_e32 v219, v209, v165
	v_lshlrev_b32_e32 v230, 16, v10
	v_and_b32_e32 v231, 0xffff0000, v10
	v_mul_f32_e32 v230, v230, v218
	v_mul_f32_e32 v231, v231, v219
	v_cvt_pk_bf16_f32 v10, v230, v231
	v_mul_f32_e32 v218, v209, v166
	v_mul_f32_e32 v219, v209, v167
	v_lshlrev_b32_e32 v230, 16, v11
	v_and_b32_e32 v231, 0xffff0000, v11
	v_mul_f32_e32 v230, v230, v218
	v_mul_f32_e32 v231, v231, v219
	v_cvt_pk_bf16_f32 v11, v230, v231
	global_store_dwordx4 v195, v[8:11], s[30:31]
	v_mul_f32_e32 v218, v210, v160
	v_mul_f32_e32 v219, v210, v161
	v_lshlrev_b32_e32 v230, 16, v12
	v_and_b32_e32 v231, 0xffff0000, v12
	v_mul_f32_e32 v230, v230, v218
	v_mul_f32_e32 v231, v231, v219
	v_cvt_pk_bf16_f32 v12, v230, v231
	v_mul_f32_e32 v218, v210, v162
	v_mul_f32_e32 v219, v210, v163
	v_lshlrev_b32_e32 v230, 16, v13
	v_and_b32_e32 v231, 0xffff0000, v13
	v_mul_f32_e32 v230, v230, v218
	v_mul_f32_e32 v231, v231, v219
	v_cvt_pk_bf16_f32 v13, v230, v231
	v_mul_f32_e32 v218, v210, v164
	v_mul_f32_e32 v219, v210, v165
	v_lshlrev_b32_e32 v230, 16, v14
	v_and_b32_e32 v231, 0xffff0000, v14
	v_mul_f32_e32 v230, v230, v218
	v_mul_f32_e32 v231, v231, v219
	v_cvt_pk_bf16_f32 v14, v230, v231
	v_mul_f32_e32 v218, v210, v166
	v_mul_f32_e32 v219, v210, v167
	v_lshlrev_b32_e32 v230, 16, v15
	v_and_b32_e32 v231, 0xffff0000, v15
	v_mul_f32_e32 v230, v230, v218
	v_mul_f32_e32 v231, v231, v219
	v_cvt_pk_bf16_f32 v15, v230, v231
	global_store_dwordx4 v195, v[12:15], s[30:31] offset:2048
	s_add_u32 s36, s26, 0x1c00000
	s_addc_u32 s37, s27, 0
	s_add_u32 s30, s36, 0x1000
	s_addc_u32 s31, s37, 0
	v_mul_f32_e32 v218, v212, v160
	v_mul_f32_e32 v219, v212, v161
	v_lshlrev_b32_e32 v230, 16, v20
	v_and_b32_e32 v231, 0xffff0000, v20
	v_mul_f32_e32 v230, v230, v218
	v_mul_f32_e32 v231, v231, v219
	v_cvt_pk_bf16_f32 v20, v230, v231
	v_mul_f32_e32 v218, v212, v162
	v_mul_f32_e32 v219, v212, v163
	v_lshlrev_b32_e32 v230, 16, v21
	v_and_b32_e32 v231, 0xffff0000, v21
	v_mul_f32_e32 v230, v230, v218
	v_mul_f32_e32 v231, v231, v219
	v_cvt_pk_bf16_f32 v21, v230, v231
	v_mul_f32_e32 v218, v212, v164
	v_mul_f32_e32 v219, v212, v165
	v_lshlrev_b32_e32 v230, 16, v22
	v_and_b32_e32 v231, 0xffff0000, v22
	v_mul_f32_e32 v230, v230, v218
	v_mul_f32_e32 v231, v231, v219
	v_cvt_pk_bf16_f32 v22, v230, v231
	v_mul_f32_e32 v218, v212, v166
	v_mul_f32_e32 v219, v212, v167
	v_lshlrev_b32_e32 v230, 16, v23
	v_and_b32_e32 v231, 0xffff0000, v23
	v_mul_f32_e32 v230, v230, v218
	v_mul_f32_e32 v231, v231, v219
	v_cvt_pk_bf16_f32 v23, v230, v231
	global_store_dwordx4 v195, v[20:23], s[36:37]
	v_mul_f32_e32 v218, v213, v160
	v_mul_f32_e32 v219, v213, v161
	v_lshlrev_b32_e32 v230, 16, v24
	v_and_b32_e32 v231, 0xffff0000, v24
	v_mul_f32_e32 v230, v230, v218
	v_mul_f32_e32 v231, v231, v219
	v_cvt_pk_bf16_f32 v24, v230, v231
	v_mul_f32_e32 v218, v213, v162
	v_mul_f32_e32 v219, v213, v163
	v_lshlrev_b32_e32 v230, 16, v25
	v_and_b32_e32 v231, 0xffff0000, v25
	v_mul_f32_e32 v230, v230, v218
	v_mul_f32_e32 v231, v231, v219
	v_cvt_pk_bf16_f32 v25, v230, v231
	v_mul_f32_e32 v218, v213, v164
	v_mul_f32_e32 v219, v213, v165
	v_lshlrev_b32_e32 v230, 16, v26
	v_and_b32_e32 v231, 0xffff0000, v26
	v_mul_f32_e32 v230, v230, v218
	v_mul_f32_e32 v231, v231, v219
	v_cvt_pk_bf16_f32 v26, v230, v231
	v_mul_f32_e32 v218, v213, v166
	v_mul_f32_e32 v219, v213, v167
	v_lshlrev_b32_e32 v230, 16, v27
	v_and_b32_e32 v231, 0xffff0000, v27
	v_mul_f32_e32 v230, v230, v218
	v_mul_f32_e32 v231, v231, v219
	v_cvt_pk_bf16_f32 v27, v230, v231
	global_store_dwordx4 v195, v[24:27], s[36:37] offset:2048
	v_mul_f32_e32 v218, v214, v160
	v_mul_f32_e32 v219, v214, v161
	v_lshlrev_b32_e32 v230, 16, v28
	v_and_b32_e32 v231, 0xffff0000, v28
	v_mul_f32_e32 v230, v230, v218
	v_mul_f32_e32 v231, v231, v219
	v_cvt_pk_bf16_f32 v28, v230, v231
	v_mul_f32_e32 v218, v214, v162
	v_mul_f32_e32 v219, v214, v163
	v_lshlrev_b32_e32 v230, 16, v29
	v_and_b32_e32 v231, 0xffff0000, v29
	v_mul_f32_e32 v230, v230, v218
	v_mul_f32_e32 v231, v231, v219
	v_cvt_pk_bf16_f32 v29, v230, v231
	v_mul_f32_e32 v218, v214, v164
	v_mul_f32_e32 v219, v214, v165
	v_lshlrev_b32_e32 v230, 16, v30
	v_and_b32_e32 v231, 0xffff0000, v30
	v_mul_f32_e32 v230, v230, v218
	v_mul_f32_e32 v231, v231, v219
	v_cvt_pk_bf16_f32 v30, v230, v231
	v_mul_f32_e32 v218, v214, v166
	v_mul_f32_e32 v219, v214, v167
	v_lshlrev_b32_e32 v230, 16, v31
	v_and_b32_e32 v231, 0xffff0000, v31
	v_mul_f32_e32 v230, v230, v218
	v_mul_f32_e32 v231, v231, v219
	v_cvt_pk_bf16_f32 v31, v230, v231
	global_store_dwordx4 v195, v[28:31], s[30:31]
	v_mul_f32_e32 v218, v215, v160
	v_mul_f32_e32 v219, v215, v161
	v_lshlrev_b32_e32 v230, 16, v32
	v_and_b32_e32 v231, 0xffff0000, v32
	v_mul_f32_e32 v230, v230, v218
	v_mul_f32_e32 v231, v231, v219
	v_cvt_pk_bf16_f32 v32, v230, v231
	v_mul_f32_e32 v218, v215, v162
	v_mul_f32_e32 v219, v215, v163
	v_lshlrev_b32_e32 v230, 16, v33
	v_and_b32_e32 v231, 0xffff0000, v33
	v_mul_f32_e32 v230, v230, v218
	v_mul_f32_e32 v231, v231, v219
	v_cvt_pk_bf16_f32 v33, v230, v231
	v_mul_f32_e32 v218, v215, v164
	v_mul_f32_e32 v219, v215, v165
	v_lshlrev_b32_e32 v230, 16, v34
	v_and_b32_e32 v231, 0xffff0000, v34
	v_mul_f32_e32 v230, v230, v218
	v_mul_f32_e32 v231, v231, v219
	v_cvt_pk_bf16_f32 v34, v230, v231
	v_mul_f32_e32 v218, v215, v166
	v_mul_f32_e32 v219, v215, v167
	v_lshlrev_b32_e32 v230, 16, v35
	v_and_b32_e32 v231, 0xffff0000, v35
	v_mul_f32_e32 v230, v230, v218
	v_mul_f32_e32 v231, v231, v219
	v_cvt_pk_bf16_f32 v35, v230, v231
	global_store_dwordx4 v195, v[32:35], s[30:31] offset:2048
	v_lshlrev_b32_e32 v232, 16, v16
	v_and_b32_e32 v233, 0xffff0000, v16
	v_lshlrev_b32_e32 v234, 16, v17
	v_and_b32_e32 v235, 0xffff0000, v17
	v_lshlrev_b32_e32 v236, 16, v18
	v_and_b32_e32 v237, 0xffff0000, v18
	v_lshlrev_b32_e32 v238, 16, v19
	v_and_b32_e32 v239, 0xffff0000, v19
	v_mul_f32_e32 v232, v232, v211
	v_mul_f32_e32 v233, v233, v211
	v_mul_f32_e32 v234, v234, v211
	v_mul_f32_e32 v235, v235, v211
	v_mul_f32_e32 v236, v236, v211
	v_mul_f32_e32 v237, v237, v211
	v_mul_f32_e32 v238, v238, v211
	v_mul_f32_e32 v239, v239, v211
	v_mul_f32_e32 v232, v232, v168
	v_mul_f32_e32 v233, v233, v169
	v_mul_f32_e32 v234, v234, v170
	v_mul_f32_e32 v235, v235, v171
	v_mul_f32_e32 v236, v236, v172
	v_mul_f32_e32 v237, v237, v173
	v_mul_f32_e32 v238, v238, v174
	v_mul_f32_e32 v239, v239, v175
	ds_bpermute_b32 v240, v193, v232
	ds_bpermute_b32 v241, v193, v233
	ds_bpermute_b32 v242, v193, v234
	ds_bpermute_b32 v243, v193, v235
	ds_bpermute_b32 v244, v193, v236
	ds_bpermute_b32 v245, v193, v237
	ds_bpermute_b32 v246, v193, v238
	ds_bpermute_b32 v247, v193, v239
	s_and_b32 s35, s34, 0xfff
	v_cvt_f32_u32_e32 v218, s35
	v_mul_f32_e32 v218, 0x3e22f983, v218
	s_waitcnt lgkmcnt(0)
; DI u32x4 pack8(const float (&f)[8]) { u32x4 w; w.x = pk2(f[0], f[1]); w.y = pk2(f[2], f[3]); w.z = pk2(f[4], f[5]); w.w = pk2(f[6], f[7]); return w; }
; DI void phase_mla_qk(const Params& p) {
;     ...
;               for (int e = 0; e < 8; ++e) {
;                   const float a = f[e] * sc * gkr[e], pa = __shfl_xor(a, 4);
;                   float sn, cs; sincosf(pos * inv[e], &sn, &cs);
;                   o[e] = (l8 < 4) ? a * cs - pa * sn : a * cs + pa * sn;
;               }
;               if (ok[r] && lane < 8) *(u32x4*)kpp = pack8(o); }
	v_mul_f32_e32 v220, v218, v182
	v_fract_f32_e32 v220, v220
	v_sin_f32_e32 v221, v220
	v_cos_f32_e32 v222, v220
	v_mul_f32_e32 v240, v240, v190
	v_mul_f32_e32 v240, v240, v221
	v_fma_f32 v232, v232, v222, v240
	v_mul_f32_e32 v223, v218, v183
	v_fract_f32_e32 v223, v223
	v_sin_f32_e32 v224, v223
	v_cos_f32_e32 v225, v223
	v_mul_f32_e32 v241, v241, v190
	v_mul_f32_e32 v241, v241, v224
	v_fma_f32 v233, v233, v225, v241
	v_mul_f32_e32 v220, v218, v184
	v_fract_f32_e32 v220, v220
	v_sin_f32_e32 v221, v220
	v_cos_f32_e32 v222, v220
	v_mul_f32_e32 v242, v242, v190
	v_mul_f32_e32 v242, v242, v221
	v_fma_f32 v234, v234, v222, v242
	v_mul_f32_e32 v223, v218, v185
	v_fract_f32_e32 v223, v223
	v_sin_f32_e32 v224, v223
	v_cos_f32_e32 v225, v223
	v_mul_f32_e32 v243, v243, v190
	v_mul_f32_e32 v243, v243, v224
	v_fma_f32 v235, v235, v225, v243
	v_mul_f32_e32 v220, v218, v186
	v_fract_f32_e32 v220, v220
	v_sin_f32_e32 v221, v220
	v_cos_f32_e32 v222, v220
	v_mul_f32_e32 v244, v244, v190
	v_mul_f32_e32 v244, v244, v221
	v_fma_f32 v236, v236, v222, v244
	v_mul_f32_e32 v223, v218, v187
	v_fract_f32_e32 v223, v223
	v_sin_f32_e32 v224, v223
	v_cos_f32_e32 v225, v223
	v_mul_f32_e32 v245, v245, v190
	v_mul_f32_e32 v245, v245, v224
	v_fma_f32 v237, v237, v225, v245
	v_mul_f32_e32 v220, v218, v188
	v_fract_f32_e32 v220, v220
	v_sin_f32_e32 v221, v220
	v_cos_f32_e32 v222, v220
	v_mul_f32_e32 v246, v246, v190
	v_mul_f32_e32 v246, v246, v221
	v_fma_f32 v238, v238, v222, v246
	v_mul_f32_e32 v223, v218, v189
	v_fract_f32_e32 v223, v223
	v_sin_f32_e32 v224, v223
	v_cos_f32_e32 v225, v223
	v_mul_f32_e32 v247, v247, v190
	v_mul_f32_e32 v247, v247, v224
	v_fma_f32 v239, v239, v225, v247
	v_cvt_pk_bf16_f32 v16, v232, v233
	v_cvt_pk_bf16_f32 v17, v234, v235
	v_cvt_pk_bf16_f32 v18, v236, v237
	v_cvt_pk_bf16_f32 v19, v238, v239
	s_mov_b64 exec, 0xff
	global_store_dwordx4 v196, v[16:19], s[28:29]
	s_mov_b64 exec, -1
	v_lshlrev_b32_e32 v232, 16, v36
	v_and_b32_e32 v233, 0xffff0000, v36
	v_lshlrev_b32_e32 v234, 16, v37
	v_and_b32_e32 v235, 0xffff0000, v37
	v_lshlrev_b32_e32 v236, 16, v38
	v_and_b32_e32 v237, 0xffff0000, v38
	v_lshlrev_b32_e32 v238, 16, v39
	v_and_b32_e32 v239, 0xffff0000, v39
	v_mul_f32_e32 v232, v232, v216
	v_mul_f32_e32 v233, v233, v216
	v_mul_f32_e32 v234, v234, v216
	v_mul_f32_e32 v235, v235, v216
	v_mul_f32_e32 v236, v236, v216
	v_mul_f32_e32 v237, v237, v216
	v_mul_f32_e32 v238, v238, v216
	v_mul_f32_e32 v239, v239, v216
	v_mul_f32_e32 v232, v232, v168
	v_mul_f32_e32 v233, v233, v169
	v_mul_f32_e32 v234, v234, v170
	v_mul_f32_e32 v235, v235, v171
	v_mul_f32_e32 v236, v236, v172
	v_mul_f32_e32 v237, v237, v173
	v_mul_f32_e32 v238, v238, v174
	v_mul_f32_e32 v239, v239, v175
	ds_bpermute_b32 v240, v193, v232
	ds_bpermute_b32 v241, v193, v233
	ds_bpermute_b32 v242, v193, v234
	ds_bpermute_b32 v243, v193, v235
	ds_bpermute_b32 v244, v193, v236
	ds_bpermute_b32 v245, v193, v237
	ds_bpermute_b32 v246, v193, v238
	ds_bpermute_b32 v247, v193, v239
	s_add_i32 s35, s34, 0x800
	s_and_b32 s35, s35, 0xfff
	v_cvt_f32_u32_e32 v218, s35
	v_mul_f32_e32 v218, 0x3e22f983, v218
	s_waitcnt lgkmcnt(0)
	v_mul_f32_e32 v220, v218, v182
	v_fract_f32_e32 v220, v220
	v_sin_f32_e32 v221, v220
	v_cos_f32_e32 v222, v220
	v_mul_f32_e32 v240, v240, v190
	v_mul_f32_e32 v240, v240, v221
	v_fma_f32 v232, v232, v222, v240
	v_mul_f32_e32 v223, v218, v183
	v_fract_f32_e32 v223, v223
	v_sin_f32_e32 v224, v223
	v_cos_f32_e32 v225, v223
	v_mul_f32_e32 v241, v241, v190
	v_mul_f32_e32 v241, v241, v224
	v_fma_f32 v233, v233, v225, v241
	v_mul_f32_e32 v220, v218, v184
	v_fract_f32_e32 v220, v220
	v_sin_f32_e32 v221, v220
	v_cos_f32_e32 v222, v220
	v_mul_f32_e32 v242, v242, v190
	v_mul_f32_e32 v242, v242, v221
	v_fma_f32 v234, v234, v222, v242
	v_mul_f32_e32 v223, v218, v185
	v_fract_f32_e32 v223, v223
	v_sin_f32_e32 v224, v223
	v_cos_f32_e32 v225, v223
	v_mul_f32_e32 v243, v243, v190
	v_mul_f32_e32 v243, v243, v224
	v_fma_f32 v235, v235, v225, v243
	v_mul_f32_e32 v220, v218, v186
	v_fract_f32_e32 v220, v220
	v_sin_f32_e32 v221, v220
	v_cos_f32_e32 v222, v220
	v_mul_f32_e32 v244, v244, v190
	v_mul_f32_e32 v244, v244, v221
	v_fma_f32 v236, v236, v222, v244
	v_mul_f32_e32 v223, v218, v187
	v_fract_f32_e32 v223, v223
	v_sin_f32_e32 v224, v223
	v_cos_f32_e32 v225, v223
	v_mul_f32_e32 v245, v245, v190
	v_mul_f32_e32 v245, v245, v224
	v_fma_f32 v237, v237, v225, v245
	v_mul_f32_e32 v220, v218, v188
	v_fract_f32_e32 v220, v220
	v_sin_f32_e32 v221, v220
	v_cos_f32_e32 v222, v220
	v_mul_f32_e32 v246, v246, v190
	v_mul_f32_e32 v246, v246, v221
	v_fma_f32 v238, v238, v222, v246
	v_mul_f32_e32 v223, v218, v189
	v_fract_f32_e32 v223, v223
	v_sin_f32_e32 v224, v223
	v_cos_f32_e32 v225, v223
	v_mul_f32_e32 v247, v247, v190
	v_mul_f32_e32 v247, v247, v224
	v_fma_f32 v239, v239, v225, v247
	v_cvt_pk_bf16_f32 v36, v232, v233
	v_cvt_pk_bf16_f32 v37, v234, v235
	v_cvt_pk_bf16_f32 v38, v236, v237
	v_cvt_pk_bf16_f32 v39, v238, v239
	s_add_u32 s36, s28, 0x440000
	s_addc_u32 s37, s29, 0
	s_mov_b64 exec, 0xff
	global_store_dwordx4 v196, v[36:39], s[36:37]
	s_mov_b64 exec, -1
	s_add_u32 s26, s26, 0x3800000
	s_addc_u32 s27, s27, 0
	s_add_u32 s28, s28, 0x880000
	s_addc_u32 s29, s29, 0
	s_addk_i32 s34, 0x1000
	s_waitcnt vmcnt(30)
; DI void phase_mla_qk(const Params& p) {
;     ...
;                 float f[8]; unpack8(wk[r][i], f); float ss = 0.f;
; #pragma unroll
;                 for (int e = 0; e < 8; ++e) ss += f[e] * f[e];
;                 ss += __shfl_xor(ss, 1); ss += __shfl_xor(ss, 2); ss += __shfl_xor(ss, 4); ss += __shfl_xor(ss, 8);
;     ...
;             { float f[8], o[8]; unpack8(wp[r], f); float ss = 0.f;
; #pragma unroll
;               for (int e = 0; e < 8; ++e) ss += f[e] * f[e];
;               ss += __shfl_xor(ss, 1); ss += __shfl_xor(ss, 2); ss += __shfl_xor(ss, 4);
	v_lshlrev_b32_e32 v218, 16, v40
	v_and_b32_e32 v219, 0xffff0000, v40
	v_mul_f32_e32 v207, v218, v218
	v_fmac_f32_e32 v207, v219, v219
	v_lshlrev_b32_e32 v218, 16, v41
	v_and_b32_e32 v219, 0xffff0000, v41
	v_fmac_f32_e32 v207, v218, v218
	v_fmac_f32_e32 v207, v219, v219
	v_lshlrev_b32_e32 v218, 16, v42
	v_and_b32_e32 v219, 0xffff0000, v42
	v_fmac_f32_e32 v207, v218, v218
	v_fmac_f32_e32 v207, v219, v219
	v_lshlrev_b32_e32 v218, 16, v43
	v_and_b32_e32 v219, 0xffff0000, v43
	v_fmac_f32_e32 v207, v218, v218
	v_fmac_f32_e32 v207, v219, v219
	v_lshlrev_b32_e32 v218, 16, v44
	v_and_b32_e32 v219, 0xffff0000, v44
	v_mul_f32_e32 v208, v218, v218
	v_fmac_f32_e32 v208, v219, v219
	v_lshlrev_b32_e32 v218, 16, v45
	v_and_b32_e32 v219, 0xffff0000, v45
	v_fmac_f32_e32 v208, v218, v218
	v_fmac_f32_e32 v208, v219, v219
	v_lshlrev_b32_e32 v218, 16, v46
	v_and_b32_e32 v219, 0xffff0000, v46
	v_fmac_f32_e32 v208, v218, v218
	v_fmac_f32_e32 v208, v219, v219
	v_lshlrev_b32_e32 v218, 16, v47
	v_and_b32_e32 v219, 0xffff0000, v47
	v_fmac_f32_e32 v208, v218, v218
	v_fmac_f32_e32 v208, v219, v219
	v_lshlrev_b32_e32 v218, 16, v48
	v_and_b32_e32 v219, 0xffff0000, v48
	v_mul_f32_e32 v209, v218, v218
	v_fmac_f32_e32 v209, v219, v219
	v_lshlrev_b32_e32 v218, 16, v49
	v_and_b32_e32 v219, 0xffff0000, v49
	v_fmac_f32_e32 v209, v218, v218
	v_fmac_f32_e32 v209, v219, v219
	v_lshlrev_b32_e32 v218, 16, v50
	v_and_b32_e32 v219, 0xffff0000, v50
	v_fmac_f32_e32 v209, v218, v218
	v_fmac_f32_e32 v209, v219, v219
	v_lshlrev_b32_e32 v218, 16, v51
	v_and_b32_e32 v219, 0xffff0000, v51
	v_fmac_f32_e32 v209, v218, v218
	v_fmac_f32_e32 v209, v219, v219
	v_lshlrev_b32_e32 v218, 16, v52
	v_and_b32_e32 v219, 0xffff0000, v52
	v_mul_f32_e32 v210, v218, v218
	v_fmac_f32_e32 v210, v219, v219
	v_lshlrev_b32_e32 v218, 16, v53
	v_and_b32_e32 v219, 0xffff0000, v53
	v_fmac_f32_e32 v210, v218, v218
	v_fmac_f32_e32 v210, v219, v219
	v_lshlrev_b32_e32 v218, 16, v54
	v_and_b32_e32 v219, 0xffff0000, v54
	v_fmac_f32_e32 v210, v218, v218
	v_fmac_f32_e32 v210, v219, v219
	v_lshlrev_b32_e32 v218, 16, v55
	v_and_b32_e32 v219, 0xffff0000, v55
	v_fmac_f32_e32 v210, v218, v218
	v_fmac_f32_e32 v210, v219, v219
	v_lshlrev_b32_e32 v218, 16, v56
	v_and_b32_e32 v219, 0xffff0000, v56
	v_mul_f32_e32 v211, v218, v218
	v_fmac_f32_e32 v211, v219, v219
	v_lshlrev_b32_e32 v218, 16, v57
	v_and_b32_e32 v219, 0xffff0000, v57
	v_fmac_f32_e32 v211, v218, v218
	v_fmac_f32_e32 v211, v219, v219
	v_lshlrev_b32_e32 v218, 16, v58
	v_and_b32_e32 v219, 0xffff0000, v58
	v_fmac_f32_e32 v211, v218, v218
	v_fmac_f32_e32 v211, v219, v219
	v_lshlrev_b32_e32 v218, 16, v59
	v_and_b32_e32 v219, 0xffff0000, v59
	v_fmac_f32_e32 v211, v218, v218
	v_fmac_f32_e32 v211, v219, v219
	v_lshlrev_b32_e32 v218, 16, v60
	v_and_b32_e32 v219, 0xffff0000, v60
	v_mul_f32_e32 v212, v218, v218
	v_fmac_f32_e32 v212, v219, v219
	v_lshlrev_b32_e32 v218, 16, v61
	v_and_b32_e32 v219, 0xffff0000, v61
	v_fmac_f32_e32 v212, v218, v218
	v_fmac_f32_e32 v212, v219, v219
	v_lshlrev_b32_e32 v218, 16, v62
	v_and_b32_e32 v219, 0xffff0000, v62
	v_fmac_f32_e32 v212, v218, v218
	v_fmac_f32_e32 v212, v219, v219
	v_lshlrev_b32_e32 v218, 16, v63
	v_and_b32_e32 v219, 0xffff0000, v63
	v_fmac_f32_e32 v212, v218, v218
	v_fmac_f32_e32 v212, v219, v219
	v_lshlrev_b32_e32 v218, 16, v64
	v_and_b32_e32 v219, 0xffff0000, v64
	v_mul_f32_e32 v213, v218, v218
	v_fmac_f32_e32 v213, v219, v219
	v_lshlrev_b32_e32 v218, 16, v65
	v_and_b32_e32 v219, 0xffff0000, v65
	v_fmac_f32_e32 v213, v218, v218
	v_fmac_f32_e32 v213, v219, v219
	v_lshlrev_b32_e32 v218, 16, v66
	v_and_b32_e32 v219, 0xffff0000, v66
	v_fmac_f32_e32 v213, v218, v218
	v_fmac_f32_e32 v213, v219, v219
	v_lshlrev_b32_e32 v218, 16, v67
	v_and_b32_e32 v219, 0xffff0000, v67
	v_fmac_f32_e32 v213, v218, v218
	v_fmac_f32_e32 v213, v219, v219
	v_lshlrev_b32_e32 v218, 16, v68
	v_and_b32_e32 v219, 0xffff0000, v68
	v_mul_f32_e32 v214, v218, v218
	v_fmac_f32_e32 v214, v219, v219
	v_lshlrev_b32_e32 v218, 16, v69
	v_and_b32_e32 v219, 0xffff0000, v69
	v_fmac_f32_e32 v214, v218, v218
	v_fmac_f32_e32 v214, v219, v219
	v_lshlrev_b32_e32 v218, 16, v70
	v_and_b32_e32 v219, 0xffff0000, v70
	v_fmac_f32_e32 v214, v218, v218
	v_fmac_f32_e32 v214, v219, v219
	v_lshlrev_b32_e32 v218, 16, v71
	v_and_b32_e32 v219, 0xffff0000, v71
	v_fmac_f32_e32 v214, v218, v218
	v_fmac_f32_e32 v214, v219, v219
	v_lshlrev_b32_e32 v218, 16, v72
	v_and_b32_e32 v219, 0xffff0000, v72
	v_mul_f32_e32 v215, v218, v218
	v_fmac_f32_e32 v215, v219, v219
	v_lshlrev_b32_e32 v218, 16, v73
	v_and_b32_e32 v219, 0xffff0000, v73
	v_fmac_f32_e32 v215, v218, v218
	v_fmac_f32_e32 v215, v219, v219
	v_lshlrev_b32_e32 v218, 16, v74
	v_and_b32_e32 v219, 0xffff0000, v74
	v_fmac_f32_e32 v215, v218, v218
	v_fmac_f32_e32 v215, v219, v219
	v_lshlrev_b32_e32 v218, 16, v75
	v_and_b32_e32 v219, 0xffff0000, v75
	v_fmac_f32_e32 v215, v218, v218
	v_fmac_f32_e32 v215, v219, v219
	v_lshlrev_b32_e32 v218, 16, v76
	v_and_b32_e32 v219, 0xffff0000, v76
	v_mul_f32_e32 v216, v218, v218
	v_fmac_f32_e32 v216, v219, v219
	v_lshlrev_b32_e32 v218, 16, v77
	v_and_b32_e32 v219, 0xffff0000, v77
	v_fmac_f32_e32 v216, v218, v218
	v_fmac_f32_e32 v216, v219, v219
	v_lshlrev_b32_e32 v218, 16, v78
	v_and_b32_e32 v219, 0xffff0000, v78
	v_fmac_f32_e32 v216, v218, v218
	v_fmac_f32_e32 v216, v219, v219
	v_lshlrev_b32_e32 v218, 16, v79
	v_and_b32_e32 v219, 0xffff0000, v79
	v_fmac_f32_e32 v216, v218, v218
	v_fmac_f32_e32 v216, v219, v219
	ds_bpermute_b32 v220, v191, v207
	ds_bpermute_b32 v221, v191, v208
	ds_bpermute_b32 v222, v191, v209
	ds_bpermute_b32 v223, v191, v210
	ds_bpermute_b32 v224, v191, v211
	ds_bpermute_b32 v225, v191, v212
	ds_bpermute_b32 v226, v191, v213
	ds_bpermute_b32 v227, v191, v214
	ds_bpermute_b32 v228, v191, v215
	ds_bpermute_b32 v229, v191, v216
	s_waitcnt lgkmcnt(0)
; DI u32x4 pack8(const float (&f)[8]) { u32x4 w; w.x = pk2(f[0], f[1]); w.y = pk2(f[2], f[3]); w.z = pk2(f[4], f[5]); w.w = pk2(f[6], f[7]); return w; }
; DI void phase_mla_qk(const Params& p) {
;     ...
;                 ss += __shfl_xor(ss, 1); ss += __shfl_xor(ss, 2); ss += __shfl_xor(ss, 4); ss += __shfl_xor(ss, 8);
;                 const float sc = rsqrtf(ss * (1.f / 128.f) + EPS);
; #pragma unroll
;                 for (int e = 0; e < 8; ++e) f[e] *= sc * gk[e];
;                 if (ok[r]) *(u32x4*)(qr + 3072 + head * 256 + l16 * 8) = pack8(f);
	v_add_f32_e32 v207, v207, v220
	v_add_f32_e32 v208, v208, v221
	v_add_f32_e32 v209, v209, v222
	v_add_f32_e32 v210, v210, v223
	v_add_f32_e32 v211, v211, v224
	v_add_f32_e32 v212, v212, v225
	v_add_f32_e32 v213, v213, v226
	v_add_f32_e32 v214, v214, v227
	v_add_f32_e32 v215, v215, v228
	v_add_f32_e32 v216, v216, v229
	ds_bpermute_b32 v220, v192, v207
	ds_bpermute_b32 v221, v192, v208
	ds_bpermute_b32 v222, v192, v209
	ds_bpermute_b32 v223, v192, v210
	ds_bpermute_b32 v224, v192, v211
	ds_bpermute_b32 v225, v192, v212
	ds_bpermute_b32 v226, v192, v213
	ds_bpermute_b32 v227, v192, v214
	ds_bpermute_b32 v228, v192, v215
	ds_bpermute_b32 v229, v192, v216
	s_waitcnt lgkmcnt(0)
	v_add_f32_e32 v207, v207, v220
	v_add_f32_e32 v208, v208, v221
	v_add_f32_e32 v209, v209, v222
	v_add_f32_e32 v210, v210, v223
	v_add_f32_e32 v211, v211, v224
	v_add_f32_e32 v212, v212, v225
	v_add_f32_e32 v213, v213, v226
	v_add_f32_e32 v214, v214, v227
	v_add_f32_e32 v215, v215, v228
	v_add_f32_e32 v216, v216, v229
	ds_bpermute_b32 v220, v193, v207
	ds_bpermute_b32 v221, v193, v208
	ds_bpermute_b32 v222, v193, v209
	ds_bpermute_b32 v223, v193, v210
	ds_bpermute_b32 v224, v193, v211
	ds_bpermute_b32 v225, v193, v212
	ds_bpermute_b32 v226, v193, v213
	ds_bpermute_b32 v227, v193, v214
	ds_bpermute_b32 v228, v193, v215
	ds_bpermute_b32 v229, v193, v216
	s_waitcnt lgkmcnt(0)
	v_add_f32_e32 v207, v207, v220
	v_add_f32_e32 v208, v208, v221
	v_add_f32_e32 v209, v209, v222
	v_add_f32_e32 v210, v210, v223
	v_add_f32_e32 v211, v211, v224
	v_add_f32_e32 v212, v212, v225
	v_add_f32_e32 v213, v213, v226
	v_add_f32_e32 v214, v214, v227
	v_add_f32_e32 v215, v215, v228
	v_add_f32_e32 v216, v216, v229
	ds_bpermute_b32 v220, v194, v207
	ds_bpermute_b32 v221, v194, v208
	ds_bpermute_b32 v222, v194, v209
	ds_bpermute_b32 v223, v194, v210
	ds_bpermute_b32 v225, v194, v212
	ds_bpermute_b32 v226, v194, v213
	ds_bpermute_b32 v227, v194, v214
	ds_bpermute_b32 v228, v194, v215
	s_waitcnt lgkmcnt(0)
	v_add_f32_e32 v207, v207, v220
	v_add_f32_e32 v208, v208, v221
	v_add_f32_e32 v209, v209, v222
	v_add_f32_e32 v210, v210, v223
	v_add_f32_e32 v212, v212, v225
	v_add_f32_e32 v213, v213, v226
	v_add_f32_e32 v214, v214, v227
	v_add_f32_e32 v215, v215, v228
	v_mul_f32_e32 v207, 0x3c000000, v207
	v_add_f32_e32 v207, 0x358637bd, v207
	v_mul_f32_e32 v208, 0x3c000000, v208
	v_add_f32_e32 v208, 0x358637bd, v208
	v_mul_f32_e32 v209, 0x3c000000, v209
	v_add_f32_e32 v209, 0x358637bd, v209
	v_mul_f32_e32 v210, 0x3c000000, v210
	v_add_f32_e32 v210, 0x358637bd, v210
	v_mul_f32_e32 v211, 0x3c800000, v211
	v_add_f32_e32 v211, 0x358637bd, v211
	v_mul_f32_e32 v212, 0x3c000000, v212
	v_add_f32_e32 v212, 0x358637bd, v212
	v_mul_f32_e32 v213, 0x3c000000, v213
	v_add_f32_e32 v213, 0x358637bd, v213
	v_mul_f32_e32 v214, 0x3c000000, v214
	v_add_f32_e32 v214, 0x358637bd, v214
	v_mul_f32_e32 v215, 0x3c000000, v215
	v_add_f32_e32 v215, 0x358637bd, v215
	v_mul_f32_e32 v216, 0x3c800000, v216
	v_add_f32_e32 v216, 0x358637bd, v216
	v_rsq_f32_e32 v207, v207
	v_rsq_f32_e32 v208, v208
	v_rsq_f32_e32 v209, v209
	v_rsq_f32_e32 v210, v210
	v_rsq_f32_e32 v211, v211
	v_rsq_f32_e32 v212, v212
	v_rsq_f32_e32 v213, v213
	v_rsq_f32_e32 v214, v214
	v_rsq_f32_e32 v215, v215
	v_rsq_f32_e32 v216, v216
	s_nop 1
	s_add_u32 s30, s26, 0x1000
	s_addc_u32 s31, s27, 0
	v_mul_f32_e32 v218, v207, v160
	v_mul_f32_e32 v219, v207, v161
	v_lshlrev_b32_e32 v230, 16, v40
	v_and_b32_e32 v231, 0xffff0000, v40
	v_mul_f32_e32 v230, v230, v218
	v_mul_f32_e32 v231, v231, v219
	v_cvt_pk_bf16_f32 v40, v230, v231
	v_mul_f32_e32 v218, v207, v162
	v_mul_f32_e32 v219, v207, v163
	v_lshlrev_b32_e32 v230, 16, v41
	v_and_b32_e32 v231, 0xffff0000, v41
	v_mul_f32_e32 v230, v230, v218
	v_mul_f32_e32 v231, v231, v219
	v_cvt_pk_bf16_f32 v41, v230, v231
	v_mul_f32_e32 v218, v207, v164
	v_mul_f32_e32 v219, v207, v165
	v_lshlrev_b32_e32 v230, 16, v42
	v_and_b32_e32 v231, 0xffff0000, v42
	v_mul_f32_e32 v230, v230, v218
	v_mul_f32_e32 v231, v231, v219
	v_cvt_pk_bf16_f32 v42, v230, v231
	v_mul_f32_e32 v218, v207, v166
	v_mul_f32_e32 v219, v207, v167
	v_lshlrev_b32_e32 v230, 16, v43
	v_and_b32_e32 v231, 0xffff0000, v43
	v_mul_f32_e32 v230, v230, v218
	v_mul_f32_e32 v231, v231, v219
	v_cvt_pk_bf16_f32 v43, v230, v231
	global_store_dwordx4 v195, v[40:43], s[26:27]
	v_mul_f32_e32 v218, v208, v160
	v_mul_f32_e32 v219, v208, v161
	v_lshlrev_b32_e32 v230, 16, v44
	v_and_b32_e32 v231, 0xffff0000, v44
	v_mul_f32_e32 v230, v230, v218
	v_mul_f32_e32 v231, v231, v219
	v_cvt_pk_bf16_f32 v44, v230, v231
	v_mul_f32_e32 v218, v208, v162
	v_mul_f32_e32 v219, v208, v163
	v_lshlrev_b32_e32 v230, 16, v45
	v_and_b32_e32 v231, 0xffff0000, v45
	v_mul_f32_e32 v230, v230, v218
	v_mul_f32_e32 v231, v231, v219
	v_cvt_pk_bf16_f32 v45, v230, v231
	v_mul_f32_e32 v218, v208, v164
	v_mul_f32_e32 v219, v208, v165
	v_lshlrev_b32_e32 v230, 16, v46
	v_and_b32_e32 v231, 0xffff0000, v46
	v_mul_f32_e32 v230, v230, v218
	v_mul_f32_e32 v231, v231, v219
	v_cvt_pk_bf16_f32 v46, v230, v231
	v_mul_f32_e32 v218, v208, v166
	v_mul_f32_e32 v219, v208, v167
	v_lshlrev_b32_e32 v230, 16, v47
	v_and_b32_e32 v231, 0xffff0000, v47
	v_mul_f32_e32 v230, v230, v218
	v_mul_f32_e32 v231, v231, v219
	v_cvt_pk_bf16_f32 v47, v230, v231
	global_store_dwordx4 v195, v[44:47], s[26:27] offset:2048
	v_mul_f32_e32 v218, v209, v160
	v_mul_f32_e32 v219, v209, v161
	v_lshlrev_b32_e32 v230, 16, v48
	v_and_b32_e32 v231, 0xffff0000, v48
	v_mul_f32_e32 v230, v230, v218
	v_mul_f32_e32 v231, v231, v219
	v_cvt_pk_bf16_f32 v48, v230, v231
	v_mul_f32_e32 v218, v209, v162
	v_mul_f32_e32 v219, v209, v163
	v_lshlrev_b32_e32 v230, 16, v49
	v_and_b32_e32 v231, 0xffff0000, v49
; DI u32x4 pack8(const float (&f)[8]) { u32x4 w; w.x = pk2(f[0], f[1]); w.y = pk2(f[2], f[3]); w.z = pk2(f[4], f[5]); w.w = pk2(f[6], f[7]); return w; }
; DI void phase_mla_qk(const Params& p) {
;     ...
;                 if (ok[r]) *(u32x4*)(qr + 3072 + head * 256 + l16 * 8) = pack8(f);
;     ...
;               for (int e = 0; e < 8; ++e) {
;                   const float a = f[e] * sc * gkr[e], pa = __shfl_xor(a, 4);
;                   float sn, cs; sincosf(pos * inv[e], &sn, &cs);
	v_mul_f32_e32 v230, v230, v218
	v_mul_f32_e32 v231, v231, v219
	v_cvt_pk_bf16_f32 v49, v230, v231
	v_mul_f32_e32 v218, v209, v164
	v_mul_f32_e32 v219, v209, v165
	v_lshlrev_b32_e32 v230, 16, v50
	v_and_b32_e32 v231, 0xffff0000, v50
	v_mul_f32_e32 v230, v230, v218
	v_mul_f32_e32 v231, v231, v219
	v_cvt_pk_bf16_f32 v50, v230, v231
	v_mul_f32_e32 v218, v209, v166
	v_mul_f32_e32 v219, v209, v167
	v_lshlrev_b32_e32 v230, 16, v51
	v_and_b32_e32 v231, 0xffff0000, v51
	v_mul_f32_e32 v230, v230, v218
	v_mul_f32_e32 v231, v231, v219
	v_cvt_pk_bf16_f32 v51, v230, v231
	global_store_dwordx4 v195, v[48:51], s[30:31]
	v_mul_f32_e32 v218, v210, v160
	v_mul_f32_e32 v219, v210, v161
	v_lshlrev_b32_e32 v230, 16, v52
	v_and_b32_e32 v231, 0xffff0000, v52
	v_mul_f32_e32 v230, v230, v218
	v_mul_f32_e32 v231, v231, v219
	v_cvt_pk_bf16_f32 v52, v230, v231
	v_mul_f32_e32 v218, v210, v162
	v_mul_f32_e32 v219, v210, v163
	v_lshlrev_b32_e32 v230, 16, v53
	v_and_b32_e32 v231, 0xffff0000, v53
	v_mul_f32_e32 v230, v230, v218
	v_mul_f32_e32 v231, v231, v219
	v_cvt_pk_bf16_f32 v53, v230, v231
	v_mul_f32_e32 v218, v210, v164
	v_mul_f32_e32 v219, v210, v165
	v_lshlrev_b32_e32 v230, 16, v54
	v_and_b32_e32 v231, 0xffff0000, v54
	v_mul_f32_e32 v230, v230, v218
	v_mul_f32_e32 v231, v231, v219
	v_cvt_pk_bf16_f32 v54, v230, v231
	v_mul_f32_e32 v218, v210, v166
	v_mul_f32_e32 v219, v210, v167
	v_lshlrev_b32_e32 v230, 16, v55
	v_and_b32_e32 v231, 0xffff0000, v55
	v_mul_f32_e32 v230, v230, v218
	v_mul_f32_e32 v231, v231, v219
	v_cvt_pk_bf16_f32 v55, v230, v231
	global_store_dwordx4 v195, v[52:55], s[30:31] offset:2048
	s_add_u32 s36, s26, 0x1c00000
	s_addc_u32 s37, s27, 0
	s_add_u32 s30, s36, 0x1000
	s_addc_u32 s31, s37, 0
	v_mul_f32_e32 v218, v212, v160
	v_mul_f32_e32 v219, v212, v161
	v_lshlrev_b32_e32 v230, 16, v60
	v_and_b32_e32 v231, 0xffff0000, v60
	v_mul_f32_e32 v230, v230, v218
	v_mul_f32_e32 v231, v231, v219
	v_cvt_pk_bf16_f32 v60, v230, v231
	v_mul_f32_e32 v218, v212, v162
	v_mul_f32_e32 v219, v212, v163
	v_lshlrev_b32_e32 v230, 16, v61
	v_and_b32_e32 v231, 0xffff0000, v61
	v_mul_f32_e32 v230, v230, v218
	v_mul_f32_e32 v231, v231, v219
	v_cvt_pk_bf16_f32 v61, v230, v231
	v_mul_f32_e32 v218, v212, v164
	v_mul_f32_e32 v219, v212, v165
	v_lshlrev_b32_e32 v230, 16, v62
	v_and_b32_e32 v231, 0xffff0000, v62
	v_mul_f32_e32 v230, v230, v218
	v_mul_f32_e32 v231, v231, v219
	v_cvt_pk_bf16_f32 v62, v230, v231
	v_mul_f32_e32 v218, v212, v166
	v_mul_f32_e32 v219, v212, v167
	v_lshlrev_b32_e32 v230, 16, v63
	v_and_b32_e32 v231, 0xffff0000, v63
	v_mul_f32_e32 v230, v230, v218
	v_mul_f32_e32 v231, v231, v219
	v_cvt_pk_bf16_f32 v63, v230, v231
	global_store_dwordx4 v195, v[60:63], s[36:37]
	v_mul_f32_e32 v218, v213, v160
	v_mul_f32_e32 v219, v213, v161
	v_lshlrev_b32_e32 v230, 16, v64
	v_and_b32_e32 v231, 0xffff0000, v64
	v_mul_f32_e32 v230, v230, v218
	v_mul_f32_e32 v231, v231, v219
	v_cvt_pk_bf16_f32 v64, v230, v231
	v_mul_f32_e32 v218, v213, v162
	v_mul_f32_e32 v219, v213, v163
	v_lshlrev_b32_e32 v230, 16, v65
	v_and_b32_e32 v231, 0xffff0000, v65
	v_mul_f32_e32 v230, v230, v218
	v_mul_f32_e32 v231, v231, v219
	v_cvt_pk_bf16_f32 v65, v230, v231
	v_mul_f32_e32 v218, v213, v164
	v_mul_f32_e32 v219, v213, v165
	v_lshlrev_b32_e32 v230, 16, v66
	v_and_b32_e32 v231, 0xffff0000, v66
	v_mul_f32_e32 v230, v230, v218
	v_mul_f32_e32 v231, v231, v219
	v_cvt_pk_bf16_f32 v66, v230, v231
	v_mul_f32_e32 v218, v213, v166
	v_mul_f32_e32 v219, v213, v167
	v_lshlrev_b32_e32 v230, 16, v67
	v_and_b32_e32 v231, 0xffff0000, v67
	v_mul_f32_e32 v230, v230, v218
	v_mul_f32_e32 v231, v231, v219
	v_cvt_pk_bf16_f32 v67, v230, v231
	global_store_dwordx4 v195, v[64:67], s[36:37] offset:2048
	v_mul_f32_e32 v218, v214, v160
	v_mul_f32_e32 v219, v214, v161
	v_lshlrev_b32_e32 v230, 16, v68
	v_and_b32_e32 v231, 0xffff0000, v68
	v_mul_f32_e32 v230, v230, v218
	v_mul_f32_e32 v231, v231, v219
	v_cvt_pk_bf16_f32 v68, v230, v231
	v_mul_f32_e32 v218, v214, v162
	v_mul_f32_e32 v219, v214, v163
	v_lshlrev_b32_e32 v230, 16, v69
	v_and_b32_e32 v231, 0xffff0000, v69
	v_mul_f32_e32 v230, v230, v218
	v_mul_f32_e32 v231, v231, v219
	v_cvt_pk_bf16_f32 v69, v230, v231
	v_mul_f32_e32 v218, v214, v164
	v_mul_f32_e32 v219, v214, v165
	v_lshlrev_b32_e32 v230, 16, v70
	v_and_b32_e32 v231, 0xffff0000, v70
	v_mul_f32_e32 v230, v230, v218
	v_mul_f32_e32 v231, v231, v219
	v_cvt_pk_bf16_f32 v70, v230, v231
	v_mul_f32_e32 v218, v214, v166
	v_mul_f32_e32 v219, v214, v167
	v_lshlrev_b32_e32 v230, 16, v71
	v_and_b32_e32 v231, 0xffff0000, v71
	v_mul_f32_e32 v230, v230, v218
	v_mul_f32_e32 v231, v231, v219
	v_cvt_pk_bf16_f32 v71, v230, v231
	global_store_dwordx4 v195, v[68:71], s[30:31]
	v_mul_f32_e32 v218, v215, v160
	v_mul_f32_e32 v219, v215, v161
	v_lshlrev_b32_e32 v230, 16, v72
	v_and_b32_e32 v231, 0xffff0000, v72
	v_mul_f32_e32 v230, v230, v218
	v_mul_f32_e32 v231, v231, v219
	v_cvt_pk_bf16_f32 v72, v230, v231
	v_mul_f32_e32 v218, v215, v162
	v_mul_f32_e32 v219, v215, v163
	v_lshlrev_b32_e32 v230, 16, v73
	v_and_b32_e32 v231, 0xffff0000, v73
	v_mul_f32_e32 v230, v230, v218
	v_mul_f32_e32 v231, v231, v219
	v_cvt_pk_bf16_f32 v73, v230, v231
	v_mul_f32_e32 v218, v215, v164
	v_mul_f32_e32 v219, v215, v165
	v_lshlrev_b32_e32 v230, 16, v74
	v_and_b32_e32 v231, 0xffff0000, v74
	v_mul_f32_e32 v230, v230, v218
	v_mul_f32_e32 v231, v231, v219
	v_cvt_pk_bf16_f32 v74, v230, v231
	v_mul_f32_e32 v218, v215, v166
	v_mul_f32_e32 v219, v215, v167
	v_lshlrev_b32_e32 v230, 16, v75
	v_and_b32_e32 v231, 0xffff0000, v75
	v_mul_f32_e32 v230, v230, v218
	v_mul_f32_e32 v231, v231, v219
	v_cvt_pk_bf16_f32 v75, v230, v231
	global_store_dwordx4 v195, v[72:75], s[30:31] offset:2048
	v_lshlrev_b32_e32 v232, 16, v56
	v_and_b32_e32 v233, 0xffff0000, v56
	v_lshlrev_b32_e32 v234, 16, v57
	v_and_b32_e32 v235, 0xffff0000, v57
	v_lshlrev_b32_e32 v236, 16, v58
	v_and_b32_e32 v237, 0xffff0000, v58
	v_lshlrev_b32_e32 v238, 16, v59
	v_and_b32_e32 v239, 0xffff0000, v59
	v_mul_f32_e32 v232, v232, v211
	v_mul_f32_e32 v233, v233, v211
	v_mul_f32_e32 v234, v234, v211
	v_mul_f32_e32 v235, v235, v211
	v_mul_f32_e32 v236, v236, v211
	v_mul_f32_e32 v237, v237, v211
	v_mul_f32_e32 v238, v238, v211
	v_mul_f32_e32 v239, v239, v211
	v_mul_f32_e32 v232, v232, v168
	v_mul_f32_e32 v233, v233, v169
	v_mul_f32_e32 v234, v234, v170
	v_mul_f32_e32 v235, v235, v171
	v_mul_f32_e32 v236, v236, v172
	v_mul_f32_e32 v237, v237, v173
	v_mul_f32_e32 v238, v238, v174
	v_mul_f32_e32 v239, v239, v175
	ds_bpermute_b32 v240, v193, v232
	ds_bpermute_b32 v241, v193, v233
	ds_bpermute_b32 v242, v193, v234
	ds_bpermute_b32 v243, v193, v235
	ds_bpermute_b32 v244, v193, v236
	ds_bpermute_b32 v245, v193, v237
	ds_bpermute_b32 v246, v193, v238
	ds_bpermute_b32 v247, v193, v239
	s_and_b32 s35, s34, 0xfff
	v_cvt_f32_u32_e32 v218, s35
	v_mul_f32_e32 v218, 0x3e22f983, v218
	s_waitcnt lgkmcnt(0)
; DI u32x4 pack8(const float (&f)[8]) { u32x4 w; w.x = pk2(f[0], f[1]); w.y = pk2(f[2], f[3]); w.z = pk2(f[4], f[5]); w.w = pk2(f[6], f[7]); return w; }
; DI void phase_mla_qk(const Params& p) {
;     ...
;               for (int e = 0; e < 8; ++e) {
;                   const float a = f[e] * sc * gkr[e], pa = __shfl_xor(a, 4);
;                   float sn, cs; sincosf(pos * inv[e], &sn, &cs);
;                   o[e] = (l8 < 4) ? a * cs - pa * sn : a * cs + pa * sn;
;               }
;               if (ok[r] && lane < 8) *(u32x4*)kpp = pack8(o); }
	v_mul_f32_e32 v220, v218, v182
	v_fract_f32_e32 v220, v220
	v_sin_f32_e32 v221, v220
	v_cos_f32_e32 v222, v220
	v_mul_f32_e32 v240, v240, v190
	v_mul_f32_e32 v240, v240, v221
	v_fma_f32 v232, v232, v222, v240
	v_mul_f32_e32 v223, v218, v183
	v_fract_f32_e32 v223, v223
	v_sin_f32_e32 v224, v223
	v_cos_f32_e32 v225, v223
	v_mul_f32_e32 v241, v241, v190
	v_mul_f32_e32 v241, v241, v224
	v_fma_f32 v233, v233, v225, v241
	v_mul_f32_e32 v220, v218, v184
	v_fract_f32_e32 v220, v220
	v_sin_f32_e32 v221, v220
	v_cos_f32_e32 v222, v220
	v_mul_f32_e32 v242, v242, v190
	v_mul_f32_e32 v242, v242, v221
	v_fma_f32 v234, v234, v222, v242
	v_mul_f32_e32 v223, v218, v185
	v_fract_f32_e32 v223, v223
	v_sin_f32_e32 v224, v223
	v_cos_f32_e32 v225, v223
	v_mul_f32_e32 v243, v243, v190
	v_mul_f32_e32 v243, v243, v224
	v_fma_f32 v235, v235, v225, v243
	v_mul_f32_e32 v220, v218, v186
	v_fract_f32_e32 v220, v220
	v_sin_f32_e32 v221, v220
	v_cos_f32_e32 v222, v220
	v_mul_f32_e32 v244, v244, v190
	v_mul_f32_e32 v244, v244, v221
	v_fma_f32 v236, v236, v222, v244
	v_mul_f32_e32 v223, v218, v187
	v_fract_f32_e32 v223, v223
	v_sin_f32_e32 v224, v223
	v_cos_f32_e32 v225, v223
	v_mul_f32_e32 v245, v245, v190
	v_mul_f32_e32 v245, v245, v224
	v_fma_f32 v237, v237, v225, v245
	v_mul_f32_e32 v220, v218, v188
	v_fract_f32_e32 v220, v220
	v_sin_f32_e32 v221, v220
	v_cos_f32_e32 v222, v220
	v_mul_f32_e32 v246, v246, v190
	v_mul_f32_e32 v246, v246, v221
	v_fma_f32 v238, v238, v222, v246
	v_mul_f32_e32 v223, v218, v189
	v_fract_f32_e32 v223, v223
	v_sin_f32_e32 v224, v223
	v_cos_f32_e32 v225, v223
	v_mul_f32_e32 v247, v247, v190
	v_mul_f32_e32 v247, v247, v224
	v_fma_f32 v239, v239, v225, v247
	v_cvt_pk_bf16_f32 v56, v232, v233
	v_cvt_pk_bf16_f32 v57, v234, v235
	v_cvt_pk_bf16_f32 v58, v236, v237
	v_cvt_pk_bf16_f32 v59, v238, v239
	s_mov_b64 exec, 0xff
	global_store_dwordx4 v196, v[56:59], s[28:29]
	s_mov_b64 exec, -1
	v_lshlrev_b32_e32 v232, 16, v76
	v_and_b32_e32 v233, 0xffff0000, v76
	v_lshlrev_b32_e32 v234, 16, v77
	v_and_b32_e32 v235, 0xffff0000, v77
	v_lshlrev_b32_e32 v236, 16, v78
	v_and_b32_e32 v237, 0xffff0000, v78
	v_lshlrev_b32_e32 v238, 16, v79
	v_and_b32_e32 v239, 0xffff0000, v79
	v_mul_f32_e32 v232, v232, v216
	v_mul_f32_e32 v233, v233, v216
	v_mul_f32_e32 v234, v234, v216
	v_mul_f32_e32 v235, v235, v216
	v_mul_f32_e32 v236, v236, v216
	v_mul_f32_e32 v237, v237, v216
	v_mul_f32_e32 v238, v238, v216
	v_mul_f32_e32 v239, v239, v216
	v_mul_f32_e32 v232, v232, v168
	v_mul_f32_e32 v233, v233, v169
	v_mul_f32_e32 v234, v234, v170
	v_mul_f32_e32 v235, v235, v171
	v_mul_f32_e32 v236, v236, v172
	v_mul_f32_e32 v237, v237, v173
	v_mul_f32_e32 v238, v238, v174
	v_mul_f32_e32 v239, v239, v175
	ds_bpermute_b32 v240, v193, v232
	ds_bpermute_b32 v241, v193, v233
	ds_bpermute_b32 v242, v193, v234
	ds_bpermute_b32 v243, v193, v235
	ds_bpermute_b32 v244, v193, v236
	ds_bpermute_b32 v245, v193, v237
	ds_bpermute_b32 v246, v193, v238
	ds_bpermute_b32 v247, v193, v239
	s_add_i32 s35, s34, 0x800
	s_and_b32 s35, s35, 0xfff
	v_cvt_f32_u32_e32 v218, s35
	v_mul_f32_e32 v218, 0x3e22f983, v218
	s_waitcnt lgkmcnt(0)
	v_mul_f32_e32 v220, v218, v182
	v_fract_f32_e32 v220, v220
	v_sin_f32_e32 v221, v220
	v_cos_f32_e32 v222, v220
	v_mul_f32_e32 v240, v240, v190
	v_mul_f32_e32 v240, v240, v221
	v_fma_f32 v232, v232, v222, v240
	v_mul_f32_e32 v223, v218, v183
	v_fract_f32_e32 v223, v223
	v_sin_f32_e32 v224, v223
	v_cos_f32_e32 v225, v223
	v_mul_f32_e32 v241, v241, v190
	v_mul_f32_e32 v241, v241, v224
	v_fma_f32 v233, v233, v225, v241
	v_mul_f32_e32 v220, v218, v184
	v_fract_f32_e32 v220, v220
	v_sin_f32_e32 v221, v220
	v_cos_f32_e32 v222, v220
	v_mul_f32_e32 v242, v242, v190
	v_mul_f32_e32 v242, v242, v221
	v_fma_f32 v234, v234, v222, v242
	v_mul_f32_e32 v223, v218, v185
	v_fract_f32_e32 v223, v223
	v_sin_f32_e32 v224, v223
	v_cos_f32_e32 v225, v223
	v_mul_f32_e32 v243, v243, v190
	v_mul_f32_e32 v243, v243, v224
	v_fma_f32 v235, v235, v225, v243
	v_mul_f32_e32 v220, v218, v186
	v_fract_f32_e32 v220, v220
	v_sin_f32_e32 v221, v220
	v_cos_f32_e32 v222, v220
	v_mul_f32_e32 v244, v244, v190
	v_mul_f32_e32 v244, v244, v221
	v_fma_f32 v236, v236, v222, v244
	v_mul_f32_e32 v223, v218, v187
	v_fract_f32_e32 v223, v223
	v_sin_f32_e32 v224, v223
	v_cos_f32_e32 v225, v223
	v_mul_f32_e32 v245, v245, v190
	v_mul_f32_e32 v245, v245, v224
	v_fma_f32 v237, v237, v225, v245
	v_mul_f32_e32 v220, v218, v188
	v_fract_f32_e32 v220, v220
	v_sin_f32_e32 v221, v220
	v_cos_f32_e32 v222, v220
	v_mul_f32_e32 v246, v246, v190
	v_mul_f32_e32 v246, v246, v221
	v_fma_f32 v238, v238, v222, v246
	v_mul_f32_e32 v223, v218, v189
	v_fract_f32_e32 v223, v223
	v_sin_f32_e32 v224, v223
	v_cos_f32_e32 v225, v223
	v_mul_f32_e32 v247, v247, v190
	v_mul_f32_e32 v247, v247, v224
	v_fma_f32 v239, v239, v225, v247
	v_cvt_pk_bf16_f32 v76, v232, v233
	v_cvt_pk_bf16_f32 v77, v234, v235
	v_cvt_pk_bf16_f32 v78, v236, v237
	v_cvt_pk_bf16_f32 v79, v238, v239
	s_add_u32 s36, s28, 0x440000
	s_addc_u32 s37, s29, 0
	s_mov_b64 exec, 0xff
	global_store_dwordx4 v196, v[76:79], s[36:37]
	s_mov_b64 exec, -1
	s_add_u32 s26, s26, 0x3800000
	s_addc_u32 s27, s27, 0
	s_add_u32 s28, s28, 0x880000
	s_addc_u32 s29, s29, 0
	s_addk_i32 s34, 0x1000
	s_waitcnt vmcnt(30)
; DI void phase_mla_qk(const Params& p) {
;     ...
;                 float f[8]; unpack8(wk[r][i], f); float ss = 0.f;
; #pragma unroll
;                 for (int e = 0; e < 8; ++e) ss += f[e] * f[e];
;                 ss += __shfl_xor(ss, 1); ss += __shfl_xor(ss, 2); ss += __shfl_xor(ss, 4); ss += __shfl_xor(ss, 8);
;     ...
;             { float f[8], o[8]; unpack8(wp[r], f); float ss = 0.f;
; #pragma unroll
;               for (int e = 0; e < 8; ++e) ss += f[e] * f[e];
;               ss += __shfl_xor(ss, 1); ss += __shfl_xor(ss, 2); ss += __shfl_xor(ss, 4);
	v_lshlrev_b32_e32 v218, 16, v80
	v_and_b32_e32 v219, 0xffff0000, v80
	v_mul_f32_e32 v207, v218, v218
	v_fmac_f32_e32 v207, v219, v219
	v_lshlrev_b32_e32 v218, 16, v81
	v_and_b32_e32 v219, 0xffff0000, v81
	v_fmac_f32_e32 v207, v218, v218
	v_fmac_f32_e32 v207, v219, v219
	v_lshlrev_b32_e32 v218, 16, v82
	v_and_b32_e32 v219, 0xffff0000, v82
	v_fmac_f32_e32 v207, v218, v218
	v_fmac_f32_e32 v207, v219, v219
	v_lshlrev_b32_e32 v218, 16, v83
	v_and_b32_e32 v219, 0xffff0000, v83
	v_fmac_f32_e32 v207, v218, v218
	v_fmac_f32_e32 v207, v219, v219
	v_lshlrev_b32_e32 v218, 16, v84
	v_and_b32_e32 v219, 0xffff0000, v84
	v_mul_f32_e32 v208, v218, v218
	v_fmac_f32_e32 v208, v219, v219
	v_lshlrev_b32_e32 v218, 16, v85
	v_and_b32_e32 v219, 0xffff0000, v85
	v_fmac_f32_e32 v208, v218, v218
	v_fmac_f32_e32 v208, v219, v219
	v_lshlrev_b32_e32 v218, 16, v86
	v_and_b32_e32 v219, 0xffff0000, v86
	v_fmac_f32_e32 v208, v218, v218
	v_fmac_f32_e32 v208, v219, v219
	v_lshlrev_b32_e32 v218, 16, v87
	v_and_b32_e32 v219, 0xffff0000, v87
	v_fmac_f32_e32 v208, v218, v218
	v_fmac_f32_e32 v208, v219, v219
	v_lshlrev_b32_e32 v218, 16, v88
	v_and_b32_e32 v219, 0xffff0000, v88
	v_mul_f32_e32 v209, v218, v218
	v_fmac_f32_e32 v209, v219, v219
	v_lshlrev_b32_e32 v218, 16, v89
	v_and_b32_e32 v219, 0xffff0000, v89
	v_fmac_f32_e32 v209, v218, v218
	v_fmac_f32_e32 v209, v219, v219
	v_lshlrev_b32_e32 v218, 16, v90
	v_and_b32_e32 v219, 0xffff0000, v90
	v_fmac_f32_e32 v209, v218, v218
	v_fmac_f32_e32 v209, v219, v219
	v_lshlrev_b32_e32 v218, 16, v91
	v_and_b32_e32 v219, 0xffff0000, v91
	v_fmac_f32_e32 v209, v218, v218
	v_fmac_f32_e32 v209, v219, v219
	v_lshlrev_b32_e32 v218, 16, v92
	v_and_b32_e32 v219, 0xffff0000, v92
	v_mul_f32_e32 v210, v218, v218
	v_fmac_f32_e32 v210, v219, v219
	v_lshlrev_b32_e32 v218, 16, v93
	v_and_b32_e32 v219, 0xffff0000, v93
	v_fmac_f32_e32 v210, v218, v218
	v_fmac_f32_e32 v210, v219, v219
	v_lshlrev_b32_e32 v218, 16, v94
	v_and_b32_e32 v219, 0xffff0000, v94
	v_fmac_f32_e32 v210, v218, v218
	v_fmac_f32_e32 v210, v219, v219
	v_lshlrev_b32_e32 v218, 16, v95
	v_and_b32_e32 v219, 0xffff0000, v95
	v_fmac_f32_e32 v210, v218, v218
	v_fmac_f32_e32 v210, v219, v219
	v_lshlrev_b32_e32 v218, 16, v96
	v_and_b32_e32 v219, 0xffff0000, v96
	v_mul_f32_e32 v211, v218, v218
	v_fmac_f32_e32 v211, v219, v219
	v_lshlrev_b32_e32 v218, 16, v97
	v_and_b32_e32 v219, 0xffff0000, v97
	v_fmac_f32_e32 v211, v218, v218
	v_fmac_f32_e32 v211, v219, v219
	v_lshlrev_b32_e32 v218, 16, v98
	v_and_b32_e32 v219, 0xffff0000, v98
	v_fmac_f32_e32 v211, v218, v218
	v_fmac_f32_e32 v211, v219, v219
	v_lshlrev_b32_e32 v218, 16, v99
	v_and_b32_e32 v219, 0xffff0000, v99
	v_fmac_f32_e32 v211, v218, v218
	v_fmac_f32_e32 v211, v219, v219
	v_lshlrev_b32_e32 v218, 16, v100
	v_and_b32_e32 v219, 0xffff0000, v100
	v_mul_f32_e32 v212, v218, v218
	v_fmac_f32_e32 v212, v219, v219
	v_lshlrev_b32_e32 v218, 16, v101
	v_and_b32_e32 v219, 0xffff0000, v101
	v_fmac_f32_e32 v212, v218, v218
	v_fmac_f32_e32 v212, v219, v219
	v_lshlrev_b32_e32 v218, 16, v102
	v_and_b32_e32 v219, 0xffff0000, v102
	v_fmac_f32_e32 v212, v218, v218
	v_fmac_f32_e32 v212, v219, v219
	v_lshlrev_b32_e32 v218, 16, v103
	v_and_b32_e32 v219, 0xffff0000, v103
	v_fmac_f32_e32 v212, v218, v218
	v_fmac_f32_e32 v212, v219, v219
	v_lshlrev_b32_e32 v218, 16, v104
	v_and_b32_e32 v219, 0xffff0000, v104
	v_mul_f32_e32 v213, v218, v218
	v_fmac_f32_e32 v213, v219, v219
	v_lshlrev_b32_e32 v218, 16, v105
	v_and_b32_e32 v219, 0xffff0000, v105
	v_fmac_f32_e32 v213, v218, v218
	v_fmac_f32_e32 v213, v219, v219
	v_lshlrev_b32_e32 v218, 16, v106
	v_and_b32_e32 v219, 0xffff0000, v106
	v_fmac_f32_e32 v213, v218, v218
	v_fmac_f32_e32 v213, v219, v219
	v_lshlrev_b32_e32 v218, 16, v107
	v_and_b32_e32 v219, 0xffff0000, v107
	v_fmac_f32_e32 v213, v218, v218
	v_fmac_f32_e32 v213, v219, v219
	v_lshlrev_b32_e32 v218, 16, v108
	v_and_b32_e32 v219, 0xffff0000, v108
	v_mul_f32_e32 v214, v218, v218
	v_fmac_f32_e32 v214, v219, v219
	v_lshlrev_b32_e32 v218, 16, v109
	v_and_b32_e32 v219, 0xffff0000, v109
	v_fmac_f32_e32 v214, v218, v218
	v_fmac_f32_e32 v214, v219, v219
	v_lshlrev_b32_e32 v218, 16, v110
	v_and_b32_e32 v219, 0xffff0000, v110
	v_fmac_f32_e32 v214, v218, v218
	v_fmac_f32_e32 v214, v219, v219
	v_lshlrev_b32_e32 v218, 16, v111
	v_and_b32_e32 v219, 0xffff0000, v111
	v_fmac_f32_e32 v214, v218, v218
	v_fmac_f32_e32 v214, v219, v219
	v_lshlrev_b32_e32 v218, 16, v112
	v_and_b32_e32 v219, 0xffff0000, v112
	v_mul_f32_e32 v215, v218, v218
	v_fmac_f32_e32 v215, v219, v219
	v_lshlrev_b32_e32 v218, 16, v113
	v_and_b32_e32 v219, 0xffff0000, v113
	v_fmac_f32_e32 v215, v218, v218
	v_fmac_f32_e32 v215, v219, v219
	v_lshlrev_b32_e32 v218, 16, v114
	v_and_b32_e32 v219, 0xffff0000, v114
	v_fmac_f32_e32 v215, v218, v218
	v_fmac_f32_e32 v215, v219, v219
	v_lshlrev_b32_e32 v218, 16, v115
	v_and_b32_e32 v219, 0xffff0000, v115
	v_fmac_f32_e32 v215, v218, v218
	v_fmac_f32_e32 v215, v219, v219
	v_lshlrev_b32_e32 v218, 16, v116
	v_and_b32_e32 v219, 0xffff0000, v116
	v_mul_f32_e32 v216, v218, v218
	v_fmac_f32_e32 v216, v219, v219
	v_lshlrev_b32_e32 v218, 16, v117
	v_and_b32_e32 v219, 0xffff0000, v117
	v_fmac_f32_e32 v216, v218, v218
	v_fmac_f32_e32 v216, v219, v219
	v_lshlrev_b32_e32 v218, 16, v118
	v_and_b32_e32 v219, 0xffff0000, v118
	v_fmac_f32_e32 v216, v218, v218
	v_fmac_f32_e32 v216, v219, v219
	v_lshlrev_b32_e32 v218, 16, v119
	v_and_b32_e32 v219, 0xffff0000, v119
	v_fmac_f32_e32 v216, v218, v218
	v_fmac_f32_e32 v216, v219, v219
	ds_bpermute_b32 v220, v191, v207
	ds_bpermute_b32 v221, v191, v208
	ds_bpermute_b32 v222, v191, v209
	ds_bpermute_b32 v223, v191, v210
	ds_bpermute_b32 v224, v191, v211
	ds_bpermute_b32 v225, v191, v212
	ds_bpermute_b32 v226, v191, v213
	ds_bpermute_b32 v227, v191, v214
	ds_bpermute_b32 v228, v191, v215
	ds_bpermute_b32 v229, v191, v216
	s_waitcnt lgkmcnt(0)
; DI u32x4 pack8(const float (&f)[8]) { u32x4 w; w.x = pk2(f[0], f[1]); w.y = pk2(f[2], f[3]); w.z = pk2(f[4], f[5]); w.w = pk2(f[6], f[7]); return w; }
; DI void phase_mla_qk(const Params& p) {
;     ...
;                 ss += __shfl_xor(ss, 1); ss += __shfl_xor(ss, 2); ss += __shfl_xor(ss, 4); ss += __shfl_xor(ss, 8);
;                 const float sc = rsqrtf(ss * (1.f / 128.f) + EPS);
; #pragma unroll
;                 for (int e = 0; e < 8; ++e) f[e] *= sc * gk[e];
;                 if (ok[r]) *(u32x4*)(qr + 3072 + head * 256 + l16 * 8) = pack8(f);
	v_add_f32_e32 v207, v207, v220
	v_add_f32_e32 v208, v208, v221
	v_add_f32_e32 v209, v209, v222
	v_add_f32_e32 v210, v210, v223
	v_add_f32_e32 v211, v211, v224
	v_add_f32_e32 v212, v212, v225
	v_add_f32_e32 v213, v213, v226
	v_add_f32_e32 v214, v214, v227
	v_add_f32_e32 v215, v215, v228
	v_add_f32_e32 v216, v216, v229
	ds_bpermute_b32 v220, v192, v207
	ds_bpermute_b32 v221, v192, v208
	ds_bpermute_b32 v222, v192, v209
	ds_bpermute_b32 v223, v192, v210
	ds_bpermute_b32 v224, v192, v211
	ds_bpermute_b32 v225, v192, v212
	ds_bpermute_b32 v226, v192, v213
	ds_bpermute_b32 v227, v192, v214
	ds_bpermute_b32 v228, v192, v215
	ds_bpermute_b32 v229, v192, v216
	s_waitcnt lgkmcnt(0)
	v_add_f32_e32 v207, v207, v220
	v_add_f32_e32 v208, v208, v221
	v_add_f32_e32 v209, v209, v222
	v_add_f32_e32 v210, v210, v223
	v_add_f32_e32 v211, v211, v224
	v_add_f32_e32 v212, v212, v225
	v_add_f32_e32 v213, v213, v226
	v_add_f32_e32 v214, v214, v227
	v_add_f32_e32 v215, v215, v228
	v_add_f32_e32 v216, v216, v229
	ds_bpermute_b32 v220, v193, v207
	ds_bpermute_b32 v221, v193, v208
	ds_bpermute_b32 v222, v193, v209
	ds_bpermute_b32 v223, v193, v210
	ds_bpermute_b32 v224, v193, v211
	ds_bpermute_b32 v225, v193, v212
	ds_bpermute_b32 v226, v193, v213
	ds_bpermute_b32 v227, v193, v214
	ds_bpermute_b32 v228, v193, v215
	ds_bpermute_b32 v229, v193, v216
	s_waitcnt lgkmcnt(0)
	v_add_f32_e32 v207, v207, v220
	v_add_f32_e32 v208, v208, v221
	v_add_f32_e32 v209, v209, v222
	v_add_f32_e32 v210, v210, v223
	v_add_f32_e32 v211, v211, v224
	v_add_f32_e32 v212, v212, v225
	v_add_f32_e32 v213, v213, v226
	v_add_f32_e32 v214, v214, v227
	v_add_f32_e32 v215, v215, v228
	v_add_f32_e32 v216, v216, v229
	ds_bpermute_b32 v220, v194, v207
	ds_bpermute_b32 v221, v194, v208
	ds_bpermute_b32 v222, v194, v209
	ds_bpermute_b32 v223, v194, v210
	ds_bpermute_b32 v225, v194, v212
	ds_bpermute_b32 v226, v194, v213
	ds_bpermute_b32 v227, v194, v214
	ds_bpermute_b32 v228, v194, v215
	s_waitcnt lgkmcnt(0)
	v_add_f32_e32 v207, v207, v220
	v_add_f32_e32 v208, v208, v221
	v_add_f32_e32 v209, v209, v222
	v_add_f32_e32 v210, v210, v223
	v_add_f32_e32 v212, v212, v225
	v_add_f32_e32 v213, v213, v226
	v_add_f32_e32 v214, v214, v227
	v_add_f32_e32 v215, v215, v228
	v_mul_f32_e32 v207, 0x3c000000, v207
	v_add_f32_e32 v207, 0x358637bd, v207
	v_mul_f32_e32 v208, 0x3c000000, v208
	v_add_f32_e32 v208, 0x358637bd, v208
	v_mul_f32_e32 v209, 0x3c000000, v209
	v_add_f32_e32 v209, 0x358637bd, v209
	v_mul_f32_e32 v210, 0x3c000000, v210
	v_add_f32_e32 v210, 0x358637bd, v210
	v_mul_f32_e32 v211, 0x3c800000, v211
	v_add_f32_e32 v211, 0x358637bd, v211
	v_mul_f32_e32 v212, 0x3c000000, v212
	v_add_f32_e32 v212, 0x358637bd, v212
	v_mul_f32_e32 v213, 0x3c000000, v213
	v_add_f32_e32 v213, 0x358637bd, v213
	v_mul_f32_e32 v214, 0x3c000000, v214
	v_add_f32_e32 v214, 0x358637bd, v214
	v_mul_f32_e32 v215, 0x3c000000, v215
	v_add_f32_e32 v215, 0x358637bd, v215
	v_mul_f32_e32 v216, 0x3c800000, v216
	v_add_f32_e32 v216, 0x358637bd, v216
	v_rsq_f32_e32 v207, v207
	v_rsq_f32_e32 v208, v208
	v_rsq_f32_e32 v209, v209
	v_rsq_f32_e32 v210, v210
	v_rsq_f32_e32 v211, v211
	v_rsq_f32_e32 v212, v212
	v_rsq_f32_e32 v213, v213
	v_rsq_f32_e32 v214, v214
	v_rsq_f32_e32 v215, v215
	v_rsq_f32_e32 v216, v216
	s_nop 1
	s_add_u32 s30, s26, 0x1000
	s_addc_u32 s31, s27, 0
	v_mul_f32_e32 v218, v207, v160
	v_mul_f32_e32 v219, v207, v161
	v_lshlrev_b32_e32 v230, 16, v80
	v_and_b32_e32 v231, 0xffff0000, v80
	v_mul_f32_e32 v230, v230, v218
	v_mul_f32_e32 v231, v231, v219
	v_cvt_pk_bf16_f32 v80, v230, v231
	v_mul_f32_e32 v218, v207, v162
	v_mul_f32_e32 v219, v207, v163
	v_lshlrev_b32_e32 v230, 16, v81
	v_and_b32_e32 v231, 0xffff0000, v81
	v_mul_f32_e32 v230, v230, v218
	v_mul_f32_e32 v231, v231, v219
	v_cvt_pk_bf16_f32 v81, v230, v231
	v_mul_f32_e32 v218, v207, v164
	v_mul_f32_e32 v219, v207, v165
	v_lshlrev_b32_e32 v230, 16, v82
	v_and_b32_e32 v231, 0xffff0000, v82
	v_mul_f32_e32 v230, v230, v218
	v_mul_f32_e32 v231, v231, v219
	v_cvt_pk_bf16_f32 v82, v230, v231
	v_mul_f32_e32 v218, v207, v166
	v_mul_f32_e32 v219, v207, v167
	v_lshlrev_b32_e32 v230, 16, v83
	v_and_b32_e32 v231, 0xffff0000, v83
	v_mul_f32_e32 v230, v230, v218
	v_mul_f32_e32 v231, v231, v219
	v_cvt_pk_bf16_f32 v83, v230, v231
	global_store_dwordx4 v195, v[80:83], s[26:27]
	v_mul_f32_e32 v218, v208, v160
	v_mul_f32_e32 v219, v208, v161
	v_lshlrev_b32_e32 v230, 16, v84
	v_and_b32_e32 v231, 0xffff0000, v84
	v_mul_f32_e32 v230, v230, v218
	v_mul_f32_e32 v231, v231, v219
	v_cvt_pk_bf16_f32 v84, v230, v231
	v_mul_f32_e32 v218, v208, v162
	v_mul_f32_e32 v219, v208, v163
	v_lshlrev_b32_e32 v230, 16, v85
	v_and_b32_e32 v231, 0xffff0000, v85
	v_mul_f32_e32 v230, v230, v218
	v_mul_f32_e32 v231, v231, v219
	v_cvt_pk_bf16_f32 v85, v230, v231
	v_mul_f32_e32 v218, v208, v164
	v_mul_f32_e32 v219, v208, v165
	v_lshlrev_b32_e32 v230, 16, v86
	v_and_b32_e32 v231, 0xffff0000, v86
	v_mul_f32_e32 v230, v230, v218
	v_mul_f32_e32 v231, v231, v219
	v_cvt_pk_bf16_f32 v86, v230, v231
	v_mul_f32_e32 v218, v208, v166
	v_mul_f32_e32 v219, v208, v167
	v_lshlrev_b32_e32 v230, 16, v87
	v_and_b32_e32 v231, 0xffff0000, v87
	v_mul_f32_e32 v230, v230, v218
	v_mul_f32_e32 v231, v231, v219
	v_cvt_pk_bf16_f32 v87, v230, v231
	global_store_dwordx4 v195, v[84:87], s[26:27] offset:2048
	v_mul_f32_e32 v218, v209, v160
	v_mul_f32_e32 v219, v209, v161
	v_lshlrev_b32_e32 v230, 16, v88
	v_and_b32_e32 v231, 0xffff0000, v88
	v_mul_f32_e32 v230, v230, v218
	v_mul_f32_e32 v231, v231, v219
	v_cvt_pk_bf16_f32 v88, v230, v231
	v_mul_f32_e32 v218, v209, v162
	v_mul_f32_e32 v219, v209, v163
	v_lshlrev_b32_e32 v230, 16, v89
	v_and_b32_e32 v231, 0xffff0000, v89
; DI u32x4 pack8(const float (&f)[8]) { u32x4 w; w.x = pk2(f[0], f[1]); w.y = pk2(f[2], f[3]); w.z = pk2(f[4], f[5]); w.w = pk2(f[6], f[7]); return w; }
; DI void phase_mla_qk(const Params& p) {
;     ...
;                 if (ok[r]) *(u32x4*)(qr + 3072 + head * 256 + l16 * 8) = pack8(f);
;     ...
;               for (int e = 0; e < 8; ++e) {
;                   const float a = f[e] * sc * gkr[e], pa = __shfl_xor(a, 4);
;                   float sn, cs; sincosf(pos * inv[e], &sn, &cs);
	v_mul_f32_e32 v230, v230, v218
	v_mul_f32_e32 v231, v231, v219
	v_cvt_pk_bf16_f32 v89, v230, v231
	v_mul_f32_e32 v218, v209, v164
	v_mul_f32_e32 v219, v209, v165
	v_lshlrev_b32_e32 v230, 16, v90
	v_and_b32_e32 v231, 0xffff0000, v90
	v_mul_f32_e32 v230, v230, v218
	v_mul_f32_e32 v231, v231, v219
	v_cvt_pk_bf16_f32 v90, v230, v231
	v_mul_f32_e32 v218, v209, v166
	v_mul_f32_e32 v219, v209, v167
	v_lshlrev_b32_e32 v230, 16, v91
	v_and_b32_e32 v231, 0xffff0000, v91
	v_mul_f32_e32 v230, v230, v218
	v_mul_f32_e32 v231, v231, v219
	v_cvt_pk_bf16_f32 v91, v230, v231
	global_store_dwordx4 v195, v[88:91], s[30:31]
	v_mul_f32_e32 v218, v210, v160
	v_mul_f32_e32 v219, v210, v161
	v_lshlrev_b32_e32 v230, 16, v92
	v_and_b32_e32 v231, 0xffff0000, v92
	v_mul_f32_e32 v230, v230, v218
	v_mul_f32_e32 v231, v231, v219
	v_cvt_pk_bf16_f32 v92, v230, v231
	v_mul_f32_e32 v218, v210, v162
	v_mul_f32_e32 v219, v210, v163
	v_lshlrev_b32_e32 v230, 16, v93
	v_and_b32_e32 v231, 0xffff0000, v93
	v_mul_f32_e32 v230, v230, v218
	v_mul_f32_e32 v231, v231, v219
	v_cvt_pk_bf16_f32 v93, v230, v231
	v_mul_f32_e32 v218, v210, v164
	v_mul_f32_e32 v219, v210, v165
	v_lshlrev_b32_e32 v230, 16, v94
	v_and_b32_e32 v231, 0xffff0000, v94
	v_mul_f32_e32 v230, v230, v218
	v_mul_f32_e32 v231, v231, v219
	v_cvt_pk_bf16_f32 v94, v230, v231
	v_mul_f32_e32 v218, v210, v166
	v_mul_f32_e32 v219, v210, v167
	v_lshlrev_b32_e32 v230, 16, v95
	v_and_b32_e32 v231, 0xffff0000, v95
	v_mul_f32_e32 v230, v230, v218
	v_mul_f32_e32 v231, v231, v219
	v_cvt_pk_bf16_f32 v95, v230, v231
	global_store_dwordx4 v195, v[92:95], s[30:31] offset:2048
	s_add_u32 s36, s26, 0x1c00000
	s_addc_u32 s37, s27, 0
	s_add_u32 s30, s36, 0x1000
	s_addc_u32 s31, s37, 0
	v_mul_f32_e32 v218, v212, v160
	v_mul_f32_e32 v219, v212, v161
	v_lshlrev_b32_e32 v230, 16, v100
	v_and_b32_e32 v231, 0xffff0000, v100
	v_mul_f32_e32 v230, v230, v218
	v_mul_f32_e32 v231, v231, v219
	v_cvt_pk_bf16_f32 v100, v230, v231
	v_mul_f32_e32 v218, v212, v162
	v_mul_f32_e32 v219, v212, v163
	v_lshlrev_b32_e32 v230, 16, v101
	v_and_b32_e32 v231, 0xffff0000, v101
	v_mul_f32_e32 v230, v230, v218
	v_mul_f32_e32 v231, v231, v219
	v_cvt_pk_bf16_f32 v101, v230, v231
	v_mul_f32_e32 v218, v212, v164
	v_mul_f32_e32 v219, v212, v165
	v_lshlrev_b32_e32 v230, 16, v102
	v_and_b32_e32 v231, 0xffff0000, v102
	v_mul_f32_e32 v230, v230, v218
	v_mul_f32_e32 v231, v231, v219
	v_cvt_pk_bf16_f32 v102, v230, v231
	v_mul_f32_e32 v218, v212, v166
	v_mul_f32_e32 v219, v212, v167
	v_lshlrev_b32_e32 v230, 16, v103
	v_and_b32_e32 v231, 0xffff0000, v103
	v_mul_f32_e32 v230, v230, v218
	v_mul_f32_e32 v231, v231, v219
	v_cvt_pk_bf16_f32 v103, v230, v231
	global_store_dwordx4 v195, v[100:103], s[36:37]
	v_mul_f32_e32 v218, v213, v160
	v_mul_f32_e32 v219, v213, v161
	v_lshlrev_b32_e32 v230, 16, v104
	v_and_b32_e32 v231, 0xffff0000, v104
	v_mul_f32_e32 v230, v230, v218
	v_mul_f32_e32 v231, v231, v219
	v_cvt_pk_bf16_f32 v104, v230, v231
	v_mul_f32_e32 v218, v213, v162
	v_mul_f32_e32 v219, v213, v163
	v_lshlrev_b32_e32 v230, 16, v105
	v_and_b32_e32 v231, 0xffff0000, v105
	v_mul_f32_e32 v230, v230, v218
	v_mul_f32_e32 v231, v231, v219
	v_cvt_pk_bf16_f32 v105, v230, v231
	v_mul_f32_e32 v218, v213, v164
	v_mul_f32_e32 v219, v213, v165
	v_lshlrev_b32_e32 v230, 16, v106
	v_and_b32_e32 v231, 0xffff0000, v106
	v_mul_f32_e32 v230, v230, v218
	v_mul_f32_e32 v231, v231, v219
	v_cvt_pk_bf16_f32 v106, v230, v231
	v_mul_f32_e32 v218, v213, v166
	v_mul_f32_e32 v219, v213, v167
	v_lshlrev_b32_e32 v230, 16, v107
	v_and_b32_e32 v231, 0xffff0000, v107
	v_mul_f32_e32 v230, v230, v218
	v_mul_f32_e32 v231, v231, v219
	v_cvt_pk_bf16_f32 v107, v230, v231
	global_store_dwordx4 v195, v[104:107], s[36:37] offset:2048
	v_mul_f32_e32 v218, v214, v160
	v_mul_f32_e32 v219, v214, v161
	v_lshlrev_b32_e32 v230, 16, v108
	v_and_b32_e32 v231, 0xffff0000, v108
	v_mul_f32_e32 v230, v230, v218
	v_mul_f32_e32 v231, v231, v219
	v_cvt_pk_bf16_f32 v108, v230, v231
	v_mul_f32_e32 v218, v214, v162
	v_mul_f32_e32 v219, v214, v163
	v_lshlrev_b32_e32 v230, 16, v109
	v_and_b32_e32 v231, 0xffff0000, v109
	v_mul_f32_e32 v230, v230, v218
	v_mul_f32_e32 v231, v231, v219
	v_cvt_pk_bf16_f32 v109, v230, v231
	v_mul_f32_e32 v218, v214, v164
	v_mul_f32_e32 v219, v214, v165
	v_lshlrev_b32_e32 v230, 16, v110
	v_and_b32_e32 v231, 0xffff0000, v110
	v_mul_f32_e32 v230, v230, v218
	v_mul_f32_e32 v231, v231, v219
	v_cvt_pk_bf16_f32 v110, v230, v231
	v_mul_f32_e32 v218, v214, v166
	v_mul_f32_e32 v219, v214, v167
	v_lshlrev_b32_e32 v230, 16, v111
	v_and_b32_e32 v231, 0xffff0000, v111
	v_mul_f32_e32 v230, v230, v218
	v_mul_f32_e32 v231, v231, v219
	v_cvt_pk_bf16_f32 v111, v230, v231
	global_store_dwordx4 v195, v[108:111], s[30:31]
	v_mul_f32_e32 v218, v215, v160
	v_mul_f32_e32 v219, v215, v161
	v_lshlrev_b32_e32 v230, 16, v112
	v_and_b32_e32 v231, 0xffff0000, v112
	v_mul_f32_e32 v230, v230, v218
	v_mul_f32_e32 v231, v231, v219
	v_cvt_pk_bf16_f32 v112, v230, v231
	v_mul_f32_e32 v218, v215, v162
	v_mul_f32_e32 v219, v215, v163
	v_lshlrev_b32_e32 v230, 16, v113
	v_and_b32_e32 v231, 0xffff0000, v113
	v_mul_f32_e32 v230, v230, v218
	v_mul_f32_e32 v231, v231, v219
	v_cvt_pk_bf16_f32 v113, v230, v231
	v_mul_f32_e32 v218, v215, v164
	v_mul_f32_e32 v219, v215, v165
	v_lshlrev_b32_e32 v230, 16, v114
	v_and_b32_e32 v231, 0xffff0000, v114
	v_mul_f32_e32 v230, v230, v218
	v_mul_f32_e32 v231, v231, v219
	v_cvt_pk_bf16_f32 v114, v230, v231
	v_mul_f32_e32 v218, v215, v166
	v_mul_f32_e32 v219, v215, v167
	v_lshlrev_b32_e32 v230, 16, v115
	v_and_b32_e32 v231, 0xffff0000, v115
	v_mul_f32_e32 v230, v230, v218
	v_mul_f32_e32 v231, v231, v219
	v_cvt_pk_bf16_f32 v115, v230, v231
	global_store_dwordx4 v195, v[112:115], s[30:31] offset:2048
	v_lshlrev_b32_e32 v232, 16, v96
	v_and_b32_e32 v233, 0xffff0000, v96
	v_lshlrev_b32_e32 v234, 16, v97
	v_and_b32_e32 v235, 0xffff0000, v97
	v_lshlrev_b32_e32 v236, 16, v98
	v_and_b32_e32 v237, 0xffff0000, v98
	v_lshlrev_b32_e32 v238, 16, v99
	v_and_b32_e32 v239, 0xffff0000, v99
	v_mul_f32_e32 v232, v232, v211
	v_mul_f32_e32 v233, v233, v211
	v_mul_f32_e32 v234, v234, v211
	v_mul_f32_e32 v235, v235, v211
	v_mul_f32_e32 v236, v236, v211
	v_mul_f32_e32 v237, v237, v211
	v_mul_f32_e32 v238, v238, v211
	v_mul_f32_e32 v239, v239, v211
	v_mul_f32_e32 v232, v232, v168
	v_mul_f32_e32 v233, v233, v169
	v_mul_f32_e32 v234, v234, v170
	v_mul_f32_e32 v235, v235, v171
	v_mul_f32_e32 v236, v236, v172
	v_mul_f32_e32 v237, v237, v173
	v_mul_f32_e32 v238, v238, v174
	v_mul_f32_e32 v239, v239, v175
	ds_bpermute_b32 v240, v193, v232
	ds_bpermute_b32 v241, v193, v233
	ds_bpermute_b32 v242, v193, v234
	ds_bpermute_b32 v243, v193, v235
	ds_bpermute_b32 v244, v193, v236
	ds_bpermute_b32 v245, v193, v237
	ds_bpermute_b32 v246, v193, v238
	ds_bpermute_b32 v247, v193, v239
	s_and_b32 s35, s34, 0xfff
	v_cvt_f32_u32_e32 v218, s35
	v_mul_f32_e32 v218, 0x3e22f983, v218
	s_waitcnt lgkmcnt(0)
; DI u32x4 pack8(const float (&f)[8]) { u32x4 w; w.x = pk2(f[0], f[1]); w.y = pk2(f[2], f[3]); w.z = pk2(f[4], f[5]); w.w = pk2(f[6], f[7]); return w; }
; DI void phase_mla_qk(const Params& p) {
;     ...
;               for (int e = 0; e < 8; ++e) {
;                   const float a = f[e] * sc * gkr[e], pa = __shfl_xor(a, 4);
;                   float sn, cs; sincosf(pos * inv[e], &sn, &cs);
;                   o[e] = (l8 < 4) ? a * cs - pa * sn : a * cs + pa * sn;
;               }
;               if (ok[r] && lane < 8) *(u32x4*)kpp = pack8(o); }
	v_mul_f32_e32 v220, v218, v182
	v_fract_f32_e32 v220, v220
	v_sin_f32_e32 v221, v220
	v_cos_f32_e32 v222, v220
	v_mul_f32_e32 v240, v240, v190
	v_mul_f32_e32 v240, v240, v221
	v_fma_f32 v232, v232, v222, v240
	v_mul_f32_e32 v223, v218, v183
	v_fract_f32_e32 v223, v223
	v_sin_f32_e32 v224, v223
	v_cos_f32_e32 v225, v223
	v_mul_f32_e32 v241, v241, v190
	v_mul_f32_e32 v241, v241, v224
	v_fma_f32 v233, v233, v225, v241
	v_mul_f32_e32 v220, v218, v184
	v_fract_f32_e32 v220, v220
	v_sin_f32_e32 v221, v220
	v_cos_f32_e32 v222, v220
	v_mul_f32_e32 v242, v242, v190
	v_mul_f32_e32 v242, v242, v221
	v_fma_f32 v234, v234, v222, v242
	v_mul_f32_e32 v223, v218, v185
	v_fract_f32_e32 v223, v223
	v_sin_f32_e32 v224, v223
	v_cos_f32_e32 v225, v223
	v_mul_f32_e32 v243, v243, v190
	v_mul_f32_e32 v243, v243, v224
	v_fma_f32 v235, v235, v225, v243
	v_mul_f32_e32 v220, v218, v186
	v_fract_f32_e32 v220, v220
	v_sin_f32_e32 v221, v220
	v_cos_f32_e32 v222, v220
	v_mul_f32_e32 v244, v244, v190
	v_mul_f32_e32 v244, v244, v221
	v_fma_f32 v236, v236, v222, v244
	v_mul_f32_e32 v223, v218, v187
	v_fract_f32_e32 v223, v223
	v_sin_f32_e32 v224, v223
	v_cos_f32_e32 v225, v223
	v_mul_f32_e32 v245, v245, v190
	v_mul_f32_e32 v245, v245, v224
	v_fma_f32 v237, v237, v225, v245
	v_mul_f32_e32 v220, v218, v188
	v_fract_f32_e32 v220, v220
	v_sin_f32_e32 v221, v220
	v_cos_f32_e32 v222, v220
	v_mul_f32_e32 v246, v246, v190
	v_mul_f32_e32 v246, v246, v221
	v_fma_f32 v238, v238, v222, v246
	v_mul_f32_e32 v223, v218, v189
	v_fract_f32_e32 v223, v223
	v_sin_f32_e32 v224, v223
	v_cos_f32_e32 v225, v223
	v_mul_f32_e32 v247, v247, v190
	v_mul_f32_e32 v247, v247, v224
	v_fma_f32 v239, v239, v225, v247
	v_cvt_pk_bf16_f32 v96, v232, v233
	v_cvt_pk_bf16_f32 v97, v234, v235
	v_cvt_pk_bf16_f32 v98, v236, v237
	v_cvt_pk_bf16_f32 v99, v238, v239
	s_mov_b64 exec, 0xff
	global_store_dwordx4 v196, v[96:99], s[28:29]
	s_mov_b64 exec, -1
	v_lshlrev_b32_e32 v232, 16, v116
	v_and_b32_e32 v233, 0xffff0000, v116
	v_lshlrev_b32_e32 v234, 16, v117
	v_and_b32_e32 v235, 0xffff0000, v117
	v_lshlrev_b32_e32 v236, 16, v118
	v_and_b32_e32 v237, 0xffff0000, v118
	v_lshlrev_b32_e32 v238, 16, v119
	v_and_b32_e32 v239, 0xffff0000, v119
	v_mul_f32_e32 v232, v232, v216
	v_mul_f32_e32 v233, v233, v216
	v_mul_f32_e32 v234, v234, v216
	v_mul_f32_e32 v235, v235, v216
	v_mul_f32_e32 v236, v236, v216
	v_mul_f32_e32 v237, v237, v216
	v_mul_f32_e32 v238, v238, v216
	v_mul_f32_e32 v239, v239, v216
	v_mul_f32_e32 v232, v232, v168
	v_mul_f32_e32 v233, v233, v169
	v_mul_f32_e32 v234, v234, v170
	v_mul_f32_e32 v235, v235, v171
	v_mul_f32_e32 v236, v236, v172
	v_mul_f32_e32 v237, v237, v173
	v_mul_f32_e32 v238, v238, v174
	v_mul_f32_e32 v239, v239, v175
	ds_bpermute_b32 v240, v193, v232
	ds_bpermute_b32 v241, v193, v233
	ds_bpermute_b32 v242, v193, v234
	ds_bpermute_b32 v243, v193, v235
	ds_bpermute_b32 v244, v193, v236
	ds_bpermute_b32 v245, v193, v237
	ds_bpermute_b32 v246, v193, v238
	ds_bpermute_b32 v247, v193, v239
	s_add_i32 s35, s34, 0x800
	s_and_b32 s35, s35, 0xfff
	v_cvt_f32_u32_e32 v218, s35
	v_mul_f32_e32 v218, 0x3e22f983, v218
	s_waitcnt lgkmcnt(0)
	v_mul_f32_e32 v220, v218, v182
	v_fract_f32_e32 v220, v220
	v_sin_f32_e32 v221, v220
	v_cos_f32_e32 v222, v220
	v_mul_f32_e32 v240, v240, v190
	v_mul_f32_e32 v240, v240, v221
	v_fma_f32 v232, v232, v222, v240
	v_mul_f32_e32 v223, v218, v183
	v_fract_f32_e32 v223, v223
	v_sin_f32_e32 v224, v223
	v_cos_f32_e32 v225, v223
	v_mul_f32_e32 v241, v241, v190
	v_mul_f32_e32 v241, v241, v224
	v_fma_f32 v233, v233, v225, v241
	v_mul_f32_e32 v220, v218, v184
	v_fract_f32_e32 v220, v220
	v_sin_f32_e32 v221, v220
	v_cos_f32_e32 v222, v220
	v_mul_f32_e32 v242, v242, v190
	v_mul_f32_e32 v242, v242, v221
	v_fma_f32 v234, v234, v222, v242
	v_mul_f32_e32 v223, v218, v185
	v_fract_f32_e32 v223, v223
	v_sin_f32_e32 v224, v223
	v_cos_f32_e32 v225, v223
	v_mul_f32_e32 v243, v243, v190
	v_mul_f32_e32 v243, v243, v224
	v_fma_f32 v235, v235, v225, v243
	v_mul_f32_e32 v220, v218, v186
	v_fract_f32_e32 v220, v220
	v_sin_f32_e32 v221, v220
	v_cos_f32_e32 v222, v220
	v_mul_f32_e32 v244, v244, v190
	v_mul_f32_e32 v244, v244, v221
	v_fma_f32 v236, v236, v222, v244
	v_mul_f32_e32 v223, v218, v187
	v_fract_f32_e32 v223, v223
	v_sin_f32_e32 v224, v223
	v_cos_f32_e32 v225, v223
	v_mul_f32_e32 v245, v245, v190
	v_mul_f32_e32 v245, v245, v224
	v_fma_f32 v237, v237, v225, v245
	v_mul_f32_e32 v220, v218, v188
	v_fract_f32_e32 v220, v220
	v_sin_f32_e32 v221, v220
	v_cos_f32_e32 v222, v220
	v_mul_f32_e32 v246, v246, v190
	v_mul_f32_e32 v246, v246, v221
	v_fma_f32 v238, v238, v222, v246
	v_mul_f32_e32 v223, v218, v189
	v_fract_f32_e32 v223, v223
	v_sin_f32_e32 v224, v223
	v_cos_f32_e32 v225, v223
	v_mul_f32_e32 v247, v247, v190
	v_mul_f32_e32 v247, v247, v224
	v_fma_f32 v239, v239, v225, v247
	v_cvt_pk_bf16_f32 v116, v232, v233
	v_cvt_pk_bf16_f32 v117, v234, v235
	v_cvt_pk_bf16_f32 v118, v236, v237
	v_cvt_pk_bf16_f32 v119, v238, v239
	s_add_u32 s36, s28, 0x440000
	s_addc_u32 s37, s29, 0
	s_mov_b64 exec, 0xff
	global_store_dwordx4 v196, v[116:119], s[36:37]
	s_mov_b64 exec, -1
	s_add_u32 s26, s26, 0x3800000
	s_addc_u32 s27, s27, 0
	s_add_u32 s28, s28, 0x880000
	s_addc_u32 s29, s29, 0
	s_addk_i32 s34, 0x1000
	s_waitcnt vmcnt(30)
; DI void phase_mla_qk(const Params& p) {
;     ...
;                 float f[8]; unpack8(wk[r][i], f); float ss = 0.f;
; #pragma unroll
;                 for (int e = 0; e < 8; ++e) ss += f[e] * f[e];
;                 ss += __shfl_xor(ss, 1); ss += __shfl_xor(ss, 2); ss += __shfl_xor(ss, 4); ss += __shfl_xor(ss, 8);
;     ...
;             { float f[8], o[8]; unpack8(wp[r], f); float ss = 0.f;
; #pragma unroll
;               for (int e = 0; e < 8; ++e) ss += f[e] * f[e];
;               ss += __shfl_xor(ss, 1); ss += __shfl_xor(ss, 2); ss += __shfl_xor(ss, 4);
	v_lshlrev_b32_e32 v218, 16, v120
	v_and_b32_e32 v219, 0xffff0000, v120
	v_mul_f32_e32 v207, v218, v218
	v_fmac_f32_e32 v207, v219, v219
	v_lshlrev_b32_e32 v218, 16, v121
	v_and_b32_e32 v219, 0xffff0000, v121
	v_fmac_f32_e32 v207, v218, v218
	v_fmac_f32_e32 v207, v219, v219
	v_lshlrev_b32_e32 v218, 16, v122
	v_and_b32_e32 v219, 0xffff0000, v122
	v_fmac_f32_e32 v207, v218, v218
	v_fmac_f32_e32 v207, v219, v219
	v_lshlrev_b32_e32 v218, 16, v123
	v_and_b32_e32 v219, 0xffff0000, v123
	v_fmac_f32_e32 v207, v218, v218
	v_fmac_f32_e32 v207, v219, v219
	v_lshlrev_b32_e32 v218, 16, v124
	v_and_b32_e32 v219, 0xffff0000, v124
	v_mul_f32_e32 v208, v218, v218
	v_fmac_f32_e32 v208, v219, v219
	v_lshlrev_b32_e32 v218, 16, v125
	v_and_b32_e32 v219, 0xffff0000, v125
	v_fmac_f32_e32 v208, v218, v218
	v_fmac_f32_e32 v208, v219, v219
	v_lshlrev_b32_e32 v218, 16, v126
	v_and_b32_e32 v219, 0xffff0000, v126
	v_fmac_f32_e32 v208, v218, v218
	v_fmac_f32_e32 v208, v219, v219
	v_lshlrev_b32_e32 v218, 16, v127
	v_and_b32_e32 v219, 0xffff0000, v127
	v_fmac_f32_e32 v208, v218, v218
	v_fmac_f32_e32 v208, v219, v219
	v_lshlrev_b32_e32 v218, 16, v128
	v_and_b32_e32 v219, 0xffff0000, v128
	v_mul_f32_e32 v209, v218, v218
	v_fmac_f32_e32 v209, v219, v219
	v_lshlrev_b32_e32 v218, 16, v129
	v_and_b32_e32 v219, 0xffff0000, v129
	v_fmac_f32_e32 v209, v218, v218
	v_fmac_f32_e32 v209, v219, v219
	v_lshlrev_b32_e32 v218, 16, v130
	v_and_b32_e32 v219, 0xffff0000, v130
	v_fmac_f32_e32 v209, v218, v218
	v_fmac_f32_e32 v209, v219, v219
	v_lshlrev_b32_e32 v218, 16, v131
	v_and_b32_e32 v219, 0xffff0000, v131
	v_fmac_f32_e32 v209, v218, v218
	v_fmac_f32_e32 v209, v219, v219
	v_lshlrev_b32_e32 v218, 16, v132
	v_and_b32_e32 v219, 0xffff0000, v132
	v_mul_f32_e32 v210, v218, v218
	v_fmac_f32_e32 v210, v219, v219
	v_lshlrev_b32_e32 v218, 16, v133
	v_and_b32_e32 v219, 0xffff0000, v133
	v_fmac_f32_e32 v210, v218, v218
	v_fmac_f32_e32 v210, v219, v219
	v_lshlrev_b32_e32 v218, 16, v134
	v_and_b32_e32 v219, 0xffff0000, v134
	v_fmac_f32_e32 v210, v218, v218
	v_fmac_f32_e32 v210, v219, v219
	v_lshlrev_b32_e32 v218, 16, v135
	v_and_b32_e32 v219, 0xffff0000, v135
	v_fmac_f32_e32 v210, v218, v218
	v_fmac_f32_e32 v210, v219, v219
	v_lshlrev_b32_e32 v218, 16, v136
	v_and_b32_e32 v219, 0xffff0000, v136
	v_mul_f32_e32 v211, v218, v218
	v_fmac_f32_e32 v211, v219, v219
	v_lshlrev_b32_e32 v218, 16, v137
	v_and_b32_e32 v219, 0xffff0000, v137
	v_fmac_f32_e32 v211, v218, v218
	v_fmac_f32_e32 v211, v219, v219
	v_lshlrev_b32_e32 v218, 16, v138
	v_and_b32_e32 v219, 0xffff0000, v138
	v_fmac_f32_e32 v211, v218, v218
	v_fmac_f32_e32 v211, v219, v219
	v_lshlrev_b32_e32 v218, 16, v139
	v_and_b32_e32 v219, 0xffff0000, v139
	v_fmac_f32_e32 v211, v218, v218
	v_fmac_f32_e32 v211, v219, v219
	v_lshlrev_b32_e32 v218, 16, v140
	v_and_b32_e32 v219, 0xffff0000, v140
	v_mul_f32_e32 v212, v218, v218
	v_fmac_f32_e32 v212, v219, v219
	v_lshlrev_b32_e32 v218, 16, v141
	v_and_b32_e32 v219, 0xffff0000, v141
	v_fmac_f32_e32 v212, v218, v218
	v_fmac_f32_e32 v212, v219, v219
	v_lshlrev_b32_e32 v218, 16, v142
	v_and_b32_e32 v219, 0xffff0000, v142
	v_fmac_f32_e32 v212, v218, v218
	v_fmac_f32_e32 v212, v219, v219
	v_lshlrev_b32_e32 v218, 16, v143
	v_and_b32_e32 v219, 0xffff0000, v143
	v_fmac_f32_e32 v212, v218, v218
	v_fmac_f32_e32 v212, v219, v219
	v_lshlrev_b32_e32 v218, 16, v144
	v_and_b32_e32 v219, 0xffff0000, v144
	v_mul_f32_e32 v213, v218, v218
	v_fmac_f32_e32 v213, v219, v219
	v_lshlrev_b32_e32 v218, 16, v145
	v_and_b32_e32 v219, 0xffff0000, v145
	v_fmac_f32_e32 v213, v218, v218
	v_fmac_f32_e32 v213, v219, v219
	v_lshlrev_b32_e32 v218, 16, v146
	v_and_b32_e32 v219, 0xffff0000, v146
	v_fmac_f32_e32 v213, v218, v218
	v_fmac_f32_e32 v213, v219, v219
	v_lshlrev_b32_e32 v218, 16, v147
	v_and_b32_e32 v219, 0xffff0000, v147
	v_fmac_f32_e32 v213, v218, v218
	v_fmac_f32_e32 v213, v219, v219
	v_lshlrev_b32_e32 v218, 16, v148
	v_and_b32_e32 v219, 0xffff0000, v148
	v_mul_f32_e32 v214, v218, v218
	v_fmac_f32_e32 v214, v219, v219
	v_lshlrev_b32_e32 v218, 16, v149
	v_and_b32_e32 v219, 0xffff0000, v149
	v_fmac_f32_e32 v214, v218, v218
	v_fmac_f32_e32 v214, v219, v219
	v_lshlrev_b32_e32 v218, 16, v150
	v_and_b32_e32 v219, 0xffff0000, v150
	v_fmac_f32_e32 v214, v218, v218
	v_fmac_f32_e32 v214, v219, v219
	v_lshlrev_b32_e32 v218, 16, v151
	v_and_b32_e32 v219, 0xffff0000, v151
	v_fmac_f32_e32 v214, v218, v218
	v_fmac_f32_e32 v214, v219, v219
	v_lshlrev_b32_e32 v218, 16, v152
	v_and_b32_e32 v219, 0xffff0000, v152
	v_mul_f32_e32 v215, v218, v218
	v_fmac_f32_e32 v215, v219, v219
	v_lshlrev_b32_e32 v218, 16, v153
	v_and_b32_e32 v219, 0xffff0000, v153
	v_fmac_f32_e32 v215, v218, v218
	v_fmac_f32_e32 v215, v219, v219
	v_lshlrev_b32_e32 v218, 16, v154
	v_and_b32_e32 v219, 0xffff0000, v154
	v_fmac_f32_e32 v215, v218, v218
	v_fmac_f32_e32 v215, v219, v219
	v_lshlrev_b32_e32 v218, 16, v155
	v_and_b32_e32 v219, 0xffff0000, v155
	v_fmac_f32_e32 v215, v218, v218
	v_fmac_f32_e32 v215, v219, v219
	v_lshlrev_b32_e32 v218, 16, v156
	v_and_b32_e32 v219, 0xffff0000, v156
	v_mul_f32_e32 v216, v218, v218
	v_fmac_f32_e32 v216, v219, v219
	v_lshlrev_b32_e32 v218, 16, v157
	v_and_b32_e32 v219, 0xffff0000, v157
	v_fmac_f32_e32 v216, v218, v218
	v_fmac_f32_e32 v216, v219, v219
	v_lshlrev_b32_e32 v218, 16, v158
	v_and_b32_e32 v219, 0xffff0000, v158
	v_fmac_f32_e32 v216, v218, v218
	v_fmac_f32_e32 v216, v219, v219
	v_lshlrev_b32_e32 v218, 16, v159
	v_and_b32_e32 v219, 0xffff0000, v159
	v_fmac_f32_e32 v216, v218, v218
	v_fmac_f32_e32 v216, v219, v219
	ds_bpermute_b32 v220, v191, v207
	ds_bpermute_b32 v221, v191, v208
	ds_bpermute_b32 v222, v191, v209
	ds_bpermute_b32 v223, v191, v210
	ds_bpermute_b32 v224, v191, v211
	ds_bpermute_b32 v225, v191, v212
	ds_bpermute_b32 v226, v191, v213
	ds_bpermute_b32 v227, v191, v214
	ds_bpermute_b32 v228, v191, v215
	ds_bpermute_b32 v229, v191, v216
	s_waitcnt lgkmcnt(0)
; DI u32x4 pack8(const float (&f)[8]) { u32x4 w; w.x = pk2(f[0], f[1]); w.y = pk2(f[2], f[3]); w.z = pk2(f[4], f[5]); w.w = pk2(f[6], f[7]); return w; }
; DI void phase_mla_qk(const Params& p) {
;     ...
;             for (int i = 0; i < 4; ++i) {
;                 const int head = 4 * i + (lane >> 4);
;                 float f[8]; unpack8(wk[r][i], f); float ss = 0.f;
; #pragma unroll
;                 for (int e = 0; e < 8; ++e) ss += f[e] * f[e];
;                 ss += __shfl_xor(ss, 1); ss += __shfl_xor(ss, 2); ss += __shfl_xor(ss, 4); ss += __shfl_xor(ss, 8);
;                 const float sc = rsqrtf(ss * (1.f / 128.f) + EPS);
; #pragma unroll
;                 for (int e = 0; e < 8; ++e) f[e] *= sc * gk[e];
;                 if (ok[r]) *(u32x4*)(qr + 3072 + head * 256 + l16 * 8) = pack8(f);
;             }
;             { float f[8], o[8]; unpack8(wp[r], f); float ss = 0.f;
; #pragma unroll
;               for (int e = 0; e < 8; ++e) ss += f[e] * f[e];
;               ss += __shfl_xor(ss, 1); ss += __shfl_xor(ss, 2); ss += __shfl_xor(ss, 4);
;               const float sc = rsqrtf(ss * (1.f / 64.f) + EPS);
	v_add_f32_e32 v207, v207, v220
	v_add_f32_e32 v208, v208, v221
	v_add_f32_e32 v209, v209, v222
	v_add_f32_e32 v210, v210, v223
	v_add_f32_e32 v211, v211, v224
	v_add_f32_e32 v212, v212, v225
	v_add_f32_e32 v213, v213, v226
	v_add_f32_e32 v214, v214, v227
	v_add_f32_e32 v215, v215, v228
	v_add_f32_e32 v216, v216, v229
	ds_bpermute_b32 v220, v192, v207
	ds_bpermute_b32 v221, v192, v208
	ds_bpermute_b32 v222, v192, v209
	ds_bpermute_b32 v223, v192, v210
	ds_bpermute_b32 v224, v192, v211
	ds_bpermute_b32 v225, v192, v212
	ds_bpermute_b32 v226, v192, v213
	ds_bpermute_b32 v227, v192, v214
	ds_bpermute_b32 v228, v192, v215
	ds_bpermute_b32 v229, v192, v216
	s_waitcnt lgkmcnt(0)
	v_add_f32_e32 v207, v207, v220
	v_add_f32_e32 v208, v208, v221
	v_add_f32_e32 v209, v209, v222
	v_add_f32_e32 v210, v210, v223
	v_add_f32_e32 v211, v211, v224
	v_add_f32_e32 v212, v212, v225
	v_add_f32_e32 v213, v213, v226
	v_add_f32_e32 v214, v214, v227
	v_add_f32_e32 v215, v215, v228
	v_add_f32_e32 v216, v216, v229
	ds_bpermute_b32 v220, v193, v207
	ds_bpermute_b32 v221, v193, v208
	ds_bpermute_b32 v222, v193, v209
	ds_bpermute_b32 v223, v193, v210
	ds_bpermute_b32 v224, v193, v211
	ds_bpermute_b32 v225, v193, v212
	ds_bpermute_b32 v226, v193, v213
	ds_bpermute_b32 v227, v193, v214
	ds_bpermute_b32 v228, v193, v215
	ds_bpermute_b32 v229, v193, v216
	s_waitcnt lgkmcnt(0)
	v_add_f32_e32 v207, v207, v220
	v_add_f32_e32 v208, v208, v221
	v_add_f32_e32 v209, v209, v222
	v_add_f32_e32 v210, v210, v223
	v_add_f32_e32 v211, v211, v224
	v_add_f32_e32 v212, v212, v225
	v_add_f32_e32 v213, v213, v226
	v_add_f32_e32 v214, v214, v227
	v_add_f32_e32 v215, v215, v228
	v_add_f32_e32 v216, v216, v229
	ds_bpermute_b32 v220, v194, v207
	ds_bpermute_b32 v221, v194, v208
	ds_bpermute_b32 v222, v194, v209
	ds_bpermute_b32 v223, v194, v210
	ds_bpermute_b32 v225, v194, v212
	ds_bpermute_b32 v226, v194, v213
	ds_bpermute_b32 v227, v194, v214
	ds_bpermute_b32 v228, v194, v215
	s_waitcnt lgkmcnt(0)
	v_add_f32_e32 v207, v207, v220
	v_add_f32_e32 v208, v208, v221
	v_add_f32_e32 v209, v209, v222
	v_add_f32_e32 v210, v210, v223
	v_add_f32_e32 v212, v212, v225
	v_add_f32_e32 v213, v213, v226
	v_add_f32_e32 v214, v214, v227
	v_add_f32_e32 v215, v215, v228
	v_mul_f32_e32 v207, 0x3c000000, v207
	v_add_f32_e32 v207, 0x358637bd, v207
	v_mul_f32_e32 v208, 0x3c000000, v208
	v_add_f32_e32 v208, 0x358637bd, v208
	v_mul_f32_e32 v209, 0x3c000000, v209
	v_add_f32_e32 v209, 0x358637bd, v209
	v_mul_f32_e32 v210, 0x3c000000, v210
	v_add_f32_e32 v210, 0x358637bd, v210
	v_mul_f32_e32 v211, 0x3c800000, v211
	v_add_f32_e32 v211, 0x358637bd, v211
	v_mul_f32_e32 v212, 0x3c000000, v212
	v_add_f32_e32 v212, 0x358637bd, v212
	v_mul_f32_e32 v213, 0x3c000000, v213
	v_add_f32_e32 v213, 0x358637bd, v213
	v_mul_f32_e32 v214, 0x3c000000, v214
	v_add_f32_e32 v214, 0x358637bd, v214
	v_mul_f32_e32 v215, 0x3c000000, v215
	v_add_f32_e32 v215, 0x358637bd, v215
	v_mul_f32_e32 v216, 0x3c800000, v216
	v_add_f32_e32 v216, 0x358637bd, v216
	v_rsq_f32_e32 v207, v207
	v_rsq_f32_e32 v208, v208
	v_rsq_f32_e32 v209, v209
	v_rsq_f32_e32 v210, v210
	v_rsq_f32_e32 v211, v211
	v_rsq_f32_e32 v212, v212
	v_rsq_f32_e32 v213, v213
	v_rsq_f32_e32 v214, v214
	v_rsq_f32_e32 v215, v215
	v_rsq_f32_e32 v216, v216
	s_nop 1
	s_add_u32 s30, s26, 0x1000
	s_addc_u32 s31, s27, 0
	v_mul_f32_e32 v218, v207, v160
	v_mul_f32_e32 v219, v207, v161
	v_lshlrev_b32_e32 v230, 16, v120
	v_and_b32_e32 v231, 0xffff0000, v120
	v_mul_f32_e32 v230, v230, v218
	v_mul_f32_e32 v231, v231, v219
	v_cvt_pk_bf16_f32 v120, v230, v231
	v_mul_f32_e32 v218, v207, v162
	v_mul_f32_e32 v219, v207, v163
	v_lshlrev_b32_e32 v230, 16, v121
	v_and_b32_e32 v231, 0xffff0000, v121
	v_mul_f32_e32 v230, v230, v218
	v_mul_f32_e32 v231, v231, v219
	v_cvt_pk_bf16_f32 v121, v230, v231
	v_mul_f32_e32 v218, v207, v164
	v_mul_f32_e32 v219, v207, v165
	v_lshlrev_b32_e32 v230, 16, v122
	v_and_b32_e32 v231, 0xffff0000, v122
	v_mul_f32_e32 v230, v230, v218
	v_mul_f32_e32 v231, v231, v219
	v_cvt_pk_bf16_f32 v122, v230, v231
	v_mul_f32_e32 v218, v207, v166
	v_mul_f32_e32 v219, v207, v167
	v_lshlrev_b32_e32 v230, 16, v123
	v_and_b32_e32 v231, 0xffff0000, v123
	v_mul_f32_e32 v230, v230, v218
	v_mul_f32_e32 v231, v231, v219
	v_cvt_pk_bf16_f32 v123, v230, v231
	global_store_dwordx4 v195, v[120:123], s[26:27]
	v_mul_f32_e32 v218, v208, v160
	v_mul_f32_e32 v219, v208, v161
	v_lshlrev_b32_e32 v230, 16, v124
	v_and_b32_e32 v231, 0xffff0000, v124
	v_mul_f32_e32 v230, v230, v218
	v_mul_f32_e32 v231, v231, v219
	v_cvt_pk_bf16_f32 v124, v230, v231
	v_mul_f32_e32 v218, v208, v162
	v_mul_f32_e32 v219, v208, v163
	v_lshlrev_b32_e32 v230, 16, v125
	v_and_b32_e32 v231, 0xffff0000, v125
	v_mul_f32_e32 v230, v230, v218
	v_mul_f32_e32 v231, v231, v219
	v_cvt_pk_bf16_f32 v125, v230, v231
	v_mul_f32_e32 v218, v208, v164
	v_mul_f32_e32 v219, v208, v165
	v_lshlrev_b32_e32 v230, 16, v126
	v_and_b32_e32 v231, 0xffff0000, v126
	v_mul_f32_e32 v230, v230, v218
	v_mul_f32_e32 v231, v231, v219
	v_cvt_pk_bf16_f32 v126, v230, v231
	v_mul_f32_e32 v218, v208, v166
	v_mul_f32_e32 v219, v208, v167
	v_lshlrev_b32_e32 v230, 16, v127
	v_and_b32_e32 v231, 0xffff0000, v127
	v_mul_f32_e32 v230, v230, v218
	v_mul_f32_e32 v231, v231, v219
	v_cvt_pk_bf16_f32 v127, v230, v231
	global_store_dwordx4 v195, v[124:127], s[26:27] offset:2048
	v_mul_f32_e32 v218, v209, v160
	v_mul_f32_e32 v219, v209, v161
	v_lshlrev_b32_e32 v230, 16, v128
	v_and_b32_e32 v231, 0xffff0000, v128
	v_mul_f32_e32 v230, v230, v218
	v_mul_f32_e32 v231, v231, v219
	v_cvt_pk_bf16_f32 v128, v230, v231
	v_mul_f32_e32 v218, v209, v162
	v_mul_f32_e32 v219, v209, v163
	v_lshlrev_b32_e32 v230, 16, v129
; DI u32x4 pack8(const float (&f)[8]) { u32x4 w; w.x = pk2(f[0], f[1]); w.y = pk2(f[2], f[3]); w.z = pk2(f[4], f[5]); w.w = pk2(f[6], f[7]); return w; }
; DI void phase_mla_qk(const Params& p) {
;     ...
;             for (int i = 0; i < 4; ++i) {
;                 const int head = 4 * i + (lane >> 4);
;                 float f[8]; unpack8(wk[r][i], f); float ss = 0.f;
; #pragma unroll
;                 for (int e = 0; e < 8; ++e) ss += f[e] * f[e];
;                 ss += __shfl_xor(ss, 1); ss += __shfl_xor(ss, 2); ss += __shfl_xor(ss, 4); ss += __shfl_xor(ss, 8);
;                 const float sc = rsqrtf(ss * (1.f / 128.f) + EPS);
; #pragma unroll
;                 for (int e = 0; e < 8; ++e) f[e] *= sc * gk[e];
;                 if (ok[r]) *(u32x4*)(qr + 3072 + head * 256 + l16 * 8) = pack8(f);
;             }
;             { float f[8], o[8]; unpack8(wp[r], f); float ss = 0.f;
; #pragma unroll
;               for (int e = 0; e < 8; ++e) ss += f[e] * f[e];
;               ss += __shfl_xor(ss, 1); ss += __shfl_xor(ss, 2); ss += __shfl_xor(ss, 4);
;               const float sc = rsqrtf(ss * (1.f / 64.f) + EPS);
; #pragma unroll
;               for (int e = 0; e < 8; ++e) {
;                   const float a = f[e] * sc * gkr[e], pa = __shfl_xor(a, 4);
;                   float sn, cs; sincosf(pos * inv[e], &sn, &cs);
;                   o[e] = (l8 < 4) ? a * cs - pa * sn : a * cs + pa * sn;
	v_and_b32_e32 v231, 0xffff0000, v129
	v_mul_f32_e32 v230, v230, v218
	v_mul_f32_e32 v231, v231, v219
	v_cvt_pk_bf16_f32 v129, v230, v231
	v_mul_f32_e32 v218, v209, v164
	v_mul_f32_e32 v219, v209, v165
	v_lshlrev_b32_e32 v230, 16, v130
	v_and_b32_e32 v231, 0xffff0000, v130
	v_mul_f32_e32 v230, v230, v218
	v_mul_f32_e32 v231, v231, v219
	v_cvt_pk_bf16_f32 v130, v230, v231
	v_mul_f32_e32 v218, v209, v166
	v_mul_f32_e32 v219, v209, v167
	v_lshlrev_b32_e32 v230, 16, v131
	v_and_b32_e32 v231, 0xffff0000, v131
	v_mul_f32_e32 v230, v230, v218
	v_mul_f32_e32 v231, v231, v219
	v_cvt_pk_bf16_f32 v131, v230, v231
	global_store_dwordx4 v195, v[128:131], s[30:31]
	v_mul_f32_e32 v218, v210, v160
	v_mul_f32_e32 v219, v210, v161
	v_lshlrev_b32_e32 v230, 16, v132
	v_and_b32_e32 v231, 0xffff0000, v132
	v_mul_f32_e32 v230, v230, v218
	v_mul_f32_e32 v231, v231, v219
	v_cvt_pk_bf16_f32 v132, v230, v231
	v_mul_f32_e32 v218, v210, v162
	v_mul_f32_e32 v219, v210, v163
	v_lshlrev_b32_e32 v230, 16, v133
	v_and_b32_e32 v231, 0xffff0000, v133
	v_mul_f32_e32 v230, v230, v218
	v_mul_f32_e32 v231, v231, v219
	v_cvt_pk_bf16_f32 v133, v230, v231
	v_mul_f32_e32 v218, v210, v164
	v_mul_f32_e32 v219, v210, v165
	v_lshlrev_b32_e32 v230, 16, v134
	v_and_b32_e32 v231, 0xffff0000, v134
	v_mul_f32_e32 v230, v230, v218
	v_mul_f32_e32 v231, v231, v219
	v_cvt_pk_bf16_f32 v134, v230, v231
	v_mul_f32_e32 v218, v210, v166
	v_mul_f32_e32 v219, v210, v167
	v_lshlrev_b32_e32 v230, 16, v135
	v_and_b32_e32 v231, 0xffff0000, v135
	v_mul_f32_e32 v230, v230, v218
	v_mul_f32_e32 v231, v231, v219
	v_cvt_pk_bf16_f32 v135, v230, v231
	global_store_dwordx4 v195, v[132:135], s[30:31] offset:2048
	s_add_u32 s36, s26, 0x1c00000
	s_addc_u32 s37, s27, 0
	s_add_u32 s30, s36, 0x1000
	s_addc_u32 s31, s37, 0
	v_mul_f32_e32 v218, v212, v160
	v_mul_f32_e32 v219, v212, v161
	v_lshlrev_b32_e32 v230, 16, v140
	v_and_b32_e32 v231, 0xffff0000, v140
	v_mul_f32_e32 v230, v230, v218
	v_mul_f32_e32 v231, v231, v219
	v_cvt_pk_bf16_f32 v140, v230, v231
	v_mul_f32_e32 v218, v212, v162
	v_mul_f32_e32 v219, v212, v163
	v_lshlrev_b32_e32 v230, 16, v141
	v_and_b32_e32 v231, 0xffff0000, v141
	v_mul_f32_e32 v230, v230, v218
	v_mul_f32_e32 v231, v231, v219
	v_cvt_pk_bf16_f32 v141, v230, v231
	v_mul_f32_e32 v218, v212, v164
	v_mul_f32_e32 v219, v212, v165
	v_lshlrev_b32_e32 v230, 16, v142
	v_and_b32_e32 v231, 0xffff0000, v142
	v_mul_f32_e32 v230, v230, v218
	v_mul_f32_e32 v231, v231, v219
	v_cvt_pk_bf16_f32 v142, v230, v231
	v_mul_f32_e32 v218, v212, v166
	v_mul_f32_e32 v219, v212, v167
	v_lshlrev_b32_e32 v230, 16, v143
	v_and_b32_e32 v231, 0xffff0000, v143
	v_mul_f32_e32 v230, v230, v218
	v_mul_f32_e32 v231, v231, v219
	v_cvt_pk_bf16_f32 v143, v230, v231
	global_store_dwordx4 v195, v[140:143], s[36:37]
	v_mul_f32_e32 v218, v213, v160
	v_mul_f32_e32 v219, v213, v161
	v_lshlrev_b32_e32 v230, 16, v144
	v_and_b32_e32 v231, 0xffff0000, v144
	v_mul_f32_e32 v230, v230, v218
	v_mul_f32_e32 v231, v231, v219
	v_cvt_pk_bf16_f32 v144, v230, v231
	v_mul_f32_e32 v218, v213, v162
	v_mul_f32_e32 v219, v213, v163
	v_lshlrev_b32_e32 v230, 16, v145
	v_and_b32_e32 v231, 0xffff0000, v145
	v_mul_f32_e32 v230, v230, v218
	v_mul_f32_e32 v231, v231, v219
	v_cvt_pk_bf16_f32 v145, v230, v231
	v_mul_f32_e32 v218, v213, v164
	v_mul_f32_e32 v219, v213, v165
	v_lshlrev_b32_e32 v230, 16, v146
	v_and_b32_e32 v231, 0xffff0000, v146
	v_mul_f32_e32 v230, v230, v218
	v_mul_f32_e32 v231, v231, v219
	v_cvt_pk_bf16_f32 v146, v230, v231
	v_mul_f32_e32 v218, v213, v166
	v_mul_f32_e32 v219, v213, v167
	v_lshlrev_b32_e32 v230, 16, v147
	v_and_b32_e32 v231, 0xffff0000, v147
	v_mul_f32_e32 v230, v230, v218
	v_mul_f32_e32 v231, v231, v219
	v_cvt_pk_bf16_f32 v147, v230, v231
	global_store_dwordx4 v195, v[144:147], s[36:37] offset:2048
	v_mul_f32_e32 v218, v214, v160
	v_mul_f32_e32 v219, v214, v161
	v_lshlrev_b32_e32 v230, 16, v148
	v_and_b32_e32 v231, 0xffff0000, v148
	v_mul_f32_e32 v230, v230, v218
	v_mul_f32_e32 v231, v231, v219
	v_cvt_pk_bf16_f32 v148, v230, v231
	v_mul_f32_e32 v218, v214, v162
	v_mul_f32_e32 v219, v214, v163
	v_lshlrev_b32_e32 v230, 16, v149
	v_and_b32_e32 v231, 0xffff0000, v149
	v_mul_f32_e32 v230, v230, v218
	v_mul_f32_e32 v231, v231, v219
	v_cvt_pk_bf16_f32 v149, v230, v231
	v_mul_f32_e32 v218, v214, v164
	v_mul_f32_e32 v219, v214, v165
	v_lshlrev_b32_e32 v230, 16, v150
	v_and_b32_e32 v231, 0xffff0000, v150
	v_mul_f32_e32 v230, v230, v218
	v_mul_f32_e32 v231, v231, v219
	v_cvt_pk_bf16_f32 v150, v230, v231
	v_mul_f32_e32 v218, v214, v166
	v_mul_f32_e32 v219, v214, v167
	v_lshlrev_b32_e32 v230, 16, v151
	v_and_b32_e32 v231, 0xffff0000, v151
	v_mul_f32_e32 v230, v230, v218
	v_mul_f32_e32 v231, v231, v219
	v_cvt_pk_bf16_f32 v151, v230, v231
	global_store_dwordx4 v195, v[148:151], s[30:31]
	v_mul_f32_e32 v218, v215, v160
	v_mul_f32_e32 v219, v215, v161
	v_lshlrev_b32_e32 v230, 16, v152
	v_and_b32_e32 v231, 0xffff0000, v152
	v_mul_f32_e32 v230, v230, v218
	v_mul_f32_e32 v231, v231, v219
	v_cvt_pk_bf16_f32 v152, v230, v231
	v_mul_f32_e32 v218, v215, v162
	v_mul_f32_e32 v219, v215, v163
	v_lshlrev_b32_e32 v230, 16, v153
	v_and_b32_e32 v231, 0xffff0000, v153
	v_mul_f32_e32 v230, v230, v218
	v_mul_f32_e32 v231, v231, v219
	v_cvt_pk_bf16_f32 v153, v230, v231
	v_mul_f32_e32 v218, v215, v164
	v_mul_f32_e32 v219, v215, v165
	v_lshlrev_b32_e32 v230, 16, v154
	v_and_b32_e32 v231, 0xffff0000, v154
	v_mul_f32_e32 v230, v230, v218
	v_mul_f32_e32 v231, v231, v219
	v_cvt_pk_bf16_f32 v154, v230, v231
	v_mul_f32_e32 v218, v215, v166
	v_mul_f32_e32 v219, v215, v167
	v_lshlrev_b32_e32 v230, 16, v155
	v_and_b32_e32 v231, 0xffff0000, v155
	v_mul_f32_e32 v230, v230, v218
	v_mul_f32_e32 v231, v231, v219
	v_cvt_pk_bf16_f32 v155, v230, v231
	global_store_dwordx4 v195, v[152:155], s[30:31] offset:2048
	v_lshlrev_b32_e32 v232, 16, v136
	v_and_b32_e32 v233, 0xffff0000, v136
	v_lshlrev_b32_e32 v234, 16, v137
	v_and_b32_e32 v235, 0xffff0000, v137
	v_lshlrev_b32_e32 v236, 16, v138
	v_and_b32_e32 v237, 0xffff0000, v138
	v_lshlrev_b32_e32 v238, 16, v139
	v_and_b32_e32 v239, 0xffff0000, v139
	v_mul_f32_e32 v232, v232, v211
	v_mul_f32_e32 v233, v233, v211
	v_mul_f32_e32 v234, v234, v211
	v_mul_f32_e32 v235, v235, v211
	v_mul_f32_e32 v236, v236, v211
	v_mul_f32_e32 v237, v237, v211
	v_mul_f32_e32 v238, v238, v211
	v_mul_f32_e32 v239, v239, v211
	v_mul_f32_e32 v232, v232, v168
	v_mul_f32_e32 v233, v233, v169
	v_mul_f32_e32 v234, v234, v170
	v_mul_f32_e32 v235, v235, v171
	v_mul_f32_e32 v236, v236, v172
	v_mul_f32_e32 v237, v237, v173
	v_mul_f32_e32 v238, v238, v174
	v_mul_f32_e32 v239, v239, v175
	ds_bpermute_b32 v240, v193, v232
	ds_bpermute_b32 v241, v193, v233
	ds_bpermute_b32 v242, v193, v234
	ds_bpermute_b32 v243, v193, v235
	ds_bpermute_b32 v244, v193, v236
	ds_bpermute_b32 v245, v193, v237
	ds_bpermute_b32 v246, v193, v238
	ds_bpermute_b32 v247, v193, v239
	s_and_b32 s35, s34, 0xfff
	v_cvt_f32_u32_e32 v218, s35
	v_mul_f32_e32 v218, 0x3e22f983, v218
	s_waitcnt lgkmcnt(0)
; DI u32x4 pack8(const float (&f)[8]) { u32x4 w; w.x = pk2(f[0], f[1]); w.y = pk2(f[2], f[3]); w.z = pk2(f[4], f[5]); w.w = pk2(f[6], f[7]); return w; }
; DI void phase_mla_qk(const Params& p) {
;     ...
; #pragma unroll
;               for (int e = 0; e < 8; ++e) {
;                   const float a = f[e] * sc * gkr[e], pa = __shfl_xor(a, 4);
;                   float sn, cs; sincosf(pos * inv[e], &sn, &cs);
;                   o[e] = (l8 < 4) ? a * cs - pa * sn : a * cs + pa * sn;
;               }
;               if (ok[r] && lane < 8) *(u32x4*)kpp = pack8(o); }
	v_mul_f32_e32 v220, v218, v182
	v_fract_f32_e32 v220, v220
	v_sin_f32_e32 v221, v220
	v_cos_f32_e32 v222, v220
	v_mul_f32_e32 v240, v240, v190
	v_mul_f32_e32 v240, v240, v221
	v_fma_f32 v232, v232, v222, v240
	v_mul_f32_e32 v223, v218, v183
	v_fract_f32_e32 v223, v223
	v_sin_f32_e32 v224, v223
	v_cos_f32_e32 v225, v223
	v_mul_f32_e32 v241, v241, v190
	v_mul_f32_e32 v241, v241, v224
	v_fma_f32 v233, v233, v225, v241
	v_mul_f32_e32 v220, v218, v184
	v_fract_f32_e32 v220, v220
	v_sin_f32_e32 v221, v220
	v_cos_f32_e32 v222, v220
	v_mul_f32_e32 v242, v242, v190
	v_mul_f32_e32 v242, v242, v221
	v_fma_f32 v234, v234, v222, v242
	v_mul_f32_e32 v223, v218, v185
	v_fract_f32_e32 v223, v223
	v_sin_f32_e32 v224, v223
	v_cos_f32_e32 v225, v223
	v_mul_f32_e32 v243, v243, v190
	v_mul_f32_e32 v243, v243, v224
	v_fma_f32 v235, v235, v225, v243
	v_mul_f32_e32 v220, v218, v186
	v_fract_f32_e32 v220, v220
	v_sin_f32_e32 v221, v220
	v_cos_f32_e32 v222, v220
	v_mul_f32_e32 v244, v244, v190
	v_mul_f32_e32 v244, v244, v221
	v_fma_f32 v236, v236, v222, v244
	v_mul_f32_e32 v223, v218, v187
	v_fract_f32_e32 v223, v223
	v_sin_f32_e32 v224, v223
	v_cos_f32_e32 v225, v223
	v_mul_f32_e32 v245, v245, v190
	v_mul_f32_e32 v245, v245, v224
	v_fma_f32 v237, v237, v225, v245
	v_mul_f32_e32 v220, v218, v188
	v_fract_f32_e32 v220, v220
	v_sin_f32_e32 v221, v220
	v_cos_f32_e32 v222, v220
	v_mul_f32_e32 v246, v246, v190
	v_mul_f32_e32 v246, v246, v221
	v_fma_f32 v238, v238, v222, v246
	v_mul_f32_e32 v223, v218, v189
	v_fract_f32_e32 v223, v223
	v_sin_f32_e32 v224, v223
	v_cos_f32_e32 v225, v223
	v_mul_f32_e32 v247, v247, v190
	v_mul_f32_e32 v247, v247, v224
	v_fma_f32 v239, v239, v225, v247
	v_cvt_pk_bf16_f32 v136, v232, v233
	v_cvt_pk_bf16_f32 v137, v234, v235
	v_cvt_pk_bf16_f32 v138, v236, v237
	v_cvt_pk_bf16_f32 v139, v238, v239
	s_mov_b64 exec, 0xff
	global_store_dwordx4 v196, v[136:139], s[28:29]
	s_mov_b64 exec, -1
	v_lshlrev_b32_e32 v232, 16, v156
	v_and_b32_e32 v233, 0xffff0000, v156
	v_lshlrev_b32_e32 v234, 16, v157
	v_and_b32_e32 v235, 0xffff0000, v157
	v_lshlrev_b32_e32 v236, 16, v158
	v_and_b32_e32 v237, 0xffff0000, v158
	v_lshlrev_b32_e32 v238, 16, v159
	v_and_b32_e32 v239, 0xffff0000, v159
	v_mul_f32_e32 v232, v232, v216
	v_mul_f32_e32 v233, v233, v216
	v_mul_f32_e32 v234, v234, v216
	v_mul_f32_e32 v235, v235, v216
	v_mul_f32_e32 v236, v236, v216
	v_mul_f32_e32 v237, v237, v216
	v_mul_f32_e32 v238, v238, v216
	v_mul_f32_e32 v239, v239, v216
	v_mul_f32_e32 v232, v232, v168
	v_mul_f32_e32 v233, v233, v169
	v_mul_f32_e32 v234, v234, v170
	v_mul_f32_e32 v235, v235, v171
	v_mul_f32_e32 v236, v236, v172
	v_mul_f32_e32 v237, v237, v173
	v_mul_f32_e32 v238, v238, v174
	v_mul_f32_e32 v239, v239, v175
	ds_bpermute_b32 v240, v193, v232
	ds_bpermute_b32 v241, v193, v233
	ds_bpermute_b32 v242, v193, v234
	ds_bpermute_b32 v243, v193, v235
	ds_bpermute_b32 v244, v193, v236
	ds_bpermute_b32 v245, v193, v237
	ds_bpermute_b32 v246, v193, v238
	ds_bpermute_b32 v247, v193, v239
	s_add_i32 s35, s34, 0x800
	s_and_b32 s35, s35, 0xfff
	v_cvt_f32_u32_e32 v218, s35
	v_mul_f32_e32 v218, 0x3e22f983, v218
	s_waitcnt lgkmcnt(0)
	v_mul_f32_e32 v220, v218, v182
	v_fract_f32_e32 v220, v220
	v_sin_f32_e32 v221, v220
	v_cos_f32_e32 v222, v220
	v_mul_f32_e32 v240, v240, v190
	v_mul_f32_e32 v240, v240, v221
	v_fma_f32 v232, v232, v222, v240
	v_mul_f32_e32 v223, v218, v183
	v_fract_f32_e32 v223, v223
	v_sin_f32_e32 v224, v223
	v_cos_f32_e32 v225, v223
	v_mul_f32_e32 v241, v241, v190
	v_mul_f32_e32 v241, v241, v224
	v_fma_f32 v233, v233, v225, v241
	v_mul_f32_e32 v220, v218, v184
	v_fract_f32_e32 v220, v220
	v_sin_f32_e32 v221, v220
	v_cos_f32_e32 v222, v220
	v_mul_f32_e32 v242, v242, v190
	v_mul_f32_e32 v242, v242, v221
	v_fma_f32 v234, v234, v222, v242
	v_mul_f32_e32 v223, v218, v185
	v_fract_f32_e32 v223, v223
	v_sin_f32_e32 v224, v223
	v_cos_f32_e32 v225, v223
	v_mul_f32_e32 v243, v243, v190
	v_mul_f32_e32 v243, v243, v224
	v_fma_f32 v235, v235, v225, v243
	v_mul_f32_e32 v220, v218, v186
	v_fract_f32_e32 v220, v220
	v_sin_f32_e32 v221, v220
	v_cos_f32_e32 v222, v220
	v_mul_f32_e32 v244, v244, v190
	v_mul_f32_e32 v244, v244, v221
	v_fma_f32 v236, v236, v222, v244
	v_mul_f32_e32 v223, v218, v187
	v_fract_f32_e32 v223, v223
	v_sin_f32_e32 v224, v223
	v_cos_f32_e32 v225, v223
	v_mul_f32_e32 v245, v245, v190
	v_mul_f32_e32 v245, v245, v224
	v_fma_f32 v237, v237, v225, v245
	v_mul_f32_e32 v220, v218, v188
	v_fract_f32_e32 v220, v220
	v_sin_f32_e32 v221, v220
	v_cos_f32_e32 v222, v220
	v_mul_f32_e32 v246, v246, v190
	v_mul_f32_e32 v246, v246, v221
	v_fma_f32 v238, v238, v222, v246
	v_mul_f32_e32 v223, v218, v189
	v_fract_f32_e32 v223, v223
	v_sin_f32_e32 v224, v223
	v_cos_f32_e32 v225, v223
	v_mul_f32_e32 v247, v247, v190
	v_mul_f32_e32 v247, v247, v224
	v_fma_f32 v239, v239, v225, v247
	v_cvt_pk_bf16_f32 v156, v232, v233
	v_cvt_pk_bf16_f32 v157, v234, v235
	v_cvt_pk_bf16_f32 v158, v236, v237
	v_cvt_pk_bf16_f32 v159, v238, v239
	s_add_u32 s36, s28, 0x440000
	s_addc_u32 s37, s29, 0
	s_mov_b64 exec, 0xff
	global_store_dwordx4 v196, v[156:159], s[36:37]
	s_mov_b64 exec, -1
	s_branch .LBB0_1504
; DI int otid() { int t = threadIdx.x; asm volatile("" : "+v"(t)); return t; }
; DI void phase_mla_qk(const Params& p) {
;     bf16_t* qkv = (bf16_t*)(p.ws + ACT); bf16_t* lat = (bf16_t*)(p.ws + LAT); const float* qkg = p.in[27];
;     const int tid = otid(), lane = tid & 63, gw = blockIdx.x * 8 + (tid >> 6), nw = gridDim.x * 8;
;     const int l16 = lane & 15, l8 = lane & 7;
;     float gk[8], gkr[8];
; #pragma unroll
;     for (int e = 0; e < 8; ++e) { gk[e] = qkg[192 + l16 * 8 + e]; gkr[e] = qkg[192 + 128 + l8 * 8 + e]; }
;     float inv[8];
; #pragma unroll
;     for (int e = 0; e < 8; ++e) inv[e] = powf(10000.f, -(float)((l8 & 3) * 8 + e) * (1.f / 32.f));
.Lmq_orig:
	s_movk_i32 s3, 0x4000
	v_ashrrev_i32_e32 v0, 6, v21
	v_add_u32_e32 v17, s63, v0
	v_cmp_gt_i32_e32 vcc, s3, v17
	s_and_saveexec_b64 s[24:25], vcc
	s_cbranch_execz .LBB0_1504
	s_load_dwordx2 s[12:13], s[0:1], 0xd8
	s_load_dwordx2 s[10:11], s[0:1], 0xf0
	v_lshlrev_b32_e32 v8, 3, v21
	v_and_b32_e32 v16, 0x78, v8
	v_and_b32_e32 v14, 24, v8
	v_lshlrev_b32_e32 v9, 2, v16
	v_or_b32_e32 v8, 1, v14
	s_waitcnt lgkmcnt(0)
	global_load_dwordx4 v[0:3], v9, s[12:13] offset:784
	global_load_dwordx4 v[4:7], v9, s[12:13] offset:768
	v_cvt_f32_ubyte0_e32 v9, v14
	v_cvt_f32_ubyte0_e32 v8, v8
	s_mov_b32 s14, 0xbd000000
	v_pk_mul_f32 v[8:9], v[8:9], s[14:15] op_sel_hi:[1,0]
	v_mov_b32_e32 v11, 0x461c4000
	v_cmp_eq_f32_e32 vcc, 0, v9
	s_mov_b32 s16, 0x3f2aaaab
	s_mov_b32 s15, 0x3f317218
	v_cndmask_b32_e64 v15, v11, 1.0, vcc
	v_frexp_mant_f32_e32 v10, v15
	v_cmp_gt_f32_e64 s[6:7], s16, v10
	s_mov_b32 s17, 0x42b17218
	s_mov_b32 s31, 0x3fb8aa3b
	v_cndmask_b32_e64 v12, 1.0, 2.0, s[6:7]
	v_mul_f32_e32 v10, v10, v12
	v_add_f32_e32 v12, 1.0, v10
	v_rcp_f32_e32 v26, v12
	v_add_f32_e32 v13, -1.0, v12
	v_sub_f32_e32 v19, v10, v13
	v_add_f32_e32 v13, -1.0, v10
	v_mul_f32_e32 v10, v13, v26
	v_mul_f32_e32 v18, v12, v10
	v_fma_f32 v22, v10, v12, -v18
	v_fmac_f32_e32 v22, v10, v19
	v_add_f32_e32 v12, v18, v22
	v_sub_f32_e32 v19, v13, v12
	v_pk_add_f32 v[24:25], v[12:13], v[18:19] neg_lo:[0,1] neg_hi:[0,1]
	v_mov_b32_e32 v23, v12
	v_pk_add_f32 v[12:13], v[24:25], v[22:23] neg_lo:[0,1] neg_hi:[0,1]
	s_mov_b32 s28, 0x7f800000
	v_add_f32_e32 v12, v12, v13
	v_add_f32_e32 v12, v19, v12
	v_mul_f32_e32 v12, v26, v12
	v_add_f32_e32 v18, v10, v12
	v_sub_f32_e32 v10, v18, v10
	v_sub_f32_e32 v13, v12, v10
	v_mul_f32_e32 v19, v18, v18
	v_fma_f32 v23, v18, v18, -v19
	v_add_f32_e32 v10, v13, v13
	v_fmac_f32_e32 v23, v18, v10
	v_add_f32_e32 v22, v19, v23
	v_mov_b32_e32 v12, 0x3e91f4c4
	v_fmamk_f32 v24, v22, 0x3e76c4e1, v12
	v_fmaak_f32 v24, v22, v24, 0x3ecccdef
	v_sub_f32_e32 v19, v22, v19
	v_sub_f32_e32 v30, v23, v19
	v_mul_f32_e32 v19, v22, v24
	v_fma_f32 v23, v22, v24, -v19
	v_fmac_f32_e32 v23, v30, v24
	v_add_f32_e32 v24, v19, v23
	v_add_f32_e32 v25, 0x3f2aaaaa, v24
	v_sub_f32_e32 v19, v24, v19
	v_sub_f32_e32 v19, v23, v19
	v_add_f32_e32 v23, 0xbf2aaaaa, v25
	v_add_f32_e32 v19, 0x31739010, v19
	v_sub_f32_e32 v23, v24, v23
	v_pk_mul_f32 v[26:27], v[18:19], v[22:23]
	v_pk_add_f32 v[28:29], v[18:19], v[22:23]
	v_fma_f32 v24, v22, v18, -v26
	v_fmac_f32_e32 v24, v22, v13
	v_mov_b32_e32 v27, v29
	v_fmac_f32_e32 v24, v30, v18
	v_pk_add_f32 v[22:23], v[26:27], v[24:25]
	v_ldexp_f32 v13, v13, 1
	v_sub_f32_e32 v19, v22, v26
	v_sub_f32_e32 v19, v24, v19
	v_sub_f32_e32 v24, v25, v23
	v_add_f32_e32 v27, v29, v24
	v_cvt_f64_f32_e32 v[28:29], v15
	v_frexp_exp_i32_f64_e32 v15, v[28:29]
	v_subbrev_co_u32_e64 v15, s[6:7], 0, v15, s[6:7]
	v_cvt_f32_i32_e32 v15, v15
	v_pk_mul_f32 v[24:25], v[22:23], v[22:23] op_sel:[0,1] op_sel_hi:[1,0]
	v_ldexp_f32 v29, v18, 1
	v_fma_f32 v26, v22, v23, -v24
	v_fmac_f32_e32 v26, v22, v27
	v_mul_f32_e32 v22, 0x3f317218, v15
	v_fmac_f32_e32 v26, v19, v23
	v_fma_f32 v28, v15, s15, -v22
	v_fmac_f32_e32 v28, 0xb102e308, v15
	v_add_f32_e32 v23, v24, v26
	v_pk_add_f32 v[18:19], v[22:23], v[28:29]
	v_mov_b32_e32 v30, v23
	v_mov_b32_e32 v31, v19
	v_mov_b32_e32 v25, v29
	v_pk_add_f32 v[24:25], v[30:31], v[24:25] neg_lo:[0,1] neg_hi:[0,1]
	v_mov_b32_e32 v27, v23
	v_pk_add_f32 v[24:25], v[26:27], v[24:25] neg_lo:[0,1] neg_hi:[0,1]
	v_mov_b32_e32 v29, v18
	v_add_f32_e32 v13, v13, v24
	v_add_f32_e32 v23, v13, v25
	v_pk_add_f32 v[24:25], v[18:19], v[22:23] neg_lo:[0,1] neg_hi:[0,1]
	v_pk_add_f32 v[26:27], v[18:19], v[22:23]
	v_cmp_eq_f32_e64 s[6:7], 0, v8
	v_mov_b32_e32 v25, v27
	v_pk_add_f32 v[30:31], v[28:29], v[24:25] neg_lo:[0,1] neg_hi:[0,1]
	v_pk_add_f32 v[24:25], v[28:29], v[24:25]
	v_cndmask_b32_e64 v13, v11, 1.0, s[6:7]
	v_pk_add_f32 v[28:29], v[24:25], v[18:19] op_sel:[1,0] op_sel_hi:[0,1] neg_lo:[0,1] neg_hi:[0,1]
	v_pk_add_f32 v[32:33], v[26:27], v[28:29] op_sel_hi:[1,0] neg_lo:[0,1] neg_hi:[0,1]
	v_mov_b32_e32 v24, v27
	v_pk_mov_b32 v[26:27], v[18:19], v[28:29] op_sel:[1,0]
	v_mov_b32_e32 v22, v23
	v_pk_add_f32 v[26:27], v[24:25], v[26:27] neg_lo:[0,1] neg_hi:[0,1]
	v_mov_b32_e32 v23, v18
	v_frexp_mant_f32_e32 v15, v13
	v_pk_add_f32 v[18:19], v[22:23], v[26:27] neg_lo:[0,1] neg_hi:[0,1]
	v_mov_b32_e32 v32, v30
	v_cmp_gt_f32_e64 s[8:9], s16, v15
	v_pk_add_f32 v[22:23], v[32:33], v[18:19]
	v_mov_b32_e32 v31, v25
	v_cndmask_b32_e64 v19, 1.0, 2.0, s[8:9]
	v_mul_f32_e32 v15, v15, v19
	v_add_f32_e32 v19, 1.0, v15
	v_rcp_f32_e32 v24, v19
	v_add_f32_e32 v26, -1.0, v19
	v_add_f32_e32 v27, -1.0, v15
	v_sub_f32_e32 v26, v15, v26
	v_mul_f32_e32 v15, v27, v24
	v_mul_f32_e32 v28, v19, v15
	v_fma_f32 v32, v15, v19, -v28
	v_fmac_f32_e32 v32, v15, v26
	v_add_f32_e32 v26, v28, v32
	v_sub_f32_e32 v29, v27, v26
	v_pk_add_f32 v[34:35], v[26:27], v[28:29] neg_lo:[0,1] neg_hi:[0,1]
	v_mov_b32_e32 v33, v26
	v_pk_add_f32 v[26:27], v[34:35], v[32:33] neg_lo:[0,1] neg_hi:[0,1]
	s_mov_b32 s30, 0xc2ce8ed0
	v_add_f32_e32 v19, v26, v27
	v_add_f32_e32 v19, v29, v19
	v_mul_f32_e32 v19, v24, v19
	v_add_f32_e32 v26, v15, v19
	v_sub_f32_e32 v15, v26, v15
	v_sub_f32_e32 v15, v19, v15
	v_mul_f32_e32 v19, v26, v26
	v_fma_f32 v24, v26, v26, -v19
	v_add_f32_e32 v27, v15, v15
	v_fmac_f32_e32 v24, v26, v27
	v_add_f32_e32 v28, v19, v24
	v_fmamk_f32 v27, v28, 0x3e76c4e1, v12
	v_fmaak_f32 v27, v28, v27, 0x3ecccdef
	v_sub_f32_e32 v19, v28, v19
	v_sub_f32_e32 v19, v24, v19
	v_mul_f32_e32 v24, v28, v27
	v_fma_f32 v29, v28, v27, -v24
	v_fmac_f32_e32 v29, v19, v27
	v_add_f32_e32 v32, v24, v29
	v_sub_f32_e32 v24, v32, v24
; DI void phase_mla_qk(const Params& p) {
;     ...
;     float inv[8];
; #pragma unroll
;     for (int e = 0; e < 8; ++e) inv[e] = powf(10000.f, -(float)((l8 & 3) * 8 + e) * (1.f / 32.f));
	v_add_f32_e32 v33, 0x3f2aaaaa, v32
	v_sub_f32_e32 v24, v29, v24
	v_add_f32_e32 v27, 0x31739010, v24
	v_add_f32_e32 v24, 0xbf2aaaaa, v33
	v_sub_f32_e32 v29, v32, v24
	v_pk_mul_f32 v[34:35], v[26:27], v[28:29]
	v_pk_add_f32 v[36:37], v[26:27], v[28:29]
	v_fma_f32 v32, v28, v26, -v34
	v_fmac_f32_e32 v32, v28, v15
	v_mov_b32_e32 v35, v37
	v_fmac_f32_e32 v32, v19, v26
	v_pk_add_f32 v[28:29], v[34:35], v[32:33]
	s_movk_i32 s29, 0x204
	v_sub_f32_e32 v19, v28, v34
	v_cvt_f64_f32_e32 v[34:35], v13
	v_frexp_exp_i32_f64_e32 v13, v[34:35]
	v_subbrev_co_u32_e64 v13, s[8:9], 0, v13, s[8:9]
	v_cvt_f32_i32_e32 v13, v13
	v_sub_f32_e32 v19, v32, v19
	v_sub_f32_e32 v24, v33, v29
	v_pk_mul_f32 v[32:33], v[28:29], v[28:29] op_sel:[0,1] op_sel_hi:[1,0]
	v_add_f32_e32 v24, v37, v24
	v_fma_f32 v34, v28, v29, -v32
	v_fmac_f32_e32 v34, v28, v24
	v_mul_f32_e32 v28, 0x3f317218, v13
	v_fmac_f32_e32 v34, v19, v29
	v_fma_f32 v36, v13, s15, -v28
	v_fmac_f32_e32 v36, 0xb102e308, v13
	v_ldexp_f32 v37, v26, 1
	v_add_f32_e32 v29, v32, v34
	v_pk_add_f32 v[26:27], v[28:29], v[36:37]
	v_mov_b32_e32 v38, v29
	v_mov_b32_e32 v39, v27
	v_mov_b32_e32 v33, v37
	v_pk_add_f32 v[32:33], v[38:39], v[32:33] neg_lo:[0,1] neg_hi:[0,1]
	v_mov_b32_e32 v35, v29
	v_ldexp_f32 v13, v15, 1
	v_pk_add_f32 v[32:33], v[34:35], v[32:33] neg_lo:[0,1] neg_hi:[0,1]
	v_mov_b32_e32 v37, v26
	v_add_f32_e32 v13, v13, v32
	v_add_f32_e32 v29, v13, v33
	v_pk_add_f32 v[32:33], v[26:27], v[28:29] neg_lo:[0,1] neg_hi:[0,1]
	v_pk_add_f32 v[34:35], v[26:27], v[28:29]
	v_mov_b32_e32 v28, v29
	v_mov_b32_e32 v33, v35
	v_pk_add_f32 v[38:39], v[36:37], v[32:33] neg_lo:[0,1] neg_hi:[0,1]
	v_pk_add_f32 v[32:33], v[36:37], v[32:33]
	v_mov_b32_e32 v29, v26
	v_pk_add_f32 v[36:37], v[32:33], v[26:27] op_sel:[1,0] op_sel_hi:[0,1] neg_lo:[0,1] neg_hi:[0,1]
	v_pk_add_f32 v[40:41], v[34:35], v[36:37] op_sel_hi:[1,0] neg_lo:[0,1] neg_hi:[0,1]
	v_mov_b32_e32 v32, v35
	v_pk_mov_b32 v[34:35], v[26:27], v[36:37] op_sel:[1,0]
	v_mov_b32_e32 v40, v38
	v_pk_add_f32 v[34:35], v[32:33], v[34:35] neg_lo:[0,1] neg_hi:[0,1]
	v_mov_b32_e32 v37, v23
	v_pk_add_f32 v[26:27], v[28:29], v[34:35] neg_lo:[0,1] neg_hi:[0,1]
	v_mov_b32_e32 v35, v22
	v_pk_add_f32 v[28:29], v[40:41], v[26:27]
	v_mov_b32_e32 v24, v33
	v_mov_b32_e32 v34, v28
	v_mov_b32_e32 v36, v29
	v_pk_add_f32 v[36:37], v[34:35], v[36:37]
	v_mov_b32_e32 v39, v33
	v_pk_add_f32 v[24:25], v[24:25], v[36:37]
	v_mov_b32_e32 v19, v37
	v_mov_b32_e32 v23, v25
	v_mov_b32_e32 v29, v24
	v_pk_add_f32 v[22:23], v[22:23], v[30:31] neg_lo:[0,1] neg_hi:[0,1]
	v_pk_add_f32 v[28:29], v[28:29], v[38:39] neg_lo:[0,1] neg_hi:[0,1]
	v_mov_b32_e32 v33, v22
	v_mov_b32_e32 v32, v28
	v_mov_b32_e32 v27, v36
	v_pk_add_f32 v[18:19], v[18:19], v[22:23] neg_lo:[0,1] neg_hi:[0,1]
	v_pk_add_f32 v[22:23], v[34:35], v[32:33] neg_lo:[0,1] neg_hi:[0,1]
	v_mov_b32_e32 v39, v30
	v_pk_add_f32 v[26:27], v[26:27], v[28:29] neg_lo:[0,1] neg_hi:[0,1]
	v_pk_add_f32 v[22:23], v[38:39], v[22:23] neg_lo:[0,1] neg_hi:[0,1]
	v_mov_b32_e32 v28, v26
	v_mov_b32_e32 v29, v18
	v_pk_add_f32 v[22:23], v[28:29], v[22:23]
	v_mov_b32_e32 v18, v27
	v_pk_add_f32 v[18:19], v[22:23], v[18:19]
	v_mov_b32_e32 v15, 0x204
	v_pk_add_f32 v[22:23], v[24:25], v[18:19]
	v_mov_b32_e32 v13, 0x37000000
	v_pk_add_f32 v[24:25], v[22:23], v[24:25] neg_lo:[0,1] neg_hi:[0,1]
	v_mov_b32_e32 v10, 0x3ecccdef
	v_pk_add_f32 v[18:19], v[18:19], v[24:25] neg_lo:[0,1] neg_hi:[0,1]
	v_pk_mul_f32 v[24:25], v[8:9], v[22:23]
	v_and_b32_e32 v20, 7, v21
	v_pk_fma_f32 v[22:23], v[8:9], v[22:23], v[24:25] neg_lo:[0,0,1] neg_hi:[0,0,1]
	v_cmp_class_f32_e64 s[8:9], v24, v15
	v_pk_fma_f32 v[18:19], v[8:9], v[18:19], v[22:23]
	v_mov_b32_e32 v45, 0
	v_pk_add_f32 v[22:23], v[24:25], v[18:19]
	s_add_u32 s26, s10, 0xbf00000
	v_pk_add_f32 v[26:27], v[22:23], v[24:25] neg_lo:[0,1] neg_hi:[0,1]
	v_cndmask_b32_e64 v24, v22, v24, s[8:9]
	v_cmp_class_f32_e64 s[8:9], v25, v15
	v_pk_add_f32 v[18:19], v[18:19], v[26:27] neg_lo:[0,1] neg_hi:[0,1]
	v_lshlrev_b32_e32 v44, 4, v20
	v_cndmask_b32_e64 v22, v23, v25, s[8:9]
	v_cmp_eq_f32_e64 s[8:9], s17, v22
	s_addc_u32 s27, s11, 0
	v_lshl_add_u64 v[46:47], s[10:11], 0, v[44:45]
	v_cndmask_b32_e64 v23, 0, v13, s[8:9]
	v_sub_f32_e32 v25, v22, v23
	v_mul_f32_e32 v26, 0x3fb8aa3b, v25
	v_fma_f32 v27, v25, s31, -v26
	v_rndne_f32_e32 v28, v26
	v_fmac_f32_e32 v27, 0x32a5705f, v25
	v_sub_f32_e32 v26, v26, v28
	v_add_f32_e32 v26, v26, v27
	v_exp_f32_e32 v26, v26
	v_cvt_i32_f32_e32 v27, v28
	v_cmp_neq_f32_e64 s[8:9], |v22|, s28
	s_movk_i32 s35, 0x3800
	v_lshlrev_b32_e32 v44, 1, v16
	v_cndmask_b32_e64 v19, 0, v19, s[8:9]
	v_ldexp_f32 v22, v26, v27
	v_cmp_ngt_f32_e64 s[8:9], s30, v25
	v_add_f32_e32 v19, v23, v19
	s_movk_i32 s37, 0x880
	v_cndmask_b32_e64 v23, 0, v22, s[8:9]
	v_mov_b32_e32 v22, 0x7f800000
	v_cmp_nlt_f32_e64 s[8:9], s17, v25
	v_mov_b32_e32 v90, 0x358637bd
	s_brev_b32 s34, 60
	v_cndmask_b32_e64 v23, v22, v23, s[8:9]
	v_fma_f32 v19, v23, v19, v23
	v_cmp_class_f32_e64 s[8:9], v23, s29
	s_mov_b32 s42, 0x800000
	s_mov_b32 s36, 0x358637bd
	v_cndmask_b32_e64 v19, v19, v23, s[8:9]
	v_cmp_neq_f32_e64 s[8:9], v9, |v9|
	s_mov_b32 s38, 0x3c800000
	s_brev_b32 s43, 18
	v_cndmask_b32_e64 v23, v22, 0, s[8:9]
	v_cndmask_b32_e64 v23, v23, 1.0, vcc
	v_cmp_eq_f32_e32 vcc, s17, v24
	v_cmp_class_f32_e64 s[8:9], v9, s29
	s_mov_b32 s44, 0xfe5163ab
	v_cndmask_b32_e32 v9, 0, v13, vcc
	v_cndmask_b32_e64 v78, |v19|, v23, s[8:9]
	v_sub_f32_e32 v19, v24, v9
	v_mul_f32_e32 v23, 0x3fb8aa3b, v19
	v_fma_f32 v25, v19, s31, -v23
	v_rndne_f32_e32 v26, v23
	v_fmac_f32_e32 v25, 0x32a5705f, v19
	v_sub_f32_e32 v23, v23, v26
	v_add_f32_e32 v23, v23, v25
	v_exp_f32_e32 v23, v23
	v_cvt_i32_f32_e32 v25, v26
; DI void phase_mla_qk(const Params& p) {
;     ...
;     float inv[8];
; #pragma unroll
;     for (int e = 0; e < 8; ++e) inv[e] = powf(10000.f, -(float)((l8 & 3) * 8 + e) * (1.f / 32.f));
	v_cmp_neq_f32_e64 vcc, |v24|, s28
	v_cmp_neq_f32_e64 s[8:9], v8, |v8|
	s_mov_b32 s45, 0x3c439041
	v_cndmask_b32_e32 v18, 0, v18, vcc
	v_add_f32_e32 v9, v9, v18
	v_ldexp_f32 v18, v23, v25
	v_cmp_ngt_f32_e32 vcc, s30, v19
	s_mov_b32 s46, 0xdb629599
	s_mov_b32 s47, 0xf534ddc0
	v_cndmask_b32_e32 v18, 0, v18, vcc
	v_cmp_nlt_f32_e32 vcc, s17, v19
	s_mov_b32 s48, 0xfc2757d1
	s_mov_b32 s49, 0x4e441529
	v_cndmask_b32_e32 v18, v22, v18, vcc
	v_fma_f32 v9, v18, v9, v18
	v_cmp_class_f32_e64 vcc, v18, s29
	s_mov_b32 s50, 0xa2f9836e
	s_mov_b32 s51, 0x3fc90fda
	v_cndmask_b32_e32 v9, v9, v18, vcc
	v_cndmask_b32_e64 v18, v22, 0, s[8:9]
	v_cndmask_b32_e64 v18, v18, 1.0, s[6:7]
	v_cmp_class_f32_e64 s[6:7], v8, s29
	v_or_b32_e32 v8, 2, v14
	s_mov_b32 s52, 0x3f22f983
	v_cndmask_b32_e64 v79, |v9|, v18, s[6:7]
	v_or_b32_e32 v18, 3, v14
	v_cvt_f32_ubyte0_e32 v9, v8
	v_cvt_f32_ubyte0_e32 v8, v18
	v_pk_mul_f32 v[8:9], v[8:9], s[14:15] op_sel_hi:[1,0]
	s_mov_b32 s53, 0xbfc90fda
	v_cmp_eq_f32_e32 vcc, 0, v9
	v_mov_b32_e32 v91, 0x3c0881c4
	v_mov_b32_e32 v92, 0xbab64f3b
	v_cndmask_b32_e64 v23, v11, 1.0, vcc
	v_frexp_mant_f32_e32 v18, v23
	v_cmp_gt_f32_e64 s[6:7], s16, v18
	s_brev_b32 s54, 1
	s_movk_i32 s55, 0x1f8
	v_cndmask_b32_e64 v19, 1.0, 2.0, s[6:7]
	v_mul_f32_e32 v18, v18, v19
	v_add_f32_e32 v25, 1.0, v18
	v_rcp_f32_e32 v30, v25
	v_add_f32_e32 v19, -1.0, v25
	v_sub_f32_e32 v27, v18, v19
	v_add_f32_e32 v19, -1.0, v18
	v_mul_f32_e32 v31, v19, v30
	v_mul_f32_e32 v24, v25, v31
	v_fma_f32 v26, v31, v25, -v24
	v_fmac_f32_e32 v26, v31, v27
	v_add_f32_e32 v18, v24, v26
	v_sub_f32_e32 v25, v19, v18
	v_pk_add_f32 v[28:29], v[18:19], v[24:25] neg_lo:[0,1] neg_hi:[0,1]
	v_mov_b32_e32 v27, v18
	v_pk_add_f32 v[18:19], v[28:29], v[26:27] neg_lo:[0,1] neg_hi:[0,1]
	s_movk_i32 s56, 0x3fff
	v_add_f32_e32 v18, v18, v19
	v_add_f32_e32 v18, v25, v18
	v_mul_f32_e32 v19, v30, v18
	v_add_f32_e32 v18, v31, v19
	v_sub_f32_e32 v24, v18, v31
	v_sub_f32_e32 v32, v19, v24
	v_mul_f32_e32 v19, v18, v18
	v_fma_f32 v25, v18, v18, -v19
	v_add_f32_e32 v24, v32, v32
	v_fmac_f32_e32 v25, v18, v24
	v_add_f32_e32 v24, v19, v25
	v_fmamk_f32 v26, v24, 0x3e76c4e1, v12
	v_fmaak_f32 v26, v24, v26, 0x3ecccdef
	v_sub_f32_e32 v19, v24, v19
	v_sub_f32_e32 v33, v25, v19
	v_mul_f32_e32 v19, v24, v26
	v_fma_f32 v25, v24, v26, -v19
	v_fmac_f32_e32 v25, v33, v26
	v_add_f32_e32 v26, v19, v25
	v_add_f32_e32 v27, 0x3f2aaaaa, v26
	v_sub_f32_e32 v19, v26, v19
	v_sub_f32_e32 v19, v25, v19
	v_add_f32_e32 v25, 0xbf2aaaaa, v27
	v_add_f32_e32 v19, 0x31739010, v19
	v_sub_f32_e32 v25, v26, v25
	v_pk_mul_f32 v[28:29], v[18:19], v[24:25]
	v_pk_add_f32 v[30:31], v[18:19], v[24:25]
	v_fma_f32 v26, v24, v18, -v28
	v_fmac_f32_e32 v26, v24, v32
	v_mov_b32_e32 v29, v31
	v_fmac_f32_e32 v26, v33, v18
	v_pk_add_f32 v[24:25], v[28:29], v[26:27]
	v_not_b32_e32 v93, 63
	v_sub_f32_e32 v19, v24, v28
	v_cvt_f64_f32_e32 v[28:29], v23
	v_frexp_exp_i32_f64_e32 v23, v[28:29]
	v_subbrev_co_u32_e64 v23, s[6:7], 0, v23, s[6:7]
	v_cvt_f32_i32_e32 v23, v23
	v_sub_f32_e32 v19, v26, v19
	v_sub_f32_e32 v26, v27, v25
	v_add_f32_e32 v30, v31, v26
	v_pk_mul_f32 v[26:27], v[24:25], v[24:25] op_sel:[0,1] op_sel_hi:[1,0]
	v_ldexp_f32 v31, v18, 1
	v_fma_f32 v28, v24, v25, -v26
	v_fmac_f32_e32 v28, v24, v30
	v_mul_f32_e32 v24, 0x3f317218, v23
	v_fmac_f32_e32 v28, v19, v25
	v_fma_f32 v30, v23, s15, -v24
	v_fmac_f32_e32 v30, 0xb102e308, v23
	v_add_f32_e32 v25, v26, v28
	v_pk_add_f32 v[18:19], v[24:25], v[30:31]
	v_ldexp_f32 v23, v32, 1
	v_mov_b32_e32 v32, v25
	v_mov_b32_e32 v33, v19
	v_mov_b32_e32 v27, v31
	v_pk_add_f32 v[26:27], v[32:33], v[26:27] neg_lo:[0,1] neg_hi:[0,1]
	v_mov_b32_e32 v29, v25
	v_pk_add_f32 v[26:27], v[28:29], v[26:27] neg_lo:[0,1] neg_hi:[0,1]
	v_mov_b32_e32 v31, v18
	v_add_f32_e32 v23, v23, v26
	v_add_f32_e32 v25, v23, v27
	v_pk_add_f32 v[26:27], v[18:19], v[24:25] neg_lo:[0,1] neg_hi:[0,1]
	v_pk_add_f32 v[28:29], v[18:19], v[24:25]
	v_mov_b32_e32 v24, v25
	v_mov_b32_e32 v27, v29
	v_pk_add_f32 v[32:33], v[30:31], v[26:27] neg_lo:[0,1] neg_hi:[0,1]
	v_pk_add_f32 v[26:27], v[30:31], v[26:27]
	v_mov_b32_e32 v25, v18
	v_pk_add_f32 v[30:31], v[26:27], v[18:19] op_sel:[1,0] op_sel_hi:[0,1] neg_lo:[0,1] neg_hi:[0,1]
	v_pk_add_f32 v[34:35], v[28:29], v[30:31] op_sel_hi:[1,0] neg_lo:[0,1] neg_hi:[0,1]
	v_mov_b32_e32 v26, v29
	v_pk_mov_b32 v[28:29], v[18:19], v[30:31] op_sel:[1,0]
	v_mov_b32_e32 v34, v32
	v_pk_add_f32 v[28:29], v[26:27], v[28:29] neg_lo:[0,1] neg_hi:[0,1]
	v_cmp_eq_f32_e64 s[6:7], 0, v8
	v_pk_add_f32 v[18:19], v[24:25], v[28:29] neg_lo:[0,1] neg_hi:[0,1]
	v_mov_b32_e32 v33, v27
	v_pk_add_f32 v[24:25], v[34:35], v[18:19]
	v_cndmask_b32_e64 v19, v11, 1.0, s[6:7]
	v_frexp_mant_f32_e32 v23, v19
	v_cmp_gt_f32_e64 s[8:9], s16, v23
	v_not_b32_e32 v94, 31
	v_mov_b32_e32 v95, 0x7fc00000
	v_cndmask_b32_e64 v26, 1.0, 2.0, s[8:9]
	v_mul_f32_e32 v23, v23, v26
	v_add_f32_e32 v26, 1.0, v23
	v_rcp_f32_e32 v38, v26
	v_add_f32_e32 v28, -1.0, v26
	v_add_f32_e32 v29, -1.0, v23
	v_sub_f32_e32 v28, v23, v28
	v_mul_f32_e32 v23, v29, v38
	v_mul_f32_e32 v30, v26, v23
	v_fma_f32 v34, v23, v26, -v30
	v_fmac_f32_e32 v34, v23, v28
	v_add_f32_e32 v28, v30, v34
	v_sub_f32_e32 v31, v29, v28
	v_pk_add_f32 v[36:37], v[28:29], v[30:31] neg_lo:[0,1] neg_hi:[0,1]
	v_mov_b32_e32 v35, v28
	v_pk_add_f32 v[28:29], v[36:37], v[34:35] neg_lo:[0,1] neg_hi:[0,1]
	s_nop 0
	v_add_f32_e32 v26, v28, v29
	v_add_f32_e32 v26, v31, v26
	v_mul_f32_e32 v26, v38, v26
	v_add_f32_e32 v28, v23, v26
	v_sub_f32_e32 v23, v28, v23
	v_sub_f32_e32 v23, v26, v23
	v_mul_f32_e32 v26, v28, v28
	v_fma_f32 v29, v28, v28, -v26
	v_add_f32_e32 v30, v23, v23
	v_fmac_f32_e32 v29, v28, v30
	v_add_f32_e32 v30, v26, v29
; DI void phase_mla_qk(const Params& p) {
;     ...
;     float inv[8];
; #pragma unroll
;     for (int e = 0; e < 8; ++e) inv[e] = powf(10000.f, -(float)((l8 & 3) * 8 + e) * (1.f / 32.f));
	v_fmamk_f32 v31, v30, 0x3e76c4e1, v12
	v_fmaak_f32 v31, v30, v31, 0x3ecccdef
	v_sub_f32_e32 v26, v30, v26
	v_sub_f32_e32 v26, v29, v26
	v_mul_f32_e32 v29, v30, v31
	v_fma_f32 v34, v30, v31, -v29
	v_fmac_f32_e32 v34, v26, v31
	v_add_f32_e32 v31, v29, v34
	v_add_f32_e32 v35, 0x3f2aaaaa, v31
	v_sub_f32_e32 v29, v31, v29
	v_sub_f32_e32 v29, v34, v29
	v_add_f32_e32 v34, 0xbf2aaaaa, v35
	v_add_f32_e32 v29, 0x31739010, v29
	v_sub_f32_e32 v31, v31, v34
	v_pk_mul_f32 v[36:37], v[28:29], v[30:31]
	v_pk_add_f32 v[38:39], v[28:29], v[30:31]
	v_fma_f32 v34, v30, v28, -v36
	v_fmac_f32_e32 v34, v30, v23
	v_mov_b32_e32 v37, v39
	v_fmac_f32_e32 v34, v26, v28
	v_pk_add_f32 v[30:31], v[36:37], v[34:35]
	s_nop 0
	v_sub_f32_e32 v26, v30, v36
	v_cvt_f64_f32_e32 v[36:37], v19
	v_frexp_exp_i32_f64_e32 v19, v[36:37]
	v_subbrev_co_u32_e64 v19, s[8:9], 0, v19, s[8:9]
	v_cvt_f32_i32_e32 v19, v19
	v_sub_f32_e32 v26, v34, v26
	v_sub_f32_e32 v29, v35, v31
	v_pk_mul_f32 v[34:35], v[30:31], v[30:31] op_sel:[0,1] op_sel_hi:[1,0]
	v_add_f32_e32 v29, v39, v29
	v_fma_f32 v36, v30, v31, -v34
	v_fmac_f32_e32 v36, v30, v29
	v_mul_f32_e32 v30, 0x3f317218, v19
	v_fmac_f32_e32 v36, v26, v31
	v_fma_f32 v38, v19, s15, -v30
	v_fmac_f32_e32 v38, 0xb102e308, v19
	v_ldexp_f32 v39, v28, 1
	v_add_f32_e32 v31, v34, v36
	v_pk_add_f32 v[28:29], v[30:31], v[38:39]
	v_mov_b32_e32 v40, v31
	v_mov_b32_e32 v41, v29
	v_mov_b32_e32 v35, v39
	v_pk_add_f32 v[34:35], v[40:41], v[34:35] neg_lo:[0,1] neg_hi:[0,1]
	v_mov_b32_e32 v37, v31
	v_ldexp_f32 v19, v23, 1
	v_pk_add_f32 v[34:35], v[36:37], v[34:35] neg_lo:[0,1] neg_hi:[0,1]
	v_mov_b32_e32 v39, v28
	v_add_f32_e32 v19, v19, v34
	v_add_f32_e32 v31, v19, v35
	v_pk_add_f32 v[34:35], v[28:29], v[30:31] neg_lo:[0,1] neg_hi:[0,1]
	v_pk_add_f32 v[36:37], v[28:29], v[30:31]
	v_mov_b32_e32 v30, v31
	v_mov_b32_e32 v35, v37
	v_pk_add_f32 v[40:41], v[38:39], v[34:35] neg_lo:[0,1] neg_hi:[0,1]
	v_pk_add_f32 v[34:35], v[38:39], v[34:35]
	v_mov_b32_e32 v31, v28
	v_pk_add_f32 v[38:39], v[34:35], v[28:29] op_sel:[1,0] op_sel_hi:[0,1] neg_lo:[0,1] neg_hi:[0,1]
	v_pk_add_f32 v[42:43], v[36:37], v[38:39] op_sel_hi:[1,0] neg_lo:[0,1] neg_hi:[0,1]
	v_mov_b32_e32 v34, v37
	v_pk_mov_b32 v[36:37], v[28:29], v[38:39] op_sel:[1,0]
	v_mov_b32_e32 v42, v40
	v_pk_add_f32 v[36:37], v[34:35], v[36:37] neg_lo:[0,1] neg_hi:[0,1]
	v_mov_b32_e32 v39, v25
	v_pk_add_f32 v[28:29], v[30:31], v[36:37] neg_lo:[0,1] neg_hi:[0,1]
	v_mov_b32_e32 v37, v24
	v_pk_add_f32 v[30:31], v[42:43], v[28:29]
	v_mov_b32_e32 v26, v35
	v_mov_b32_e32 v36, v30
	v_mov_b32_e32 v38, v31
	v_pk_add_f32 v[38:39], v[36:37], v[38:39]
	v_mov_b32_e32 v41, v35
	v_pk_add_f32 v[26:27], v[26:27], v[38:39]
	v_mov_b32_e32 v19, v39
	v_mov_b32_e32 v25, v27
	v_mov_b32_e32 v31, v26
	v_pk_add_f32 v[24:25], v[24:25], v[32:33] neg_lo:[0,1] neg_hi:[0,1]
	v_pk_add_f32 v[30:31], v[30:31], v[40:41] neg_lo:[0,1] neg_hi:[0,1]
	v_mov_b32_e32 v35, v24
	v_mov_b32_e32 v34, v30
	v_mov_b32_e32 v29, v38
	v_pk_add_f32 v[18:19], v[18:19], v[24:25] neg_lo:[0,1] neg_hi:[0,1]
	v_pk_add_f32 v[24:25], v[36:37], v[34:35] neg_lo:[0,1] neg_hi:[0,1]
	v_mov_b32_e32 v41, v32
	v_pk_add_f32 v[28:29], v[28:29], v[30:31] neg_lo:[0,1] neg_hi:[0,1]
	v_pk_add_f32 v[24:25], v[40:41], v[24:25] neg_lo:[0,1] neg_hi:[0,1]
	v_mov_b32_e32 v30, v28
	v_mov_b32_e32 v31, v18
	v_pk_add_f32 v[24:25], v[30:31], v[24:25]
	v_mov_b32_e32 v18, v29
	v_pk_add_f32 v[18:19], v[24:25], v[18:19]
	s_nop 0
	v_pk_add_f32 v[24:25], v[26:27], v[18:19]
	s_nop 0
	v_pk_add_f32 v[26:27], v[24:25], v[26:27] neg_lo:[0,1] neg_hi:[0,1]
	s_nop 0
	v_pk_add_f32 v[18:19], v[18:19], v[26:27] neg_lo:[0,1] neg_hi:[0,1]
	v_pk_mul_f32 v[26:27], v[8:9], v[24:25]
	s_nop 0
	v_pk_fma_f32 v[24:25], v[8:9], v[24:25], v[26:27] neg_lo:[0,0,1] neg_hi:[0,0,1]
	v_cmp_class_f32_e64 s[8:9], v26, v15
	v_pk_fma_f32 v[18:19], v[8:9], v[18:19], v[24:25]
	s_nop 0
	v_pk_add_f32 v[24:25], v[26:27], v[18:19]
	s_nop 0
	v_cndmask_b32_e64 v23, v24, v26, s[8:9]
	v_cmp_class_f32_e64 s[8:9], v27, v15
	v_pk_add_f32 v[28:29], v[24:25], v[26:27] neg_lo:[0,1] neg_hi:[0,1]
	s_nop 0
	v_cndmask_b32_e64 v24, v25, v27, s[8:9]
	v_cmp_eq_f32_e64 s[8:9], s17, v24
	v_pk_add_f32 v[18:19], v[18:19], v[28:29] neg_lo:[0,1] neg_hi:[0,1]
	s_nop 0
	v_cndmask_b32_e64 v25, 0, v13, s[8:9]
	v_sub_f32_e32 v26, v24, v25
	v_mul_f32_e32 v27, 0x3fb8aa3b, v26
	v_fma_f32 v28, v26, s31, -v27
	v_rndne_f32_e32 v29, v27
	v_fmac_f32_e32 v28, 0x32a5705f, v26
	v_sub_f32_e32 v27, v27, v29
	v_add_f32_e32 v27, v27, v28
	v_exp_f32_e32 v27, v27
	v_cvt_i32_f32_e32 v28, v29
	v_cmp_neq_f32_e64 s[8:9], |v24|, s28
	v_ldexp_f32 v24, v27, v28
	s_nop 0
	v_cndmask_b32_e64 v19, 0, v19, s[8:9]
	v_cmp_ngt_f32_e64 s[8:9], s30, v26
	v_add_f32_e32 v19, v25, v19
	s_nop 0
	v_cndmask_b32_e64 v24, 0, v24, s[8:9]
	v_cmp_nlt_f32_e64 s[8:9], s17, v26
	s_nop 1
	v_cndmask_b32_e64 v24, v22, v24, s[8:9]
	v_fma_f32 v19, v24, v19, v24
	v_cmp_class_f32_e64 s[8:9], v24, s29
	s_nop 1
	v_cndmask_b32_e64 v19, v19, v24, s[8:9]
	v_cmp_neq_f32_e64 s[8:9], v9, |v9|
	s_nop 1
	v_cndmask_b32_e64 v24, v22, 0, s[8:9]
	v_cndmask_b32_e64 v24, v24, 1.0, vcc
	v_cmp_eq_f32_e32 vcc, s17, v23
	v_cmp_class_f32_e64 s[8:9], v9, s29
	s_nop 0
	v_cndmask_b32_e32 v9, 0, v13, vcc
	v_cndmask_b32_e64 v80, |v19|, v24, s[8:9]
	v_sub_f32_e32 v19, v23, v9
	v_mul_f32_e32 v24, 0x3fb8aa3b, v19
	v_fma_f32 v25, v19, s31, -v24
	v_rndne_f32_e32 v26, v24
	v_fmac_f32_e32 v25, 0x32a5705f, v19
	v_sub_f32_e32 v24, v24, v26
	v_add_f32_e32 v24, v24, v25
	v_exp_f32_e32 v24, v24
	v_cvt_i32_f32_e32 v25, v26
	v_cmp_neq_f32_e64 vcc, |v23|, s28
	v_cmp_neq_f32_e64 s[8:9], v8, |v8|
	s_nop 0
	v_cndmask_b32_e32 v18, 0, v18, vcc
	v_add_f32_e32 v9, v9, v18
; DI void phase_mla_qk(const Params& p) {
;     ...
;     float inv[8];
; #pragma unroll
;     for (int e = 0; e < 8; ++e) inv[e] = powf(10000.f, -(float)((l8 & 3) * 8 + e) * (1.f / 32.f));
	v_ldexp_f32 v18, v24, v25
	v_cmp_ngt_f32_e32 vcc, s30, v19
	s_nop 1
	v_cndmask_b32_e32 v18, 0, v18, vcc
	v_cmp_nlt_f32_e32 vcc, s17, v19
	s_nop 1
	v_cndmask_b32_e32 v18, v22, v18, vcc
	v_fma_f32 v9, v18, v9, v18
	v_cmp_class_f32_e64 vcc, v18, s29
	s_nop 1
	v_cndmask_b32_e32 v9, v9, v18, vcc
	v_cndmask_b32_e64 v18, v22, 0, s[8:9]
	v_cndmask_b32_e64 v18, v18, 1.0, s[6:7]
	v_cmp_class_f32_e64 s[6:7], v8, s29
	v_or_b32_e32 v8, 4, v14
	s_nop 0
	v_cndmask_b32_e64 v81, |v9|, v18, s[6:7]
	v_or_b32_e32 v18, 5, v14
	v_cvt_f32_ubyte0_e32 v9, v8
	v_cvt_f32_ubyte0_e32 v8, v18
	v_pk_mul_f32 v[8:9], v[8:9], s[14:15] op_sel_hi:[1,0]
	s_nop 0
	v_cmp_eq_f32_e32 vcc, 0, v9
	s_nop 1
	v_cndmask_b32_e64 v23, v11, 1.0, vcc
	v_frexp_mant_f32_e32 v18, v23
	v_cmp_gt_f32_e64 s[6:7], s16, v18
	s_nop 1
	v_cndmask_b32_e64 v19, 1.0, 2.0, s[6:7]
	v_mul_f32_e32 v18, v18, v19
	v_add_f32_e32 v25, 1.0, v18
	v_rcp_f32_e32 v30, v25
	v_add_f32_e32 v19, -1.0, v25
	v_sub_f32_e32 v27, v18, v19
	v_add_f32_e32 v19, -1.0, v18
	v_mul_f32_e32 v31, v19, v30
	v_mul_f32_e32 v24, v25, v31
	v_fma_f32 v26, v31, v25, -v24
	v_fmac_f32_e32 v26, v31, v27
	v_add_f32_e32 v18, v24, v26
	v_sub_f32_e32 v25, v19, v18
	v_pk_add_f32 v[28:29], v[18:19], v[24:25] neg_lo:[0,1] neg_hi:[0,1]
	v_mov_b32_e32 v27, v18
	v_pk_add_f32 v[18:19], v[28:29], v[26:27] neg_lo:[0,1] neg_hi:[0,1]
	s_nop 0
	v_add_f32_e32 v18, v18, v19
	v_add_f32_e32 v18, v25, v18
	v_mul_f32_e32 v19, v30, v18
	v_add_f32_e32 v18, v31, v19
	v_sub_f32_e32 v24, v18, v31
	v_sub_f32_e32 v32, v19, v24
	v_mul_f32_e32 v19, v18, v18
	v_fma_f32 v25, v18, v18, -v19
	v_add_f32_e32 v24, v32, v32
	v_fmac_f32_e32 v25, v18, v24
	v_add_f32_e32 v24, v19, v25
	v_fmamk_f32 v26, v24, 0x3e76c4e1, v12
	v_fmaak_f32 v26, v24, v26, 0x3ecccdef
	v_sub_f32_e32 v19, v24, v19
	v_sub_f32_e32 v33, v25, v19
	v_mul_f32_e32 v19, v24, v26
	v_fma_f32 v25, v24, v26, -v19
	v_fmac_f32_e32 v25, v33, v26
	v_add_f32_e32 v26, v19, v25
	v_add_f32_e32 v27, 0x3f2aaaaa, v26
	v_sub_f32_e32 v19, v26, v19
	v_sub_f32_e32 v19, v25, v19
	v_add_f32_e32 v25, 0xbf2aaaaa, v27
	v_add_f32_e32 v19, 0x31739010, v19
	v_sub_f32_e32 v25, v26, v25
	v_pk_mul_f32 v[28:29], v[18:19], v[24:25]
	v_pk_add_f32 v[30:31], v[18:19], v[24:25]
	v_fma_f32 v26, v24, v18, -v28
	v_fmac_f32_e32 v26, v24, v32
	v_mov_b32_e32 v29, v31
	v_fmac_f32_e32 v26, v33, v18
	v_pk_add_f32 v[24:25], v[28:29], v[26:27]
	s_nop 0
	v_sub_f32_e32 v19, v24, v28
	v_cvt_f64_f32_e32 v[28:29], v23
	v_frexp_exp_i32_f64_e32 v23, v[28:29]
	v_subbrev_co_u32_e64 v23, s[6:7], 0, v23, s[6:7]
	v_cvt_f32_i32_e32 v23, v23
	v_sub_f32_e32 v19, v26, v19
	v_sub_f32_e32 v26, v27, v25
	v_add_f32_e32 v30, v31, v26
	v_pk_mul_f32 v[26:27], v[24:25], v[24:25] op_sel:[0,1] op_sel_hi:[1,0]
	v_ldexp_f32 v31, v18, 1
	v_fma_f32 v28, v24, v25, -v26
	v_fmac_f32_e32 v28, v24, v30
	v_mul_f32_e32 v24, 0x3f317218, v23
	v_fmac_f32_e32 v28, v19, v25
	v_fma_f32 v30, v23, s15, -v24
	v_fmac_f32_e32 v30, 0xb102e308, v23
	v_add_f32_e32 v25, v26, v28
	v_pk_add_f32 v[18:19], v[24:25], v[30:31]
	v_ldexp_f32 v23, v32, 1
	v_mov_b32_e32 v32, v25
	v_mov_b32_e32 v33, v19
	v_mov_b32_e32 v27, v31
	v_pk_add_f32 v[26:27], v[32:33], v[26:27] neg_lo:[0,1] neg_hi:[0,1]
	v_mov_b32_e32 v29, v25
	v_pk_add_f32 v[26:27], v[28:29], v[26:27] neg_lo:[0,1] neg_hi:[0,1]
	v_mov_b32_e32 v31, v18
	v_add_f32_e32 v23, v23, v26
	v_add_f32_e32 v25, v23, v27
	v_pk_add_f32 v[26:27], v[18:19], v[24:25] neg_lo:[0,1] neg_hi:[0,1]
	v_pk_add_f32 v[28:29], v[18:19], v[24:25]
	v_mov_b32_e32 v24, v25
	v_mov_b32_e32 v27, v29
	v_pk_add_f32 v[32:33], v[30:31], v[26:27] neg_lo:[0,1] neg_hi:[0,1]
	v_pk_add_f32 v[26:27], v[30:31], v[26:27]
	v_mov_b32_e32 v25, v18
	v_pk_add_f32 v[30:31], v[26:27], v[18:19] op_sel:[1,0] op_sel_hi:[0,1] neg_lo:[0,1] neg_hi:[0,1]
	v_pk_add_f32 v[34:35], v[28:29], v[30:31] op_sel_hi:[1,0] neg_lo:[0,1] neg_hi:[0,1]
	v_mov_b32_e32 v26, v29
	v_pk_mov_b32 v[28:29], v[18:19], v[30:31] op_sel:[1,0]
	v_mov_b32_e32 v34, v32
	v_pk_add_f32 v[28:29], v[26:27], v[28:29] neg_lo:[0,1] neg_hi:[0,1]
	v_cmp_eq_f32_e64 s[6:7], 0, v8
	v_pk_add_f32 v[18:19], v[24:25], v[28:29] neg_lo:[0,1] neg_hi:[0,1]
	v_mov_b32_e32 v33, v27
	v_pk_add_f32 v[24:25], v[34:35], v[18:19]
	v_cndmask_b32_e64 v19, v11, 1.0, s[6:7]
	v_frexp_mant_f32_e32 v23, v19
	v_cmp_gt_f32_e64 s[8:9], s16, v23
	s_nop 1
	v_cndmask_b32_e64 v26, 1.0, 2.0, s[8:9]
	v_mul_f32_e32 v23, v23, v26
	v_add_f32_e32 v26, 1.0, v23
	v_rcp_f32_e32 v38, v26
	v_add_f32_e32 v28, -1.0, v26
	v_add_f32_e32 v29, -1.0, v23
	v_sub_f32_e32 v28, v23, v28
	v_mul_f32_e32 v23, v29, v38
	v_mul_f32_e32 v30, v26, v23
	v_fma_f32 v34, v23, v26, -v30
	v_fmac_f32_e32 v34, v23, v28
	v_add_f32_e32 v28, v30, v34
	v_sub_f32_e32 v31, v29, v28
	v_pk_add_f32 v[36:37], v[28:29], v[30:31] neg_lo:[0,1] neg_hi:[0,1]
	v_mov_b32_e32 v35, v28
	v_pk_add_f32 v[28:29], v[36:37], v[34:35] neg_lo:[0,1] neg_hi:[0,1]
	s_nop 0
	v_add_f32_e32 v26, v28, v29
	v_add_f32_e32 v26, v31, v26
	v_mul_f32_e32 v26, v38, v26
	v_add_f32_e32 v28, v23, v26
	v_sub_f32_e32 v23, v28, v23
	v_sub_f32_e32 v23, v26, v23
	v_mul_f32_e32 v26, v28, v28
	v_fma_f32 v29, v28, v28, -v26
	v_add_f32_e32 v30, v23, v23
	v_fmac_f32_e32 v29, v28, v30
	v_add_f32_e32 v30, v26, v29
	v_fmamk_f32 v31, v30, 0x3e76c4e1, v12
	v_fmaak_f32 v31, v30, v31, 0x3ecccdef
	v_sub_f32_e32 v26, v30, v26
	v_sub_f32_e32 v26, v29, v26
	v_mul_f32_e32 v29, v30, v31
	v_fma_f32 v34, v30, v31, -v29
	v_fmac_f32_e32 v34, v26, v31
	v_add_f32_e32 v31, v29, v34
	v_add_f32_e32 v35, 0x3f2aaaaa, v31
	v_sub_f32_e32 v29, v31, v29
	v_sub_f32_e32 v29, v34, v29
	v_add_f32_e32 v34, 0xbf2aaaaa, v35
	v_add_f32_e32 v29, 0x31739010, v29
	v_sub_f32_e32 v31, v31, v34
	v_pk_mul_f32 v[36:37], v[28:29], v[30:31]
; DI void phase_mla_qk(const Params& p) {
;     ...
;     float inv[8];
; #pragma unroll
;     for (int e = 0; e < 8; ++e) inv[e] = powf(10000.f, -(float)((l8 & 3) * 8 + e) * (1.f / 32.f));
	v_pk_add_f32 v[38:39], v[28:29], v[30:31]
	v_fma_f32 v34, v30, v28, -v36
	v_fmac_f32_e32 v34, v30, v23
	v_mov_b32_e32 v37, v39
	v_fmac_f32_e32 v34, v26, v28
	v_pk_add_f32 v[30:31], v[36:37], v[34:35]
	s_nop 0
	v_sub_f32_e32 v26, v30, v36
	v_cvt_f64_f32_e32 v[36:37], v19
	v_frexp_exp_i32_f64_e32 v19, v[36:37]
	v_subbrev_co_u32_e64 v19, s[8:9], 0, v19, s[8:9]
	v_cvt_f32_i32_e32 v19, v19
	v_sub_f32_e32 v26, v34, v26
	v_sub_f32_e32 v29, v35, v31
	v_pk_mul_f32 v[34:35], v[30:31], v[30:31] op_sel:[0,1] op_sel_hi:[1,0]
	v_add_f32_e32 v29, v39, v29
	v_fma_f32 v36, v30, v31, -v34
	v_fmac_f32_e32 v36, v30, v29
	v_mul_f32_e32 v30, 0x3f317218, v19
	v_fmac_f32_e32 v36, v26, v31
	v_fma_f32 v38, v19, s15, -v30
	v_fmac_f32_e32 v38, 0xb102e308, v19
	v_ldexp_f32 v39, v28, 1
	v_add_f32_e32 v31, v34, v36
	v_pk_add_f32 v[28:29], v[30:31], v[38:39]
	v_mov_b32_e32 v40, v31
	v_mov_b32_e32 v41, v29
	v_mov_b32_e32 v35, v39
	v_pk_add_f32 v[34:35], v[40:41], v[34:35] neg_lo:[0,1] neg_hi:[0,1]
	v_mov_b32_e32 v37, v31
	v_ldexp_f32 v19, v23, 1
	v_pk_add_f32 v[34:35], v[36:37], v[34:35] neg_lo:[0,1] neg_hi:[0,1]
	v_mov_b32_e32 v39, v28
	v_add_f32_e32 v19, v19, v34
	v_add_f32_e32 v31, v19, v35
	v_pk_add_f32 v[34:35], v[28:29], v[30:31] neg_lo:[0,1] neg_hi:[0,1]
	v_pk_add_f32 v[36:37], v[28:29], v[30:31]
	v_mov_b32_e32 v30, v31
	v_mov_b32_e32 v35, v37
	v_pk_add_f32 v[40:41], v[38:39], v[34:35] neg_lo:[0,1] neg_hi:[0,1]
	v_pk_add_f32 v[34:35], v[38:39], v[34:35]
	v_mov_b32_e32 v31, v28
	v_pk_add_f32 v[38:39], v[34:35], v[28:29] op_sel:[1,0] op_sel_hi:[0,1] neg_lo:[0,1] neg_hi:[0,1]
	v_pk_add_f32 v[42:43], v[36:37], v[38:39] op_sel_hi:[1,0] neg_lo:[0,1] neg_hi:[0,1]
	v_mov_b32_e32 v34, v37
	v_pk_mov_b32 v[36:37], v[28:29], v[38:39] op_sel:[1,0]
	v_mov_b32_e32 v42, v40
	v_pk_add_f32 v[36:37], v[34:35], v[36:37] neg_lo:[0,1] neg_hi:[0,1]
	v_mov_b32_e32 v39, v25
	v_pk_add_f32 v[28:29], v[30:31], v[36:37] neg_lo:[0,1] neg_hi:[0,1]
	v_mov_b32_e32 v37, v24
	v_pk_add_f32 v[30:31], v[42:43], v[28:29]
	v_mov_b32_e32 v26, v35
	v_mov_b32_e32 v36, v30
	v_mov_b32_e32 v38, v31
	v_pk_add_f32 v[38:39], v[36:37], v[38:39]
	v_mov_b32_e32 v41, v35
	v_pk_add_f32 v[26:27], v[26:27], v[38:39]
	v_mov_b32_e32 v19, v39
	v_mov_b32_e32 v25, v27
	v_mov_b32_e32 v31, v26
	v_pk_add_f32 v[24:25], v[24:25], v[32:33] neg_lo:[0,1] neg_hi:[0,1]
	v_pk_add_f32 v[30:31], v[30:31], v[40:41] neg_lo:[0,1] neg_hi:[0,1]
	v_mov_b32_e32 v35, v24
	v_mov_b32_e32 v34, v30
	v_mov_b32_e32 v29, v38
	v_pk_add_f32 v[18:19], v[18:19], v[24:25] neg_lo:[0,1] neg_hi:[0,1]
	v_pk_add_f32 v[24:25], v[36:37], v[34:35] neg_lo:[0,1] neg_hi:[0,1]
	v_mov_b32_e32 v41, v32
	v_pk_add_f32 v[28:29], v[28:29], v[30:31] neg_lo:[0,1] neg_hi:[0,1]
	v_pk_add_f32 v[24:25], v[40:41], v[24:25] neg_lo:[0,1] neg_hi:[0,1]
	v_mov_b32_e32 v30, v28
	v_mov_b32_e32 v31, v18
	v_pk_add_f32 v[24:25], v[30:31], v[24:25]
	v_mov_b32_e32 v18, v29
	v_pk_add_f32 v[18:19], v[24:25], v[18:19]
	s_nop 0
	v_pk_add_f32 v[24:25], v[26:27], v[18:19]
	s_nop 0
	v_pk_add_f32 v[26:27], v[24:25], v[26:27] neg_lo:[0,1] neg_hi:[0,1]
	s_nop 0
	v_pk_add_f32 v[18:19], v[18:19], v[26:27] neg_lo:[0,1] neg_hi:[0,1]
	v_pk_mul_f32 v[26:27], v[8:9], v[24:25]
	s_nop 0
	v_pk_fma_f32 v[24:25], v[8:9], v[24:25], v[26:27] neg_lo:[0,0,1] neg_hi:[0,0,1]
	v_cmp_class_f32_e64 s[8:9], v26, v15
	v_pk_fma_f32 v[18:19], v[8:9], v[18:19], v[24:25]
	s_nop 0
	v_pk_add_f32 v[24:25], v[26:27], v[18:19]
	s_nop 0
	v_cndmask_b32_e64 v23, v24, v26, s[8:9]
	v_cmp_class_f32_e64 s[8:9], v27, v15
	v_pk_add_f32 v[28:29], v[24:25], v[26:27] neg_lo:[0,1] neg_hi:[0,1]
	s_nop 0
	v_cndmask_b32_e64 v24, v25, v27, s[8:9]
	v_cmp_eq_f32_e64 s[8:9], s17, v24
	v_pk_add_f32 v[18:19], v[18:19], v[28:29] neg_lo:[0,1] neg_hi:[0,1]
	s_nop 0
	v_cndmask_b32_e64 v25, 0, v13, s[8:9]
	v_sub_f32_e32 v26, v24, v25
	v_mul_f32_e32 v27, 0x3fb8aa3b, v26
	v_fma_f32 v28, v26, s31, -v27
	v_rndne_f32_e32 v29, v27
	v_fmac_f32_e32 v28, 0x32a5705f, v26
	v_sub_f32_e32 v27, v27, v29
	v_add_f32_e32 v27, v27, v28
	v_exp_f32_e32 v27, v27
	v_cvt_i32_f32_e32 v28, v29
	v_cmp_neq_f32_e64 s[8:9], |v24|, s28
	v_ldexp_f32 v24, v27, v28
	s_nop 0
	v_cndmask_b32_e64 v19, 0, v19, s[8:9]
	v_cmp_ngt_f32_e64 s[8:9], s30, v26
	v_add_f32_e32 v19, v25, v19
	s_nop 0
	v_cndmask_b32_e64 v24, 0, v24, s[8:9]
	v_cmp_nlt_f32_e64 s[8:9], s17, v26
	s_nop 1
	v_cndmask_b32_e64 v24, v22, v24, s[8:9]
	v_fma_f32 v19, v24, v19, v24
	v_cmp_class_f32_e64 s[8:9], v24, s29
	s_nop 1
	v_cndmask_b32_e64 v19, v19, v24, s[8:9]
	v_cmp_neq_f32_e64 s[8:9], v9, |v9|
	s_nop 1
	v_cndmask_b32_e64 v24, v22, 0, s[8:9]
	v_cndmask_b32_e64 v24, v24, 1.0, vcc
	v_cmp_eq_f32_e32 vcc, s17, v23
	v_cmp_class_f32_e64 s[8:9], v9, s29
	s_nop 0
	v_cndmask_b32_e32 v9, 0, v13, vcc
	v_cndmask_b32_e64 v82, |v19|, v24, s[8:9]
	v_sub_f32_e32 v19, v23, v9
	v_mul_f32_e32 v24, 0x3fb8aa3b, v19
	v_fma_f32 v25, v19, s31, -v24
	v_rndne_f32_e32 v26, v24
	v_fmac_f32_e32 v25, 0x32a5705f, v19
	v_sub_f32_e32 v24, v24, v26
	v_add_f32_e32 v24, v24, v25
	v_exp_f32_e32 v24, v24
	v_cvt_i32_f32_e32 v25, v26
	v_cmp_neq_f32_e64 vcc, |v23|, s28
	v_cmp_neq_f32_e64 s[8:9], v8, |v8|
	s_nop 0
	v_cndmask_b32_e32 v18, 0, v18, vcc
	v_add_f32_e32 v9, v9, v18
	v_ldexp_f32 v18, v24, v25
	v_cmp_ngt_f32_e32 vcc, s30, v19
	s_nop 1
	v_cndmask_b32_e32 v18, 0, v18, vcc
	v_cmp_nlt_f32_e32 vcc, s17, v19
	s_nop 1
	v_cndmask_b32_e32 v18, v22, v18, vcc
	v_fma_f32 v9, v18, v9, v18
	v_cmp_class_f32_e64 vcc, v18, s29
	s_nop 1
	v_cndmask_b32_e32 v9, v9, v18, vcc
	v_cndmask_b32_e64 v18, v22, 0, s[8:9]
	v_cndmask_b32_e64 v18, v18, 1.0, s[6:7]
	v_cmp_class_f32_e64 s[6:7], v8, s29
	v_or_b32_e32 v8, 6, v14
	v_or_b32_e32 v14, 7, v14
	v_cndmask_b32_e64 v83, |v9|, v18, s[6:7]
; DI void phase_mla_qk(const Params& p) {
;     ...
;     float inv[8];
; #pragma unroll
;     for (int e = 0; e < 8; ++e) inv[e] = powf(10000.f, -(float)((l8 & 3) * 8 + e) * (1.f / 32.f));
	v_cvt_f32_ubyte0_e32 v9, v8
	v_cvt_f32_ubyte0_e32 v8, v14
	v_pk_mul_f32 v[18:19], v[8:9], s[14:15] op_sel_hi:[1,0]
	s_nop 0
	v_cmp_eq_f32_e32 vcc, 0, v19
	s_nop 1
	v_cndmask_b32_e64 v14, v11, 1.0, vcc
	v_frexp_mant_f32_e32 v8, v14
	v_cmp_gt_f32_e64 s[6:7], s16, v8
	s_nop 1
	v_cndmask_b32_e64 v9, 1.0, 2.0, s[6:7]
	v_mul_f32_e32 v8, v8, v9
	v_add_f32_e32 v23, 1.0, v8
	v_rcp_f32_e32 v30, v23
	v_add_f32_e32 v9, -1.0, v23
	v_sub_f32_e32 v25, v8, v9
	v_add_f32_e32 v9, -1.0, v8
	v_mul_f32_e32 v31, v9, v30
	v_mul_f32_e32 v24, v23, v31
	v_fma_f32 v26, v31, v23, -v24
	v_fmac_f32_e32 v26, v31, v25
	v_add_f32_e32 v8, v24, v26
	v_sub_f32_e32 v25, v9, v8
	v_pk_add_f32 v[28:29], v[8:9], v[24:25] neg_lo:[0,1] neg_hi:[0,1]
	v_mov_b32_e32 v27, v8
	v_pk_add_f32 v[8:9], v[28:29], v[26:27] neg_lo:[0,1] neg_hi:[0,1]
	s_nop 0
	v_add_f32_e32 v8, v8, v9
	v_add_f32_e32 v8, v25, v8
	v_mul_f32_e32 v9, v30, v8
	v_add_f32_e32 v8, v31, v9
	v_sub_f32_e32 v23, v8, v31
	v_sub_f32_e32 v23, v9, v23
	v_mul_f32_e32 v9, v8, v8
	v_fma_f32 v25, v8, v8, -v9
	v_add_f32_e32 v24, v23, v23
	v_fmac_f32_e32 v25, v8, v24
	v_add_f32_e32 v24, v9, v25
	v_fmamk_f32 v26, v24, 0x3e76c4e1, v12
	v_fmaak_f32 v26, v24, v26, 0x3ecccdef
	v_sub_f32_e32 v9, v24, v9
	v_sub_f32_e32 v32, v25, v9
	v_mul_f32_e32 v9, v24, v26
	v_fma_f32 v25, v24, v26, -v9
	v_fmac_f32_e32 v25, v32, v26
	v_add_f32_e32 v26, v9, v25
	v_add_f32_e32 v27, 0x3f2aaaaa, v26
	v_sub_f32_e32 v9, v26, v9
	v_sub_f32_e32 v9, v25, v9
	v_add_f32_e32 v25, 0xbf2aaaaa, v27
	v_add_f32_e32 v9, 0x31739010, v9
	v_sub_f32_e32 v25, v26, v25
	v_pk_mul_f32 v[28:29], v[8:9], v[24:25]
	v_pk_add_f32 v[30:31], v[8:9], v[24:25]
	v_fma_f32 v26, v24, v8, -v28
	v_fmac_f32_e32 v26, v24, v23
	v_mov_b32_e32 v29, v31
	v_fmac_f32_e32 v26, v32, v8
	v_pk_add_f32 v[24:25], v[28:29], v[26:27]
	s_nop 0
	v_sub_f32_e32 v9, v24, v28
	v_cvt_f64_f32_e32 v[28:29], v14
	v_frexp_exp_i32_f64_e32 v14, v[28:29]
	v_subbrev_co_u32_e64 v14, s[6:7], 0, v14, s[6:7]
	v_cvt_f32_i32_e32 v14, v14
	v_sub_f32_e32 v9, v26, v9
	v_sub_f32_e32 v26, v27, v25
	v_add_f32_e32 v30, v31, v26
	v_pk_mul_f32 v[26:27], v[24:25], v[24:25] op_sel:[0,1] op_sel_hi:[1,0]
	v_ldexp_f32 v31, v8, 1
	v_fma_f32 v28, v24, v25, -v26
	v_fmac_f32_e32 v28, v24, v30
	v_mul_f32_e32 v24, 0x3f317218, v14
	v_fmac_f32_e32 v28, v9, v25
	v_fma_f32 v30, v14, s15, -v24
	v_fmac_f32_e32 v30, 0xb102e308, v14
	v_add_f32_e32 v25, v26, v28
	v_pk_add_f32 v[8:9], v[24:25], v[30:31]
	v_mov_b32_e32 v32, v25
	v_mov_b32_e32 v33, v9
	v_mov_b32_e32 v27, v31
	v_pk_add_f32 v[26:27], v[32:33], v[26:27] neg_lo:[0,1] neg_hi:[0,1]
	v_mov_b32_e32 v29, v25
	v_ldexp_f32 v14, v23, 1
	v_pk_add_f32 v[26:27], v[28:29], v[26:27] neg_lo:[0,1] neg_hi:[0,1]
	v_mov_b32_e32 v31, v8
	v_add_f32_e32 v14, v14, v26
	v_add_f32_e32 v25, v14, v27
	v_pk_add_f32 v[26:27], v[8:9], v[24:25] neg_lo:[0,1] neg_hi:[0,1]
	v_pk_add_f32 v[28:29], v[8:9], v[24:25]
	v_mov_b32_e32 v24, v25
	v_mov_b32_e32 v27, v29
	v_pk_add_f32 v[32:33], v[30:31], v[26:27] neg_lo:[0,1] neg_hi:[0,1]
	v_pk_add_f32 v[26:27], v[30:31], v[26:27]
	v_mov_b32_e32 v25, v8
	v_pk_add_f32 v[30:31], v[26:27], v[8:9] op_sel:[1,0] op_sel_hi:[0,1] neg_lo:[0,1] neg_hi:[0,1]
	v_pk_add_f32 v[34:35], v[28:29], v[30:31] op_sel_hi:[1,0] neg_lo:[0,1] neg_hi:[0,1]
	v_mov_b32_e32 v26, v29
	v_pk_mov_b32 v[28:29], v[8:9], v[30:31] op_sel:[1,0]
	v_mov_b32_e32 v34, v32
	v_pk_add_f32 v[28:29], v[26:27], v[28:29] neg_lo:[0,1] neg_hi:[0,1]
	v_cmp_eq_f32_e64 s[6:7], 0, v18
	v_pk_add_f32 v[8:9], v[24:25], v[28:29] neg_lo:[0,1] neg_hi:[0,1]
	v_mov_b32_e32 v33, v27
	v_pk_add_f32 v[24:25], v[34:35], v[8:9]
	v_cndmask_b32_e64 v9, v11, 1.0, s[6:7]
	v_frexp_mant_f32_e32 v11, v9
	v_cmp_gt_f32_e64 s[8:9], s16, v11
	s_nop 1
	v_cndmask_b32_e64 v14, 1.0, 2.0, s[8:9]
	v_mul_f32_e32 v11, v11, v14
	v_add_f32_e32 v14, 1.0, v11
	v_rcp_f32_e32 v23, v14
	v_add_f32_e32 v26, -1.0, v14
	v_add_f32_e32 v29, -1.0, v11
	v_sub_f32_e32 v26, v11, v26
	v_mul_f32_e32 v11, v29, v23
	v_mul_f32_e32 v30, v14, v11
	v_fma_f32 v34, v11, v14, -v30
	v_fmac_f32_e32 v34, v11, v26
	v_add_f32_e32 v28, v30, v34
	v_sub_f32_e32 v31, v29, v28
	v_pk_add_f32 v[36:37], v[28:29], v[30:31] neg_lo:[0,1] neg_hi:[0,1]
	v_mov_b32_e32 v35, v28
	v_pk_add_f32 v[28:29], v[36:37], v[34:35] neg_lo:[0,1] neg_hi:[0,1]
	s_nop 0
	v_add_f32_e32 v14, v28, v29
	v_add_f32_e32 v14, v31, v14
	v_mul_f32_e32 v14, v23, v14
	v_add_f32_e32 v28, v11, v14
	v_sub_f32_e32 v11, v28, v11
	v_sub_f32_e32 v14, v14, v11
	v_mul_f32_e32 v11, v28, v28
	v_fma_f32 v23, v28, v28, -v11
	v_add_f32_e32 v26, v14, v14
	v_fmac_f32_e32 v23, v28, v26
	v_add_f32_e32 v30, v11, v23
	v_fmac_f32_e32 v12, 0x3e76c4e1, v30
	v_fmac_f32_e32 v10, v30, v12
	v_sub_f32_e32 v11, v30, v11
	v_sub_f32_e32 v12, v23, v11
	v_mul_f32_e32 v23, v30, v10
	v_fma_f32 v26, v30, v10, -v23
	v_fmac_f32_e32 v26, v12, v10
	v_add_f32_e32 v10, v23, v26
	v_sub_f32_e32 v23, v10, v23
	v_add_f32_e32 v11, 0x3f2aaaaa, v10
	v_sub_f32_e32 v23, v26, v23
	v_add_f32_e32 v29, 0x31739010, v23
	v_add_f32_e32 v23, 0xbf2aaaaa, v11
	v_sub_f32_e32 v31, v10, v23
	v_pk_mul_f32 v[34:35], v[28:29], v[30:31]
	v_pk_add_f32 v[36:37], v[28:29], v[30:31]
	v_fma_f32 v10, v30, v28, -v34
	v_fmac_f32_e32 v10, v30, v14
	v_mov_b32_e32 v35, v37
	v_fmac_f32_e32 v10, v12, v28
	v_pk_add_f32 v[30:31], v[34:35], v[10:11]
	s_nop 0
	v_sub_f32_e32 v12, v30, v34
	v_cvt_f64_f32_e32 v[34:35], v9
	v_frexp_exp_i32_f64_e32 v9, v[34:35]
	v_subbrev_co_u32_e64 v9, s[8:9], 0, v9, s[8:9]
	v_cvt_f32_i32_e32 v9, v9
	v_sub_f32_e32 v12, v10, v12
	v_sub_f32_e32 v10, v11, v31
	v_add_f32_e32 v23, v37, v10
	v_pk_mul_f32 v[10:11], v[30:31], v[30:31] op_sel:[0,1] op_sel_hi:[1,0]
	v_ldexp_f32 v37, v28, 1
	v_fma_f32 v34, v30, v31, -v10
; DI u32x4 pack8(const float (&f)[8]) { u32x4 w; w.x = pk2(f[0], f[1]); w.y = pk2(f[2], f[3]); w.z = pk2(f[4], f[5]); w.w = pk2(f[6], f[7]); return w; }
; DI void phase_mla_qk(const Params& p) {
;     ...
;     float inv[8];
; #pragma unroll
;     for (int e = 0; e < 8; ++e) inv[e] = powf(10000.f, -(float)((l8 & 3) * 8 + e) * (1.f / 32.f));
;     ...
;                 ss += __shfl_xor(ss, 1); ss += __shfl_xor(ss, 2); ss += __shfl_xor(ss, 4); ss += __shfl_xor(ss, 8);
;                 const float sc = rsqrtf(ss * (1.f / 128.f) + EPS);
; #pragma unroll
;                 for (int e = 0; e < 8; ++e) f[e] *= sc * gk[e];
;                 if (ok[r]) *(u32x4*)(qr + 3072 + head * 256 + l16 * 8) = pack8(f);
;             }
;             { float f[8], o[8]; unpack8(wp[r], f); float ss = 0.f;
; #pragma unroll
;               for (int e = 0; e < 8; ++e) ss += f[e] * f[e];
;               ss += __shfl_xor(ss, 1); ss += __shfl_xor(ss, 2); ss += __shfl_xor(ss, 4);
;               const float sc = rsqrtf(ss * (1.f / 64.f) + EPS);
; #pragma unroll
;               for (int e = 0; e < 8; ++e) {
;                   const float a = f[e] * sc * gkr[e], pa = __shfl_xor(a, 4);
	v_fmac_f32_e32 v34, v30, v23
	v_mul_f32_e32 v30, 0x3f317218, v9
	v_fmac_f32_e32 v34, v12, v31
	v_fma_f32 v36, v9, s15, -v30
	v_fmac_f32_e32 v36, 0xb102e308, v9
	v_add_f32_e32 v31, v10, v34
	v_pk_add_f32 v[28:29], v[30:31], v[36:37]
	v_mov_b32_e32 v38, v31
	v_mov_b32_e32 v39, v29
	v_mov_b32_e32 v11, v37
	v_pk_add_f32 v[10:11], v[38:39], v[10:11] neg_lo:[0,1] neg_hi:[0,1]
	v_mov_b32_e32 v35, v31
	v_ldexp_f32 v9, v14, 1
	v_pk_add_f32 v[10:11], v[34:35], v[10:11] neg_lo:[0,1] neg_hi:[0,1]
	v_mov_b32_e32 v37, v28
	v_add_f32_e32 v9, v9, v10
	v_add_f32_e32 v31, v9, v11
	v_pk_add_f32 v[10:11], v[28:29], v[30:31] neg_lo:[0,1] neg_hi:[0,1]
	v_pk_add_f32 v[34:35], v[28:29], v[30:31]
	v_mov_b32_e32 v30, v31
	v_mov_b32_e32 v11, v35
	v_pk_add_f32 v[38:39], v[36:37], v[10:11] neg_lo:[0,1] neg_hi:[0,1]
	v_pk_add_f32 v[10:11], v[36:37], v[10:11]
	v_mov_b32_e32 v31, v28
	v_pk_add_f32 v[36:37], v[10:11], v[28:29] op_sel:[1,0] op_sel_hi:[0,1] neg_lo:[0,1] neg_hi:[0,1]
	v_pk_add_f32 v[40:41], v[34:35], v[36:37] op_sel_hi:[1,0] neg_lo:[0,1] neg_hi:[0,1]
	v_mov_b32_e32 v10, v35
	v_pk_mov_b32 v[34:35], v[28:29], v[36:37] op_sel:[1,0]
	v_mov_b32_e32 v40, v38
	v_pk_add_f32 v[34:35], v[10:11], v[34:35] neg_lo:[0,1] neg_hi:[0,1]
	v_mov_b32_e32 v37, v25
	v_pk_add_f32 v[28:29], v[30:31], v[34:35] neg_lo:[0,1] neg_hi:[0,1]
	v_mov_b32_e32 v35, v24
	v_pk_add_f32 v[30:31], v[40:41], v[28:29]
	v_mov_b32_e32 v26, v11
	v_mov_b32_e32 v34, v30
	v_mov_b32_e32 v36, v31
	v_pk_add_f32 v[36:37], v[34:35], v[36:37]
	v_mov_b32_e32 v39, v11
	v_pk_add_f32 v[10:11], v[26:27], v[36:37]
	v_mov_b32_e32 v9, v37
	v_mov_b32_e32 v25, v11
	v_mov_b32_e32 v31, v10
	v_pk_add_f32 v[24:25], v[24:25], v[32:33] neg_lo:[0,1] neg_hi:[0,1]
	v_pk_add_f32 v[26:27], v[30:31], v[38:39] neg_lo:[0,1] neg_hi:[0,1]
	v_mov_b32_e32 v31, v24
	v_mov_b32_e32 v30, v26
	v_mov_b32_e32 v29, v36
	v_pk_add_f32 v[8:9], v[8:9], v[24:25] neg_lo:[0,1] neg_hi:[0,1]
	v_pk_add_f32 v[24:25], v[34:35], v[30:31] neg_lo:[0,1] neg_hi:[0,1]
	v_mov_b32_e32 v39, v32
	v_pk_add_f32 v[26:27], v[28:29], v[26:27] neg_lo:[0,1] neg_hi:[0,1]
	v_pk_add_f32 v[24:25], v[38:39], v[24:25] neg_lo:[0,1] neg_hi:[0,1]
	v_mov_b32_e32 v28, v26
	v_mov_b32_e32 v29, v8
	v_pk_add_f32 v[24:25], v[28:29], v[24:25]
	v_mov_b32_e32 v8, v27
	v_pk_add_f32 v[8:9], v[24:25], v[8:9]
	v_lshlrev_b32_e32 v28, 5, v20
	v_pk_add_f32 v[24:25], v[10:11], v[8:9]
	s_nop 0
	v_pk_add_f32 v[10:11], v[24:25], v[10:11] neg_lo:[0,1] neg_hi:[0,1]
	s_nop 0
	v_pk_add_f32 v[8:9], v[8:9], v[10:11] neg_lo:[0,1] neg_hi:[0,1]
	v_pk_mul_f32 v[10:11], v[18:19], v[24:25]
	s_nop 0
	v_pk_fma_f32 v[24:25], v[18:19], v[24:25], v[10:11] neg_lo:[0,0,1] neg_hi:[0,0,1]
	v_cmp_class_f32_e64 s[8:9], v10, v15
	v_pk_fma_f32 v[8:9], v[18:19], v[8:9], v[24:25]
	s_nop 0
	v_pk_add_f32 v[24:25], v[10:11], v[8:9]
	s_nop 0
	v_pk_add_f32 v[26:27], v[24:25], v[10:11] neg_lo:[0,1] neg_hi:[0,1]
	v_cndmask_b32_e64 v23, v24, v10, s[8:9]
	v_cmp_class_f32_e64 s[8:9], v11, v15
	v_pk_add_f32 v[26:27], v[8:9], v[26:27] neg_lo:[0,1] neg_hi:[0,1]
	s_nop 0
	v_cndmask_b32_e64 v8, v25, v11, s[8:9]
	v_cmp_eq_f32_e64 s[8:9], s17, v8
	s_nop 1
	v_cndmask_b32_e64 v9, 0, v13, s[8:9]
	v_sub_f32_e32 v10, v8, v9
	v_mul_f32_e32 v11, 0x3fb8aa3b, v10
	v_fma_f32 v12, v10, s31, -v11
	v_rndne_f32_e32 v14, v11
	v_fmac_f32_e32 v12, 0x32a5705f, v10
	v_sub_f32_e32 v11, v11, v14
	v_add_f32_e32 v11, v11, v12
	v_exp_f32_e32 v11, v11
	v_cvt_i32_f32_e32 v12, v14
	v_cmp_neq_f32_e64 s[8:9], |v8|, s28
	s_nop 1
	v_cndmask_b32_e64 v8, 0, v27, s[8:9]
	v_add_f32_e32 v8, v9, v8
	v_ldexp_f32 v9, v11, v12
	v_cmp_ngt_f32_e64 s[8:9], s30, v10
	s_nop 1
	v_cndmask_b32_e64 v9, 0, v9, s[8:9]
	v_cmp_nlt_f32_e64 s[8:9], s17, v10
	s_nop 1
	v_cndmask_b32_e64 v9, v22, v9, s[8:9]
	v_fma_f32 v8, v9, v8, v9
	v_cmp_class_f32_e64 s[8:9], v9, s29
	s_nop 1
	v_cndmask_b32_e64 v8, v8, v9, s[8:9]
	v_cmp_neq_f32_e64 s[8:9], v19, |v19|
	s_nop 1
	v_cndmask_b32_e64 v9, v22, 0, s[8:9]
	v_cndmask_b32_e64 v9, v9, 1.0, vcc
	v_cmp_eq_f32_e32 vcc, s17, v23
	v_cmp_class_f32_e64 s[8:9], v19, s29
	s_nop 0
	v_cndmask_b32_e32 v19, 0, v13, vcc
	v_sub_f32_e32 v24, v23, v19
	v_cndmask_b32_e64 v84, |v8|, v9, s[8:9]
	v_mul_f32_e32 v8, 0x3fb8aa3b, v24
	v_fma_f32 v9, v24, s31, -v8
	v_rndne_f32_e32 v25, v8
	v_fmac_f32_e32 v9, 0x32a5705f, v24
	v_sub_f32_e32 v8, v8, v25
	v_add_f32_e32 v27, v8, v9
	global_load_dwordx4 v[8:11], v28, s[12:13] offset:1280
	global_load_dwordx4 v[12:15], v28, s[12:13] offset:1296
	v_exp_f32_e32 v27, v27
	v_cvt_i32_f32_e32 v25, v25
	v_cmp_neq_f32_e64 vcc, |v23|, s28
	v_cmp_neq_f32_e64 s[8:9], v18, |v18|
	s_nop 0
	v_cndmask_b32_e32 v23, 0, v26, vcc
	v_add_f32_e32 v19, v19, v23
	v_ldexp_f32 v23, v27, v25
	v_cmp_ngt_f32_e32 vcc, s30, v24
	s_mov_b64 s[30:31], 0x1800
	s_nop 0
	v_cndmask_b32_e32 v23, 0, v23, vcc
	v_cmp_nlt_f32_e32 vcc, s17, v24
	s_nop 1
	v_cndmask_b32_e32 v23, v22, v23, vcc
	v_fma_f32 v19, v23, v19, v23
	v_cmp_class_f32_e64 vcc, v23, s29
	v_cndmask_b32_e64 v22, v22, 0, s[8:9]
	v_cndmask_b32_e64 v22, v22, 1.0, s[6:7]
	v_cndmask_b32_e32 v19, v19, v23, vcc
	v_cmp_class_f32_e64 s[6:7], v18, s29
	v_lshlrev_b32_e32 v18, 4, v21
	v_and_b32_e32 v18, 0x300, v18
	v_cndmask_b32_e64 v85, |v19|, v22, s[6:7]
	v_and_b32_e32 v19, 63, v21
	v_mbcnt_hi_u32_b32 v21, -1, v178
	v_and_b32_e32 v23, 64, v21
	v_xor_b32_e32 v22, 1, v21
	v_add_u32_e32 v23, 64, v23
	v_cmp_lt_i32_e32 vcc, v22, v23
	v_or_b32_e32 v24, 0xc00, v18
	v_cmp_gt_u32_e64 s[6:7], 8, v19
	v_cndmask_b32_e32 v22, v21, v22, vcc
	v_lshlrev_b32_e32 v86, 2, v22
	v_xor_b32_e32 v22, 2, v21
	v_cmp_lt_i32_e32 vcc, v22, v23
	s_mov_b64 s[28:29], 0
	v_lshlrev_b32_e32 v48, 1, v18
	v_cndmask_b32_e32 v22, v21, v22, vcc
	v_lshlrev_b32_e32 v87, 2, v22
	v_xor_b32_e32 v22, 4, v21
	v_cmp_lt_i32_e32 vcc, v22, v23
	v_lshlrev_b32_e32 v52, 1, v24
	s_nop 0
	v_cndmask_b32_e32 v22, v21, v22, vcc
	v_lshlrev_b32_e32 v88, 2, v22
	v_xor_b32_e32 v22, 8, v21
	v_cmp_lt_i32_e32 vcc, v22, v23
	s_nop 1
	v_cndmask_b32_e32 v21, v21, v22, vcc
	v_or_b32_e32 v22, 0x800, v18
	v_lshlrev_b32_e32 v89, 2, v21
	v_cmp_gt_u32_e32 vcc, 4, v20
	v_lshlrev_b32_e32 v50, 1, v22
	s_branch .LBB0_1428
